# all per-segment s_setprio flips in the GEMM K-loops deleted; one static s_setprio 1 for waves 0-3 around each K-loop
# speedup vs baseline: 1.0076x; 1.0005x over previous
.LBB0_71:
	s_ashr_i32 s15, s14, 31
	s_lshl_b64 s[16:17], s[14:15], 19
	s_add_u32 s16, s2, s16
	s_addc_u32 s17, s26, s17
	s_and_b64 s[18:19], s[6:7], exec
	s_cselect_b32 s15, s17, s23
	s_cselect_b32 s40, s16, s22
	s_ashr_i32 s13, s12, 31
	s_lshl_b64 s[18:19], s[12:13], 19
	s_add_u32 s18, s27, s18
	s_addc_u32 s19, s28, s19
	s_and_b64 s[24:25], s[6:7], exec
	s_cselect_b32 s13, s19, s21
	s_cselect_b32 s41, s18, s20
	s_add_u32 s42, s20, 0x100
	s_addc_u32 s43, s21, 0
	s_add_u32 s20, s22, 0x40080
	v_mov_b32_e32 v0, 0
	s_addc_u32 s21, s23, 0
	s_mov_b32 s44, -2
	v_mov_b32_e32 v1, v0
	v_mov_b32_e32 v2, v0
	v_mov_b32_e32 v3, v0
	v_mov_b32_e32 v4, v0
	v_mov_b32_e32 v5, v0
	v_mov_b32_e32 v6, v0
	v_mov_b32_e32 v7, v0
	v_mov_b32_e32 v16, v0
	v_mov_b32_e32 v17, v0
	v_mov_b32_e32 v18, v0
	v_mov_b32_e32 v19, v0
	v_mov_b32_e32 v20, v0
	v_mov_b32_e32 v21, v0
	v_mov_b32_e32 v22, v0
	v_mov_b32_e32 v23, v0
	v_mov_b32_e32 v32, v0
	v_mov_b32_e32 v33, v0
	v_mov_b32_e32 v34, v0
	v_mov_b32_e32 v35, v0
	v_mov_b32_e32 v36, v0
	v_mov_b32_e32 v37, v0
	v_mov_b32_e32 v38, v0
	v_mov_b32_e32 v39, v0
	v_mov_b32_e32 v48, v0
	v_mov_b32_e32 v49, v0
	v_mov_b32_e32 v50, v0
	v_mov_b32_e32 v51, v0
	v_mov_b32_e32 v52, v0
	v_mov_b32_e32 v53, v0
	v_mov_b32_e32 v54, v0
	v_mov_b32_e32 v55, v0
	v_mov_b32_e32 v8, v0
	v_mov_b32_e32 v9, v0
	v_mov_b32_e32 v10, v0
	v_mov_b32_e32 v11, v0
	v_mov_b32_e32 v12, v0
	v_mov_b32_e32 v13, v0
	v_mov_b32_e32 v14, v0
	v_mov_b32_e32 v15, v0
	v_mov_b32_e32 v24, v0
	v_mov_b32_e32 v25, v0
	v_mov_b32_e32 v26, v0
	v_mov_b32_e32 v27, v0
	v_mov_b32_e32 v28, v0
	v_mov_b32_e32 v29, v0
	v_mov_b32_e32 v30, v0
	v_mov_b32_e32 v31, v0
	v_mov_b32_e32 v40, v0
	v_mov_b32_e32 v41, v0
	v_mov_b32_e32 v42, v0
	v_mov_b32_e32 v43, v0
	v_mov_b32_e32 v44, v0
	v_mov_b32_e32 v45, v0
	v_mov_b32_e32 v46, v0
	v_mov_b32_e32 v47, v0
	v_mov_b32_e32 v56, v0
	v_mov_b32_e32 v57, v0
	v_mov_b32_e32 v58, v0
	v_mov_b32_e32 v59, v0
	v_mov_b32_e32 v60, v0
	v_mov_b32_e32 v61, v0
	v_mov_b32_e32 v62, v0
	v_mov_b32_e32 v63, v0
	v_mov_b32_e32 v64, v0
	v_mov_b32_e32 v65, v0
	v_mov_b32_e32 v66, v0
	v_mov_b32_e32 v67, v0
	v_mov_b32_e32 v68, v0
	v_mov_b32_e32 v69, v0
	v_mov_b32_e32 v70, v0
	v_mov_b32_e32 v71, v0
	v_mov_b32_e32 v80, v0
	v_mov_b32_e32 v81, v0
	v_mov_b32_e32 v82, v0
	v_mov_b32_e32 v83, v0
	v_mov_b32_e32 v84, v0
	v_mov_b32_e32 v85, v0
	v_mov_b32_e32 v86, v0
	v_mov_b32_e32 v87, v0
	v_mov_b32_e32 v96, v0
	v_mov_b32_e32 v97, v0
	v_mov_b32_e32 v98, v0
	v_mov_b32_e32 v99, v0
	v_mov_b32_e32 v100, v0
	v_mov_b32_e32 v101, v0
	v_mov_b32_e32 v102, v0
	v_mov_b32_e32 v103, v0
	v_mov_b32_e32 v112, v0
	v_mov_b32_e32 v113, v0
	v_mov_b32_e32 v114, v0
	v_mov_b32_e32 v115, v0
	v_mov_b32_e32 v116, v0
	v_mov_b32_e32 v117, v0
	v_mov_b32_e32 v118, v0
	v_mov_b32_e32 v119, v0
	v_mov_b32_e32 v72, v0
	v_mov_b32_e32 v73, v0
	v_mov_b32_e32 v74, v0
	v_mov_b32_e32 v75, v0
	v_mov_b32_e32 v76, v0
	v_mov_b32_e32 v77, v0
	v_mov_b32_e32 v78, v0
	v_mov_b32_e32 v79, v0
	v_mov_b32_e32 v88, v0
	v_mov_b32_e32 v89, v0
	v_mov_b32_e32 v90, v0
	v_mov_b32_e32 v91, v0
	v_mov_b32_e32 v92, v0
	v_mov_b32_e32 v93, v0
	v_mov_b32_e32 v94, v0
	v_mov_b32_e32 v95, v0
	v_mov_b32_e32 v104, v0
	v_mov_b32_e32 v105, v0
	v_mov_b32_e32 v106, v0
	v_mov_b32_e32 v107, v0
	v_mov_b32_e32 v108, v0
	v_mov_b32_e32 v109, v0
	v_mov_b32_e32 v110, v0
	v_mov_b32_e32 v111, v0
	v_mov_b32_e32 v120, v0
	v_mov_b32_e32 v121, v0
	v_mov_b32_e32 v122, v0
	v_mov_b32_e32 v123, v0
	v_mov_b32_e32 v124, v0
	v_mov_b32_e32 v125, v0
	v_mov_b32_e32 v126, v0
	v_mov_b32_e32 v127, v0
	v_readlane_b32 s100, v252, 21
	s_sub_u32 s100, s100, 0
	s_cmp_lt_u32 s100, 4
	s_cbranch_scc0 .Lprio_0
	s_setprio 1
.Lprio_0:
.LBB0_72:
	s_add_u32 s22, s20, 0xfffc0080
	s_addc_u32 s23, s21, -1
	s_add_i32 s45, 0, 0x10000
	s_cmp_eq_u32 s44, 12
	s_cselect_b32 s25, s15, s23
	s_cselect_b32 s24, s40, s22
	v_add_u32_e32 v138, s45, v141
	s_cselect_b32 s23, s13, s43
	s_cselect_b32 s22, s41, s42
	s_add_i32 s48, 0, 0x14000
	ds_read_b128 v[144:147], v138
	ds_read_b128 v[148:151], v138 offset:1024
	ds_read_b128 v[152:155], v138 offset:2048
	ds_read_b128 v[156:159], v138 offset:3072
	v_add_u32_e32 v138, s48, v141
	ds_read_b128 v[170:173], v138
	ds_read_b128 v[174:177], v138 offset:1024
	ds_read_b128 v[178:181], v138 offset:2048
	ds_read_b128 v[182:185], v138 offset:3072
	v_lshl_add_u64 v[138:139], s[20:21], 0, v[136:137]
	s_add_i32 m0, s29, 0xc000
	ds_read_b128 v[186:189], v143
	ds_read_b128 v[190:193], v143 offset:1024
	ds_read_b128 v[194:197], v143 offset:2048
	ds_read_b128 v[198:201], v143 offset:3072
	ds_read_b128 v[202:205], v143 offset:4096
	ds_read_b128 v[228:231], v143 offset:5120
	ds_read_b128 v[232:235], v143 offset:6144
	ds_read_b128 v[236:239], v143 offset:7168
	global_load_lds_dwordx4 v[138:139], off
	v_lshl_add_u64 v[138:139], s[20:21], 0, v[134:135]
	s_add_i32 m0, s29, 0xe000
	s_nop 0
	global_load_lds_dwordx4 v[138:139], off
	s_waitcnt vmcnt(8)
	s_waitcnt lgkmcnt(0)
	s_barrier
	s_waitcnt lgkmcnt(0)
	v_mfma_f32_16x16x32_bf16 v[124:127], v[144:147], v[186:189], v[124:127]
	v_mfma_f32_16x16x32_bf16 v[120:123], v[152:155], v[186:189], v[120:123]
	v_mfma_f32_16x16x32_bf16 v[108:111], v[144:147], v[194:197], v[108:111]
	v_mfma_f32_16x16x32_bf16 v[104:107], v[152:155], v[194:197], v[104:107]
	v_mfma_f32_16x16x32_bf16 v[92:95], v[144:147], v[202:205], v[92:95]
	v_mfma_f32_16x16x32_bf16 v[88:91], v[152:155], v[202:205], v[88:91]
	v_mfma_f32_16x16x32_bf16 v[76:79], v[144:147], v[232:235], v[76:79]
	v_mfma_f32_16x16x32_bf16 v[72:75], v[152:155], v[232:235], v[72:75]
	v_mfma_f32_16x16x32_bf16 v[124:127], v[148:151], v[190:193], v[124:127]
	v_mfma_f32_16x16x32_bf16 v[120:123], v[156:159], v[190:193], v[120:123]
	v_mfma_f32_16x16x32_bf16 v[108:111], v[148:151], v[198:201], v[108:111]
	v_mfma_f32_16x16x32_bf16 v[104:107], v[156:159], v[198:201], v[104:107]
	v_mfma_f32_16x16x32_bf16 v[92:95], v[148:151], v[228:231], v[92:95]
	v_mfma_f32_16x16x32_bf16 v[88:91], v[156:159], v[228:231], v[88:91]
	v_mfma_f32_16x16x32_bf16 v[76:79], v[148:151], v[236:239], v[76:79]
	v_mfma_f32_16x16x32_bf16 v[72:75], v[156:159], v[236:239], v[72:75]
	v_mfma_f32_16x16x32_bf16 v[116:119], v[170:173], v[186:189], v[116:119]
	v_mfma_f32_16x16x32_bf16 v[112:115], v[178:181], v[186:189], v[112:115]
	v_mfma_f32_16x16x32_bf16 v[100:103], v[170:173], v[194:197], v[100:103]
	v_mfma_f32_16x16x32_bf16 v[96:99], v[178:181], v[194:197], v[96:99]
	v_mfma_f32_16x16x32_bf16 v[84:87], v[170:173], v[202:205], v[84:87]
	v_mfma_f32_16x16x32_bf16 v[80:83], v[178:181], v[202:205], v[80:83]
	v_mfma_f32_16x16x32_bf16 v[68:71], v[170:173], v[232:235], v[68:71]
	v_mfma_f32_16x16x32_bf16 v[64:67], v[178:181], v[232:235], v[64:67]
	v_mfma_f32_16x16x32_bf16 v[116:119], v[174:177], v[190:193], v[116:119]
	v_mfma_f32_16x16x32_bf16 v[112:115], v[182:185], v[190:193], v[112:115]
	v_mfma_f32_16x16x32_bf16 v[100:103], v[174:177], v[198:201], v[100:103]
	v_mfma_f32_16x16x32_bf16 v[96:99], v[182:185], v[198:201], v[96:99]
	v_mfma_f32_16x16x32_bf16 v[84:87], v[174:177], v[228:231], v[84:87]
	v_mfma_f32_16x16x32_bf16 v[80:83], v[182:185], v[228:231], v[80:83]
	v_mfma_f32_16x16x32_bf16 v[68:71], v[174:177], v[236:239], v[68:71]
	v_mfma_f32_16x16x32_bf16 v[64:67], v[182:185], v[236:239], v[64:67]
	s_barrier
	s_add_i32 s45, s45, s77
	v_lshl_add_u64 v[138:139], s[22:23], 0, v[160:161]
	s_mov_b32 m0, s45
	ds_read_b128 v[186:189], v143 offset:16384
	ds_read_b128 v[190:193], v143 offset:17408
	ds_read_b128 v[194:197], v143 offset:18432
	ds_read_b128 v[198:201], v143 offset:19456
	ds_read_b128 v[202:205], v143 offset:20480
	ds_read_b128 v[228:231], v143 offset:21504
	ds_read_b128 v[232:235], v143 offset:22528
	ds_read_b128 v[236:239], v143 offset:23552
	global_load_lds_dwordx4 v[138:139], off
	s_add_i32 m0, s45, 0x2000
	s_add_u32 s46, s22, 0x40000
	v_lshl_add_u64 v[166:167], s[22:23], 0, v[128:129]
	s_addc_u32 s47, s23, 0
	s_add_i32 s45, s48, s77
	global_load_lds_dwordx4 v[166:167], off
	v_lshl_add_u64 v[168:169], s[46:47], 0, v[160:161]
	s_mov_b32 m0, s45
	v_lshl_add_u64 v[206:207], s[24:25], 0, v[130:131]
	global_load_lds_dwordx4 v[168:169], off
	v_lshl_add_u64 v[168:169], s[46:47], 0, v[128:129]
	s_add_i32 m0, s45, 0x2000
	s_nop 0
	global_load_lds_dwordx4 v[168:169], off
	v_lshl_add_u64 v[168:169], s[24:25], 0, v[132:133]
	s_mov_b32 m0, s29
	s_nop 0
	global_load_lds_dwordx4 v[168:169], off
	s_mov_b32 m0, s30
	s_nop 0
	global_load_lds_dwordx4 v[206:207], off
	s_waitcnt vmcnt(8)
	s_waitcnt lgkmcnt(0)
	s_barrier
	s_waitcnt lgkmcnt(0)
	v_mfma_f32_16x16x32_bf16 v[60:63], v[144:147], v[186:189], v[60:63]
	v_mfma_f32_16x16x32_bf16 v[56:59], v[152:155], v[186:189], v[56:59]
	v_mfma_f32_16x16x32_bf16 v[44:47], v[144:147], v[194:197], v[44:47]
	v_mfma_f32_16x16x32_bf16 v[40:43], v[152:155], v[194:197], v[40:43]
	v_mfma_f32_16x16x32_bf16 v[28:31], v[144:147], v[202:205], v[28:31]
	v_mfma_f32_16x16x32_bf16 v[24:27], v[152:155], v[202:205], v[24:27]
	v_mfma_f32_16x16x32_bf16 v[12:15], v[144:147], v[232:235], v[12:15]
	v_mfma_f32_16x16x32_bf16 v[8:11], v[152:155], v[232:235], v[8:11]
	v_mfma_f32_16x16x32_bf16 v[60:63], v[148:151], v[190:193], v[60:63]
	v_mfma_f32_16x16x32_bf16 v[56:59], v[156:159], v[190:193], v[56:59]
	v_mfma_f32_16x16x32_bf16 v[44:47], v[148:151], v[198:201], v[44:47]
	v_mfma_f32_16x16x32_bf16 v[40:43], v[156:159], v[198:201], v[40:43]
	v_mfma_f32_16x16x32_bf16 v[28:31], v[148:151], v[228:231], v[28:31]
	v_mfma_f32_16x16x32_bf16 v[24:27], v[156:159], v[228:231], v[24:27]
	v_mfma_f32_16x16x32_bf16 v[12:15], v[148:151], v[236:239], v[12:15]
	v_mfma_f32_16x16x32_bf16 v[8:11], v[156:159], v[236:239], v[8:11]
	v_mfma_f32_16x16x32_bf16 v[52:55], v[170:173], v[186:189], v[52:55]
	v_mfma_f32_16x16x32_bf16 v[48:51], v[178:181], v[186:189], v[48:51]
	v_mfma_f32_16x16x32_bf16 v[36:39], v[170:173], v[194:197], v[36:39]
	v_mfma_f32_16x16x32_bf16 v[32:35], v[178:181], v[194:197], v[32:35]
	v_mfma_f32_16x16x32_bf16 v[20:23], v[170:173], v[202:205], v[20:23]
	v_mfma_f32_16x16x32_bf16 v[16:19], v[178:181], v[202:205], v[16:19]
	v_mfma_f32_16x16x32_bf16 v[4:7], v[170:173], v[232:235], v[4:7]
	v_mfma_f32_16x16x32_bf16 v[0:3], v[178:181], v[232:235], v[0:3]
	v_mfma_f32_16x16x32_bf16 v[52:55], v[174:177], v[190:193], v[52:55]
	v_mfma_f32_16x16x32_bf16 v[48:51], v[182:185], v[190:193], v[48:51]
	v_mfma_f32_16x16x32_bf16 v[36:39], v[174:177], v[198:201], v[36:39]
	v_mfma_f32_16x16x32_bf16 v[32:35], v[182:185], v[198:201], v[32:35]
	v_mfma_f32_16x16x32_bf16 v[20:23], v[174:177], v[228:231], v[20:23]
	v_mfma_f32_16x16x32_bf16 v[16:19], v[182:185], v[228:231], v[16:19]
	v_mfma_f32_16x16x32_bf16 v[4:7], v[174:177], v[236:239], v[4:7]
	v_mfma_f32_16x16x32_bf16 v[0:3], v[182:185], v[236:239], v[0:3]
	s_barrier
	s_add_i32 s45, 0, 0x18000
	s_add_i32 s46, 0, 0x1c000
	v_add_u32_e32 v156, s45, v141
	v_add_u32_e32 v182, s46, v141
	ds_read_b128 v[144:147], v156
	ds_read_b128 v[148:151], v156 offset:1024
	ds_read_b128 v[152:155], v156 offset:2048
	ds_read_b128 v[156:159], v156 offset:3072
	ds_read_b128 v[170:173], v182
	ds_read_b128 v[174:177], v182 offset:1024
	ds_read_b128 v[178:181], v182 offset:2048
	ds_read_b128 v[182:185], v182 offset:3072
	s_add_u32 s24, s24, 0x40000
	s_addc_u32 s25, s25, 0
	s_mov_b32 m0, s31
	v_lshl_add_u64 v[240:241], s[24:25], 0, v[132:133]
	ds_read_b128 v[186:189], v143 offset:32768
	ds_read_b128 v[190:193], v143 offset:33792
	ds_read_b128 v[194:197], v143 offset:34816
	ds_read_b128 v[198:201], v143 offset:35840
	ds_read_b128 v[202:205], v143 offset:36864
	ds_read_b128 v[228:231], v143 offset:37888
	ds_read_b128 v[232:235], v143 offset:38912
	ds_read_b128 v[236:239], v143 offset:39936
	global_load_lds_dwordx4 v[240:241], off
	v_lshl_add_u64 v[240:241], s[24:25], 0, v[130:131]
	s_mov_b32 m0, s34
	s_nop 0
	global_load_lds_dwordx4 v[240:241], off
	s_waitcnt vmcnt(8)
	s_waitcnt lgkmcnt(0)
	s_barrier
	s_waitcnt lgkmcnt(0)
	v_mfma_f32_16x16x32_bf16 v[124:127], v[144:147], v[186:189], v[124:127]
	v_mfma_f32_16x16x32_bf16 v[120:123], v[152:155], v[186:189], v[120:123]
	v_mfma_f32_16x16x32_bf16 v[108:111], v[144:147], v[194:197], v[108:111]
	v_mfma_f32_16x16x32_bf16 v[104:107], v[152:155], v[194:197], v[104:107]
	v_mfma_f32_16x16x32_bf16 v[92:95], v[144:147], v[202:205], v[92:95]
	v_mfma_f32_16x16x32_bf16 v[88:91], v[152:155], v[202:205], v[88:91]
	v_mfma_f32_16x16x32_bf16 v[76:79], v[144:147], v[232:235], v[76:79]
	v_mfma_f32_16x16x32_bf16 v[72:75], v[152:155], v[232:235], v[72:75]
	v_mfma_f32_16x16x32_bf16 v[124:127], v[148:151], v[190:193], v[124:127]
	v_mfma_f32_16x16x32_bf16 v[120:123], v[156:159], v[190:193], v[120:123]
	v_mfma_f32_16x16x32_bf16 v[108:111], v[148:151], v[198:201], v[108:111]
	v_mfma_f32_16x16x32_bf16 v[104:107], v[156:159], v[198:201], v[104:107]
	v_mfma_f32_16x16x32_bf16 v[92:95], v[148:151], v[228:231], v[92:95]
	v_mfma_f32_16x16x32_bf16 v[88:91], v[156:159], v[228:231], v[88:91]
	v_mfma_f32_16x16x32_bf16 v[76:79], v[148:151], v[236:239], v[76:79]
	v_mfma_f32_16x16x32_bf16 v[72:75], v[156:159], v[236:239], v[72:75]
	v_mfma_f32_16x16x32_bf16 v[116:119], v[170:173], v[186:189], v[116:119]
	v_mfma_f32_16x16x32_bf16 v[112:115], v[178:181], v[186:189], v[112:115]
	v_mfma_f32_16x16x32_bf16 v[100:103], v[170:173], v[194:197], v[100:103]
	v_mfma_f32_16x16x32_bf16 v[96:99], v[178:181], v[194:197], v[96:99]
	v_mfma_f32_16x16x32_bf16 v[84:87], v[170:173], v[202:205], v[84:87]
	v_mfma_f32_16x16x32_bf16 v[80:83], v[178:181], v[202:205], v[80:83]
	v_mfma_f32_16x16x32_bf16 v[68:71], v[170:173], v[232:235], v[68:71]
	v_mfma_f32_16x16x32_bf16 v[64:67], v[178:181], v[232:235], v[64:67]
	v_mfma_f32_16x16x32_bf16 v[116:119], v[174:177], v[190:193], v[116:119]
	v_mfma_f32_16x16x32_bf16 v[112:115], v[182:185], v[190:193], v[112:115]
	v_mfma_f32_16x16x32_bf16 v[100:103], v[174:177], v[198:201], v[100:103]
	v_mfma_f32_16x16x32_bf16 v[96:99], v[182:185], v[198:201], v[96:99]
	v_mfma_f32_16x16x32_bf16 v[84:87], v[174:177], v[228:231], v[84:87]
	v_mfma_f32_16x16x32_bf16 v[80:83], v[182:185], v[228:231], v[80:83]
	v_mfma_f32_16x16x32_bf16 v[68:71], v[174:177], v[236:239], v[68:71]
	v_mfma_f32_16x16x32_bf16 v[64:67], v[182:185], v[236:239], v[64:67]
	s_barrier
	s_add_i32 s24, s45, s77
	v_lshl_add_u64 v[138:139], v[138:139], 0, s[96:97]
	s_mov_b32 m0, s24
	ds_read_b128 v[186:189], v143 offset:49152
	ds_read_b128 v[190:193], v143 offset:50176
	ds_read_b128 v[194:197], v143 offset:51200
	ds_read_b128 v[198:201], v143 offset:52224
	ds_read_b128 v[202:205], v143 offset:53248
	ds_read_b128 v[228:231], v143 offset:54272
	ds_read_b128 v[232:235], v143 offset:55296
	ds_read_b128 v[236:239], v143 offset:56320
	global_load_lds_dwordx4 v[138:139], off
	s_add_i32 m0, s24, 0x2000
	s_add_u32 s22, s22, 0x40080
	v_lshl_add_u64 v[138:139], v[166:167], 0, s[96:97]
	s_addc_u32 s23, s23, 0
	s_add_i32 s24, s46, s77
	global_load_lds_dwordx4 v[138:139], off
	v_lshl_add_u64 v[138:139], s[22:23], 0, v[160:161]
	s_mov_b32 m0, s24
	s_nop 0
	global_load_lds_dwordx4 v[138:139], off
	v_lshl_add_u64 v[138:139], s[22:23], 0, v[128:129]
	s_add_i32 m0, s24, 0x2000
	s_nop 0
	global_load_lds_dwordx4 v[138:139], off
	v_lshl_add_u64 v[138:139], v[168:169], 0, s[96:97]
	s_mov_b32 m0, s35
	s_nop 0
	global_load_lds_dwordx4 v[138:139], off
	v_lshl_add_u64 v[138:139], v[206:207], 0, s[96:97]
	s_mov_b32 m0, s36
	s_nop 0
	global_load_lds_dwordx4 v[138:139], off
	s_waitcnt vmcnt(8)
	s_waitcnt lgkmcnt(0)
	s_barrier
	s_waitcnt lgkmcnt(0)
	v_mfma_f32_16x16x32_bf16 v[60:63], v[144:147], v[186:189], v[60:63]
	v_mfma_f32_16x16x32_bf16 v[56:59], v[152:155], v[186:189], v[56:59]
	v_mfma_f32_16x16x32_bf16 v[44:47], v[144:147], v[194:197], v[44:47]
	v_mfma_f32_16x16x32_bf16 v[40:43], v[152:155], v[194:197], v[40:43]
	v_mfma_f32_16x16x32_bf16 v[28:31], v[144:147], v[202:205], v[28:31]
	v_mfma_f32_16x16x32_bf16 v[24:27], v[152:155], v[202:205], v[24:27]
	v_mfma_f32_16x16x32_bf16 v[12:15], v[144:147], v[232:235], v[12:15]
	v_mfma_f32_16x16x32_bf16 v[8:11], v[152:155], v[232:235], v[8:11]
	v_mfma_f32_16x16x32_bf16 v[60:63], v[148:151], v[190:193], v[60:63]
	v_mfma_f32_16x16x32_bf16 v[56:59], v[156:159], v[190:193], v[56:59]
	v_mfma_f32_16x16x32_bf16 v[44:47], v[148:151], v[198:201], v[44:47]
	v_mfma_f32_16x16x32_bf16 v[40:43], v[156:159], v[198:201], v[40:43]
	v_mfma_f32_16x16x32_bf16 v[28:31], v[148:151], v[228:231], v[28:31]
	v_mfma_f32_16x16x32_bf16 v[24:27], v[156:159], v[228:231], v[24:27]
	v_mfma_f32_16x16x32_bf16 v[12:15], v[148:151], v[236:239], v[12:15]
	v_mfma_f32_16x16x32_bf16 v[8:11], v[156:159], v[236:239], v[8:11]
	v_mfma_f32_16x16x32_bf16 v[52:55], v[170:173], v[186:189], v[52:55]
	v_mfma_f32_16x16x32_bf16 v[48:51], v[178:181], v[186:189], v[48:51]
	v_mfma_f32_16x16x32_bf16 v[36:39], v[170:173], v[194:197], v[36:39]
	v_mfma_f32_16x16x32_bf16 v[32:35], v[178:181], v[194:197], v[32:35]
	v_mfma_f32_16x16x32_bf16 v[20:23], v[170:173], v[202:205], v[20:23]
	v_mfma_f32_16x16x32_bf16 v[16:19], v[178:181], v[202:205], v[16:19]
	v_mfma_f32_16x16x32_bf16 v[4:7], v[170:173], v[232:235], v[4:7]
	v_mfma_f32_16x16x32_bf16 v[0:3], v[178:181], v[232:235], v[0:3]
	v_mfma_f32_16x16x32_bf16 v[52:55], v[174:177], v[190:193], v[52:55]
	v_mfma_f32_16x16x32_bf16 v[48:51], v[182:185], v[190:193], v[48:51]
	v_mfma_f32_16x16x32_bf16 v[36:39], v[174:177], v[198:201], v[36:39]
	v_mfma_f32_16x16x32_bf16 v[32:35], v[182:185], v[198:201], v[32:35]
	v_mfma_f32_16x16x32_bf16 v[20:23], v[174:177], v[228:231], v[20:23]
	v_mfma_f32_16x16x32_bf16 v[16:19], v[182:185], v[228:231], v[16:19]
	v_mfma_f32_16x16x32_bf16 v[4:7], v[174:177], v[236:239], v[4:7]
	v_mfma_f32_16x16x32_bf16 v[0:3], v[182:185], v[236:239], v[0:3]
	s_barrier
	s_add_i32 s44, s44, 2
	s_add_u32 s42, s42, 0x100
	s_addc_u32 s43, s43, 0
	s_add_u32 s20, s20, 0x100
	s_addc_u32 s21, s21, 0
	s_cmp_gt_u32 s44, 13
	s_cbranch_scc0 .LBB0_72
	s_setprio 0
	v_readlane_b32 s20, v253, 23
	v_readlane_b32 s21, v253, 24
	s_and_b64 vcc, exec, s[20:21]
	s_cbranch_vccz .LBB0_75
	s_barrier

.LBB0_104:
	s_ashr_i32 s13, s12, 31
	s_lshl_b64 s[14:15], s[12:13], 19
	s_add_u32 s14, s2, s14
	s_addc_u32 s15, s24, s15
	s_and_b64 s[16:17], s[6:7], exec
	s_cselect_b32 s13, s15, s21
	s_cselect_b32 s40, s14, s20
	s_ashr_i32 s11, s10, 31
	s_lshl_b64 s[16:17], s[10:11], 19
	s_add_u32 s16, s25, s16
	s_addc_u32 s17, s26, s17
	s_and_b64 s[22:23], s[6:7], exec
	s_cselect_b32 s11, s17, s19
	s_cselect_b32 s41, s16, s18
	s_add_u32 s42, s18, 0x100
	s_addc_u32 s43, s19, 0
	s_add_u32 s18, s20, 0x40080
	v_mov_b32_e32 v0, 0
	s_addc_u32 s19, s21, 0
	s_mov_b32 s44, -2
	v_mov_b32_e32 v1, v0
	v_mov_b32_e32 v2, v0
	v_mov_b32_e32 v3, v0
	v_mov_b32_e32 v4, v0
	v_mov_b32_e32 v5, v0
	v_mov_b32_e32 v6, v0
	v_mov_b32_e32 v7, v0
	v_mov_b32_e32 v8, v0
	v_mov_b32_e32 v9, v0
	v_mov_b32_e32 v10, v0
	v_mov_b32_e32 v11, v0
	v_mov_b32_e32 v12, v0
	v_mov_b32_e32 v13, v0
	v_mov_b32_e32 v14, v0
	v_mov_b32_e32 v15, v0
	v_mov_b32_e32 v16, v0
	v_mov_b32_e32 v17, v0
	v_mov_b32_e32 v18, v0
	v_mov_b32_e32 v19, v0
	v_mov_b32_e32 v20, v0
	v_mov_b32_e32 v21, v0
	v_mov_b32_e32 v22, v0
	v_mov_b32_e32 v23, v0
	v_mov_b32_e32 v24, v0
	v_mov_b32_e32 v25, v0
	v_mov_b32_e32 v26, v0
	v_mov_b32_e32 v27, v0
	v_mov_b32_e32 v28, v0
	v_mov_b32_e32 v29, v0
	v_mov_b32_e32 v30, v0
	v_mov_b32_e32 v31, v0
	v_mov_b32_e32 v56, v0
	v_mov_b32_e32 v57, v0
	v_mov_b32_e32 v58, v0
	v_mov_b32_e32 v59, v0
	v_mov_b32_e32 v68, v0
	v_mov_b32_e32 v69, v0
	v_mov_b32_e32 v70, v0
	v_mov_b32_e32 v71, v0
	v_mov_b32_e32 v72, v0
	v_mov_b32_e32 v73, v0
	v_mov_b32_e32 v74, v0
	v_mov_b32_e32 v75, v0
	v_mov_b32_e32 v76, v0
	v_mov_b32_e32 v77, v0
	v_mov_b32_e32 v78, v0
	v_mov_b32_e32 v79, v0
	v_mov_b32_e32 v80, v0
	v_mov_b32_e32 v81, v0
	v_mov_b32_e32 v82, v0
	v_mov_b32_e32 v83, v0
	v_mov_b32_e32 v84, v0
	v_mov_b32_e32 v85, v0
	v_mov_b32_e32 v86, v0
	v_mov_b32_e32 v87, v0
	v_mov_b32_e32 v88, v0
	v_mov_b32_e32 v89, v0
	v_mov_b32_e32 v90, v0
	v_mov_b32_e32 v91, v0
	v_mov_b32_e32 v92, v0
	v_mov_b32_e32 v93, v0
	v_mov_b32_e32 v94, v0
	v_mov_b32_e32 v95, v0
	v_mov_b32_e32 v32, v0
	v_mov_b32_e32 v33, v0
	v_mov_b32_e32 v34, v0
	v_mov_b32_e32 v35, v0
	v_mov_b32_e32 v36, v0
	v_mov_b32_e32 v37, v0
	v_mov_b32_e32 v38, v0
	v_mov_b32_e32 v39, v0
	v_mov_b32_e32 v40, v0
	v_mov_b32_e32 v41, v0
	v_mov_b32_e32 v42, v0
	v_mov_b32_e32 v43, v0
	v_mov_b32_e32 v44, v0
	v_mov_b32_e32 v45, v0
	v_mov_b32_e32 v46, v0
	v_mov_b32_e32 v47, v0
	v_mov_b32_e32 v48, v0
	v_mov_b32_e32 v49, v0
	v_mov_b32_e32 v50, v0
	v_mov_b32_e32 v51, v0
	v_mov_b32_e32 v52, v0
	v_mov_b32_e32 v53, v0
	v_mov_b32_e32 v54, v0
	v_mov_b32_e32 v55, v0
	v_mov_b32_e32 v60, v0
	v_mov_b32_e32 v61, v0
	v_mov_b32_e32 v62, v0
	v_mov_b32_e32 v63, v0
	v_mov_b32_e32 v64, v0
	v_mov_b32_e32 v65, v0
	v_mov_b32_e32 v66, v0
	v_mov_b32_e32 v67, v0
	v_mov_b32_e32 v96, v0
	v_mov_b32_e32 v97, v0
	v_mov_b32_e32 v98, v0
	v_mov_b32_e32 v99, v0
	v_mov_b32_e32 v100, v0
	v_mov_b32_e32 v101, v0
	v_mov_b32_e32 v102, v0
	v_mov_b32_e32 v103, v0
	v_mov_b32_e32 v104, v0
	v_mov_b32_e32 v105, v0
	v_mov_b32_e32 v106, v0
	v_mov_b32_e32 v107, v0
	v_mov_b32_e32 v108, v0
	v_mov_b32_e32 v109, v0
	v_mov_b32_e32 v110, v0
	v_mov_b32_e32 v111, v0
	v_mov_b32_e32 v112, v0
	v_mov_b32_e32 v113, v0
	v_mov_b32_e32 v114, v0
	v_mov_b32_e32 v115, v0
	v_mov_b32_e32 v116, v0
	v_mov_b32_e32 v117, v0
	v_mov_b32_e32 v118, v0
	v_mov_b32_e32 v119, v0
	v_mov_b32_e32 v120, v0
	v_mov_b32_e32 v121, v0
	v_mov_b32_e32 v122, v0
	v_mov_b32_e32 v123, v0
	v_mov_b32_e32 v124, v0
	v_mov_b32_e32 v125, v0
	v_mov_b32_e32 v126, v0
	v_mov_b32_e32 v127, v0
	v_readlane_b32 s100, v252, 21
	s_sub_u32 s100, s100, 0
	s_cmp_lt_u32 s100, 4
	s_cbranch_scc0 .Lprio_1
	s_setprio 1
.Lprio_1:
.LBB0_105:
	s_add_u32 s20, s18, 0xfffc0080
	s_addc_u32 s21, s19, -1
	s_add_i32 s45, 0, 0x10000
	s_cmp_eq_u32 s44, 12
	s_cselect_b32 s23, s13, s21
	s_cselect_b32 s22, s40, s20
	s_cselect_b32 s21, s11, s43
	s_cselect_b32 s20, s41, s42
	s_add_i32 s48, 0, 0x14000
	v_add_u32_e32 v150, s45, v157
	v_add_u32_e32 v154, s48, v157
	ds_read_b128 v[128:131], v150
	ds_read_b128 v[132:135], v150 offset:1024
	ds_read_b128 v[146:149], v150 offset:2048
	ds_read_b128 v[150:153], v150 offset:3072
	ds_read_b128 v[170:173], v154
	ds_read_b128 v[174:177], v154 offset:1024
	ds_read_b128 v[178:181], v154 offset:2048
	ds_read_b128 v[182:185], v154 offset:3072
	v_lshl_add_u64 v[154:155], s[18:19], 0, v[144:145]
	s_add_i32 m0, s27, 0xc000
	ds_read_b128 v[186:189], v159
	ds_read_b128 v[190:193], v159 offset:1024
	ds_read_b128 v[194:197], v159 offset:2048
	ds_read_b128 v[198:201], v159 offset:3072
	ds_read_b128 v[202:205], v159 offset:4096
	ds_read_b128 v[228:231], v159 offset:5120
	ds_read_b128 v[232:235], v159 offset:6144
	ds_read_b128 v[236:239], v159 offset:7168
	global_load_lds_dwordx4 v[154:155], off
	v_lshl_add_u64 v[154:155], s[18:19], 0, v[142:143]
	s_add_i32 m0, s27, 0xe000
	s_nop 0
	global_load_lds_dwordx4 v[154:155], off
	s_waitcnt vmcnt(8)
	s_waitcnt lgkmcnt(0)
	s_barrier
	s_waitcnt lgkmcnt(0)
	v_mfma_f32_16x16x32_bf16 v[124:127], v[128:131], v[186:189], v[124:127]
	v_mfma_f32_16x16x32_bf16 v[120:123], v[146:149], v[186:189], v[120:123]
	v_mfma_f32_16x16x32_bf16 v[116:119], v[128:131], v[194:197], v[116:119]
	v_mfma_f32_16x16x32_bf16 v[112:115], v[146:149], v[194:197], v[112:115]
	v_mfma_f32_16x16x32_bf16 v[108:111], v[128:131], v[202:205], v[108:111]
	v_mfma_f32_16x16x32_bf16 v[104:107], v[146:149], v[202:205], v[104:107]
	v_mfma_f32_16x16x32_bf16 v[100:103], v[128:131], v[232:235], v[100:103]
	v_mfma_f32_16x16x32_bf16 v[96:99], v[146:149], v[232:235], v[96:99]
	v_mfma_f32_16x16x32_bf16 v[124:127], v[132:135], v[190:193], v[124:127]
	v_mfma_f32_16x16x32_bf16 v[120:123], v[150:153], v[190:193], v[120:123]
	v_mfma_f32_16x16x32_bf16 v[116:119], v[132:135], v[198:201], v[116:119]
	v_mfma_f32_16x16x32_bf16 v[112:115], v[150:153], v[198:201], v[112:115]
	v_mfma_f32_16x16x32_bf16 v[108:111], v[132:135], v[228:231], v[108:111]
	v_mfma_f32_16x16x32_bf16 v[104:107], v[150:153], v[228:231], v[104:107]
	v_mfma_f32_16x16x32_bf16 v[100:103], v[132:135], v[236:239], v[100:103]
	v_mfma_f32_16x16x32_bf16 v[96:99], v[150:153], v[236:239], v[96:99]
	v_mfma_f32_16x16x32_bf16 v[64:67], v[170:173], v[186:189], v[64:67]
	v_mfma_f32_16x16x32_bf16 v[60:63], v[178:181], v[186:189], v[60:63]
	v_mfma_f32_16x16x32_bf16 v[52:55], v[170:173], v[194:197], v[52:55]
	v_mfma_f32_16x16x32_bf16 v[48:51], v[178:181], v[194:197], v[48:51]
	v_mfma_f32_16x16x32_bf16 v[44:47], v[170:173], v[202:205], v[44:47]
	v_mfma_f32_16x16x32_bf16 v[40:43], v[178:181], v[202:205], v[40:43]
	v_mfma_f32_16x16x32_bf16 v[36:39], v[170:173], v[232:235], v[36:39]
	v_mfma_f32_16x16x32_bf16 v[32:35], v[178:181], v[232:235], v[32:35]
	v_mfma_f32_16x16x32_bf16 v[64:67], v[174:177], v[190:193], v[64:67]
	v_mfma_f32_16x16x32_bf16 v[60:63], v[182:185], v[190:193], v[60:63]
	v_mfma_f32_16x16x32_bf16 v[52:55], v[174:177], v[198:201], v[52:55]
	v_mfma_f32_16x16x32_bf16 v[48:51], v[182:185], v[198:201], v[48:51]
	v_mfma_f32_16x16x32_bf16 v[44:47], v[174:177], v[228:231], v[44:47]
	v_mfma_f32_16x16x32_bf16 v[40:43], v[182:185], v[228:231], v[40:43]
	v_mfma_f32_16x16x32_bf16 v[36:39], v[174:177], v[236:239], v[36:39]
	v_mfma_f32_16x16x32_bf16 v[32:35], v[182:185], v[236:239], v[32:35]
	s_barrier
	s_add_i32 s45, s45, s77
	v_lshl_add_u64 v[154:155], s[20:21], 0, v[160:161]
	s_mov_b32 m0, s45
	ds_read_b128 v[186:189], v159 offset:16384
	ds_read_b128 v[190:193], v159 offset:17408
	ds_read_b128 v[194:197], v159 offset:18432
	ds_read_b128 v[198:201], v159 offset:19456
	ds_read_b128 v[202:205], v159 offset:20480
	ds_read_b128 v[228:231], v159 offset:21504
	ds_read_b128 v[232:235], v159 offset:22528
	ds_read_b128 v[236:239], v159 offset:23552
	global_load_lds_dwordx4 v[154:155], off
	s_add_i32 m0, s45, 0x2000
	s_add_u32 s46, s20, 0x40000
	v_lshl_add_u64 v[166:167], s[20:21], 0, v[136:137]
	s_addc_u32 s47, s21, 0
	s_add_i32 s45, s48, s77
	global_load_lds_dwordx4 v[166:167], off
	v_lshl_add_u64 v[168:169], s[46:47], 0, v[160:161]
	s_mov_b32 m0, s45
	v_lshl_add_u64 v[206:207], s[22:23], 0, v[138:139]
	global_load_lds_dwordx4 v[168:169], off
	v_lshl_add_u64 v[168:169], s[46:47], 0, v[136:137]
	s_add_i32 m0, s45, 0x2000
	s_nop 0
	global_load_lds_dwordx4 v[168:169], off
	v_lshl_add_u64 v[168:169], s[22:23], 0, v[140:141]
	s_mov_b32 m0, s27
	s_nop 0
	global_load_lds_dwordx4 v[168:169], off
	s_mov_b32 m0, s28
	s_nop 0
	global_load_lds_dwordx4 v[206:207], off
	s_waitcnt vmcnt(8)
	s_waitcnt lgkmcnt(0)
	s_barrier
	s_waitcnt lgkmcnt(0)
	v_mfma_f32_16x16x32_bf16 v[92:95], v[128:131], v[186:189], v[92:95]
	v_mfma_f32_16x16x32_bf16 v[88:91], v[146:149], v[186:189], v[88:91]
	v_mfma_f32_16x16x32_bf16 v[84:87], v[128:131], v[194:197], v[84:87]
	v_mfma_f32_16x16x32_bf16 v[80:83], v[146:149], v[194:197], v[80:83]
	v_mfma_f32_16x16x32_bf16 v[76:79], v[128:131], v[202:205], v[76:79]
	v_mfma_f32_16x16x32_bf16 v[72:75], v[146:149], v[202:205], v[72:75]
	v_mfma_f32_16x16x32_bf16 v[68:71], v[128:131], v[232:235], v[68:71]
	v_mfma_f32_16x16x32_bf16 v[56:59], v[146:149], v[232:235], v[56:59]
	v_mfma_f32_16x16x32_bf16 v[92:95], v[132:135], v[190:193], v[92:95]
	v_mfma_f32_16x16x32_bf16 v[88:91], v[150:153], v[190:193], v[88:91]
	v_mfma_f32_16x16x32_bf16 v[84:87], v[132:135], v[198:201], v[84:87]
	v_mfma_f32_16x16x32_bf16 v[80:83], v[150:153], v[198:201], v[80:83]
	v_mfma_f32_16x16x32_bf16 v[76:79], v[132:135], v[228:231], v[76:79]
	v_mfma_f32_16x16x32_bf16 v[72:75], v[150:153], v[228:231], v[72:75]
	v_mfma_f32_16x16x32_bf16 v[68:71], v[132:135], v[236:239], v[68:71]
	v_mfma_f32_16x16x32_bf16 v[56:59], v[150:153], v[236:239], v[56:59]
	v_mfma_f32_16x16x32_bf16 v[28:31], v[170:173], v[186:189], v[28:31]
	v_mfma_f32_16x16x32_bf16 v[24:27], v[178:181], v[186:189], v[24:27]
	v_mfma_f32_16x16x32_bf16 v[20:23], v[170:173], v[194:197], v[20:23]
	v_mfma_f32_16x16x32_bf16 v[16:19], v[178:181], v[194:197], v[16:19]
	v_mfma_f32_16x16x32_bf16 v[12:15], v[170:173], v[202:205], v[12:15]
	v_mfma_f32_16x16x32_bf16 v[8:11], v[178:181], v[202:205], v[8:11]
	v_mfma_f32_16x16x32_bf16 v[4:7], v[170:173], v[232:235], v[4:7]
	v_mfma_f32_16x16x32_bf16 v[0:3], v[178:181], v[232:235], v[0:3]
	v_mfma_f32_16x16x32_bf16 v[28:31], v[174:177], v[190:193], v[28:31]
	v_mfma_f32_16x16x32_bf16 v[24:27], v[182:185], v[190:193], v[24:27]
	v_mfma_f32_16x16x32_bf16 v[20:23], v[174:177], v[198:201], v[20:23]
	v_mfma_f32_16x16x32_bf16 v[16:19], v[182:185], v[198:201], v[16:19]
	v_mfma_f32_16x16x32_bf16 v[12:15], v[174:177], v[228:231], v[12:15]
	v_mfma_f32_16x16x32_bf16 v[8:11], v[182:185], v[228:231], v[8:11]
	v_mfma_f32_16x16x32_bf16 v[4:7], v[174:177], v[236:239], v[4:7]
	v_mfma_f32_16x16x32_bf16 v[0:3], v[182:185], v[236:239], v[0:3]
	s_barrier
	s_add_i32 s45, 0, 0x18000
	s_add_i32 s46, 0, 0x1c000
	v_add_u32_e32 v150, s45, v157
	v_add_u32_e32 v182, s46, v157
	ds_read_b128 v[128:131], v150
	ds_read_b128 v[132:135], v150 offset:1024
	ds_read_b128 v[146:149], v150 offset:2048
	ds_read_b128 v[150:153], v150 offset:3072
	ds_read_b128 v[170:173], v182
	ds_read_b128 v[174:177], v182 offset:1024
	ds_read_b128 v[178:181], v182 offset:2048
	ds_read_b128 v[182:185], v182 offset:3072
	s_add_u32 s22, s22, 0x40000
	s_addc_u32 s23, s23, 0
	s_mov_b32 m0, s29
	v_lshl_add_u64 v[240:241], s[22:23], 0, v[140:141]
	ds_read_b128 v[186:189], v159 offset:32768
	ds_read_b128 v[190:193], v159 offset:33792
	ds_read_b128 v[194:197], v159 offset:34816
	ds_read_b128 v[198:201], v159 offset:35840
	ds_read_b128 v[202:205], v159 offset:36864
	ds_read_b128 v[228:231], v159 offset:37888
	ds_read_b128 v[232:235], v159 offset:38912
	ds_read_b128 v[236:239], v159 offset:39936
	global_load_lds_dwordx4 v[240:241], off
	v_lshl_add_u64 v[240:241], s[22:23], 0, v[138:139]
	s_mov_b32 m0, s30
	s_nop 0
	global_load_lds_dwordx4 v[240:241], off
	s_waitcnt vmcnt(8)
	s_waitcnt lgkmcnt(0)
	s_barrier
	s_waitcnt lgkmcnt(0)
	v_mfma_f32_16x16x32_bf16 v[124:127], v[128:131], v[186:189], v[124:127]
	v_mfma_f32_16x16x32_bf16 v[120:123], v[146:149], v[186:189], v[120:123]
	v_mfma_f32_16x16x32_bf16 v[116:119], v[128:131], v[194:197], v[116:119]
	v_mfma_f32_16x16x32_bf16 v[112:115], v[146:149], v[194:197], v[112:115]
	v_mfma_f32_16x16x32_bf16 v[108:111], v[128:131], v[202:205], v[108:111]
	v_mfma_f32_16x16x32_bf16 v[104:107], v[146:149], v[202:205], v[104:107]
	v_mfma_f32_16x16x32_bf16 v[100:103], v[128:131], v[232:235], v[100:103]
	v_mfma_f32_16x16x32_bf16 v[96:99], v[146:149], v[232:235], v[96:99]
	v_mfma_f32_16x16x32_bf16 v[124:127], v[132:135], v[190:193], v[124:127]
	v_mfma_f32_16x16x32_bf16 v[120:123], v[150:153], v[190:193], v[120:123]
	v_mfma_f32_16x16x32_bf16 v[116:119], v[132:135], v[198:201], v[116:119]
	v_mfma_f32_16x16x32_bf16 v[112:115], v[150:153], v[198:201], v[112:115]
	v_mfma_f32_16x16x32_bf16 v[108:111], v[132:135], v[228:231], v[108:111]
	v_mfma_f32_16x16x32_bf16 v[104:107], v[150:153], v[228:231], v[104:107]
	v_mfma_f32_16x16x32_bf16 v[100:103], v[132:135], v[236:239], v[100:103]
	v_mfma_f32_16x16x32_bf16 v[96:99], v[150:153], v[236:239], v[96:99]
	v_mfma_f32_16x16x32_bf16 v[64:67], v[170:173], v[186:189], v[64:67]
	v_mfma_f32_16x16x32_bf16 v[60:63], v[178:181], v[186:189], v[60:63]
	v_mfma_f32_16x16x32_bf16 v[52:55], v[170:173], v[194:197], v[52:55]
	v_mfma_f32_16x16x32_bf16 v[48:51], v[178:181], v[194:197], v[48:51]
	v_mfma_f32_16x16x32_bf16 v[44:47], v[170:173], v[202:205], v[44:47]
	v_mfma_f32_16x16x32_bf16 v[40:43], v[178:181], v[202:205], v[40:43]
	v_mfma_f32_16x16x32_bf16 v[36:39], v[170:173], v[232:235], v[36:39]
	v_mfma_f32_16x16x32_bf16 v[32:35], v[178:181], v[232:235], v[32:35]
	v_mfma_f32_16x16x32_bf16 v[64:67], v[174:177], v[190:193], v[64:67]
	v_mfma_f32_16x16x32_bf16 v[60:63], v[182:185], v[190:193], v[60:63]
	v_mfma_f32_16x16x32_bf16 v[52:55], v[174:177], v[198:201], v[52:55]
	v_mfma_f32_16x16x32_bf16 v[48:51], v[182:185], v[198:201], v[48:51]
	v_mfma_f32_16x16x32_bf16 v[44:47], v[174:177], v[228:231], v[44:47]
	v_mfma_f32_16x16x32_bf16 v[40:43], v[182:185], v[228:231], v[40:43]
	v_mfma_f32_16x16x32_bf16 v[36:39], v[174:177], v[236:239], v[36:39]
	v_mfma_f32_16x16x32_bf16 v[32:35], v[182:185], v[236:239], v[32:35]
	s_barrier
	s_add_i32 s22, s45, s77
	v_lshl_add_u64 v[154:155], v[154:155], 0, s[96:97]
	s_mov_b32 m0, s22
	ds_read_b128 v[186:189], v159 offset:49152
	ds_read_b128 v[190:193], v159 offset:50176
	ds_read_b128 v[194:197], v159 offset:51200
	ds_read_b128 v[198:201], v159 offset:52224
	ds_read_b128 v[202:205], v159 offset:53248
	ds_read_b128 v[228:231], v159 offset:54272
	ds_read_b128 v[232:235], v159 offset:55296
	ds_read_b128 v[236:239], v159 offset:56320
	global_load_lds_dwordx4 v[154:155], off
	s_add_i32 m0, s22, 0x2000
	s_add_u32 s20, s20, 0x40080
	v_lshl_add_u64 v[154:155], v[166:167], 0, s[96:97]
	s_addc_u32 s21, s21, 0
	s_add_i32 s22, s46, s77
	global_load_lds_dwordx4 v[154:155], off
	v_lshl_add_u64 v[154:155], s[20:21], 0, v[160:161]
	s_mov_b32 m0, s22
	s_nop 0
	global_load_lds_dwordx4 v[154:155], off
	v_lshl_add_u64 v[154:155], s[20:21], 0, v[136:137]
	s_add_i32 m0, s22, 0x2000
	s_nop 0
	global_load_lds_dwordx4 v[154:155], off
	v_lshl_add_u64 v[154:155], v[168:169], 0, s[96:97]
	s_mov_b32 m0, s35
	s_nop 0
	global_load_lds_dwordx4 v[154:155], off
	v_lshl_add_u64 v[154:155], v[206:207], 0, s[96:97]
	s_mov_b32 m0, s36
	s_nop 0
	global_load_lds_dwordx4 v[154:155], off
	s_waitcnt vmcnt(8)
	s_waitcnt lgkmcnt(0)
	s_barrier
	s_waitcnt lgkmcnt(0)
	v_mfma_f32_16x16x32_bf16 v[92:95], v[128:131], v[186:189], v[92:95]
	v_mfma_f32_16x16x32_bf16 v[88:91], v[146:149], v[186:189], v[88:91]
	v_mfma_f32_16x16x32_bf16 v[84:87], v[128:131], v[194:197], v[84:87]
	v_mfma_f32_16x16x32_bf16 v[80:83], v[146:149], v[194:197], v[80:83]
	v_mfma_f32_16x16x32_bf16 v[76:79], v[128:131], v[202:205], v[76:79]
	v_mfma_f32_16x16x32_bf16 v[72:75], v[146:149], v[202:205], v[72:75]
	v_mfma_f32_16x16x32_bf16 v[68:71], v[128:131], v[232:235], v[68:71]
	v_mfma_f32_16x16x32_bf16 v[56:59], v[146:149], v[232:235], v[56:59]
	v_mfma_f32_16x16x32_bf16 v[92:95], v[132:135], v[190:193], v[92:95]
	v_mfma_f32_16x16x32_bf16 v[88:91], v[150:153], v[190:193], v[88:91]
	v_mfma_f32_16x16x32_bf16 v[84:87], v[132:135], v[198:201], v[84:87]
	v_mfma_f32_16x16x32_bf16 v[80:83], v[150:153], v[198:201], v[80:83]
	v_mfma_f32_16x16x32_bf16 v[76:79], v[132:135], v[228:231], v[76:79]
	v_mfma_f32_16x16x32_bf16 v[72:75], v[150:153], v[228:231], v[72:75]
	v_mfma_f32_16x16x32_bf16 v[68:71], v[132:135], v[236:239], v[68:71]
	v_mfma_f32_16x16x32_bf16 v[56:59], v[150:153], v[236:239], v[56:59]
	v_mfma_f32_16x16x32_bf16 v[28:31], v[170:173], v[186:189], v[28:31]
	v_mfma_f32_16x16x32_bf16 v[24:27], v[178:181], v[186:189], v[24:27]
	v_mfma_f32_16x16x32_bf16 v[20:23], v[170:173], v[194:197], v[20:23]
	v_mfma_f32_16x16x32_bf16 v[16:19], v[178:181], v[194:197], v[16:19]
	v_mfma_f32_16x16x32_bf16 v[12:15], v[170:173], v[202:205], v[12:15]
	v_mfma_f32_16x16x32_bf16 v[8:11], v[178:181], v[202:205], v[8:11]
	v_mfma_f32_16x16x32_bf16 v[4:7], v[170:173], v[232:235], v[4:7]
	v_mfma_f32_16x16x32_bf16 v[0:3], v[178:181], v[232:235], v[0:3]
	v_mfma_f32_16x16x32_bf16 v[28:31], v[174:177], v[190:193], v[28:31]
	v_mfma_f32_16x16x32_bf16 v[24:27], v[182:185], v[190:193], v[24:27]
	v_mfma_f32_16x16x32_bf16 v[20:23], v[174:177], v[198:201], v[20:23]
	v_mfma_f32_16x16x32_bf16 v[16:19], v[182:185], v[198:201], v[16:19]
	v_mfma_f32_16x16x32_bf16 v[12:15], v[174:177], v[228:231], v[12:15]
	v_mfma_f32_16x16x32_bf16 v[8:11], v[182:185], v[228:231], v[8:11]
	v_mfma_f32_16x16x32_bf16 v[4:7], v[174:177], v[236:239], v[4:7]
	v_mfma_f32_16x16x32_bf16 v[0:3], v[182:185], v[236:239], v[0:3]
	s_barrier
	s_add_i32 s44, s44, 2
	s_add_u32 s42, s42, 0x100
	s_addc_u32 s43, s43, 0
	s_add_u32 s18, s18, 0x100
	s_addc_u32 s19, s19, 0
	s_cmp_gt_u32 s44, 13
	s_cbranch_scc0 .LBB0_105
	s_setprio 0
	v_readlane_b32 s18, v253, 23
	v_readlane_b32 s19, v253, 24
	s_and_b64 vcc, exec, s[18:19]
	s_cbranch_vccz .LBB0_108
	s_barrier

.LBB0_126:
	s_ashr_i32 s17, s16, 31
	s_lshl_b64 s[18:19], s[16:17], 18
	s_add_u32 s18, s2, s18
	s_addc_u32 s19, s28, s19
	s_and_b64 s[20:21], s[8:9], exec
	s_cselect_b32 s17, s19, s25
	s_cselect_b32 s42, s18, s24
	s_ashr_i32 s15, s14, 31
	s_lshl_b64 s[20:21], s[14:15], 18
	s_add_u32 s20, s29, s20
	s_addc_u32 s21, s30, s21
	s_and_b64 s[26:27], s[8:9], exec
	s_cselect_b32 s15, s21, s23
	s_cselect_b32 s43, s20, s22
	s_add_u32 s44, s22, 0x100
	s_addc_u32 s45, s23, 0
	s_add_u32 s22, s24, 0x20080
	v_mov_b32_e32 v0, 0
	s_addc_u32 s23, s25, 0
	s_mov_b32 s46, -2
	v_mov_b32_e32 v1, v0
	v_mov_b32_e32 v2, v0
	v_mov_b32_e32 v3, v0
	v_mov_b32_e32 v4, v0
	v_mov_b32_e32 v5, v0
	v_mov_b32_e32 v6, v0
	v_mov_b32_e32 v7, v0
	v_mov_b32_e32 v16, v0
	v_mov_b32_e32 v17, v0
	v_mov_b32_e32 v18, v0
	v_mov_b32_e32 v19, v0
	v_mov_b32_e32 v20, v0
	v_mov_b32_e32 v21, v0
	v_mov_b32_e32 v22, v0
	v_mov_b32_e32 v23, v0
	v_mov_b32_e32 v32, v0
	v_mov_b32_e32 v33, v0
	v_mov_b32_e32 v34, v0
	v_mov_b32_e32 v35, v0
	v_mov_b32_e32 v36, v0
	v_mov_b32_e32 v37, v0
	v_mov_b32_e32 v38, v0
	v_mov_b32_e32 v39, v0
	v_mov_b32_e32 v48, v0
	v_mov_b32_e32 v49, v0
	v_mov_b32_e32 v50, v0
	v_mov_b32_e32 v51, v0
	v_mov_b32_e32 v52, v0
	v_mov_b32_e32 v53, v0
	v_mov_b32_e32 v54, v0
	v_mov_b32_e32 v55, v0
	v_mov_b32_e32 v8, v0
	v_mov_b32_e32 v9, v0
	v_mov_b32_e32 v10, v0
	v_mov_b32_e32 v11, v0
	v_mov_b32_e32 v12, v0
	v_mov_b32_e32 v13, v0
	v_mov_b32_e32 v14, v0
	v_mov_b32_e32 v15, v0
	v_mov_b32_e32 v24, v0
	v_mov_b32_e32 v25, v0
	v_mov_b32_e32 v26, v0
	v_mov_b32_e32 v27, v0
	v_mov_b32_e32 v28, v0
	v_mov_b32_e32 v29, v0
	v_mov_b32_e32 v30, v0
	v_mov_b32_e32 v31, v0
	v_mov_b32_e32 v40, v0
	v_mov_b32_e32 v41, v0
	v_mov_b32_e32 v42, v0
	v_mov_b32_e32 v43, v0
	v_mov_b32_e32 v44, v0
	v_mov_b32_e32 v45, v0
	v_mov_b32_e32 v46, v0
	v_mov_b32_e32 v47, v0
	v_mov_b32_e32 v56, v0
	v_mov_b32_e32 v57, v0
	v_mov_b32_e32 v58, v0
	v_mov_b32_e32 v59, v0
	v_mov_b32_e32 v60, v0
	v_mov_b32_e32 v61, v0
	v_mov_b32_e32 v62, v0
	v_mov_b32_e32 v63, v0
	v_mov_b32_e32 v64, v0
	v_mov_b32_e32 v65, v0
	v_mov_b32_e32 v66, v0
	v_mov_b32_e32 v67, v0
	v_mov_b32_e32 v68, v0
	v_mov_b32_e32 v69, v0
	v_mov_b32_e32 v70, v0
	v_mov_b32_e32 v71, v0
	v_mov_b32_e32 v80, v0
	v_mov_b32_e32 v81, v0
	v_mov_b32_e32 v82, v0
	v_mov_b32_e32 v83, v0
	v_mov_b32_e32 v84, v0
	v_mov_b32_e32 v85, v0
	v_mov_b32_e32 v86, v0
	v_mov_b32_e32 v87, v0
	v_mov_b32_e32 v96, v0
	v_mov_b32_e32 v97, v0
	v_mov_b32_e32 v98, v0
	v_mov_b32_e32 v99, v0
	v_mov_b32_e32 v100, v0
	v_mov_b32_e32 v101, v0
	v_mov_b32_e32 v102, v0
	v_mov_b32_e32 v103, v0
	v_mov_b32_e32 v112, v0
	v_mov_b32_e32 v113, v0
	v_mov_b32_e32 v114, v0
	v_mov_b32_e32 v115, v0
	v_mov_b32_e32 v116, v0
	v_mov_b32_e32 v117, v0
	v_mov_b32_e32 v118, v0
	v_mov_b32_e32 v119, v0
	v_mov_b32_e32 v72, v0
	v_mov_b32_e32 v73, v0
	v_mov_b32_e32 v74, v0
	v_mov_b32_e32 v75, v0
	v_mov_b32_e32 v76, v0
	v_mov_b32_e32 v77, v0
	v_mov_b32_e32 v78, v0
	v_mov_b32_e32 v79, v0
	v_mov_b32_e32 v88, v0
	v_mov_b32_e32 v89, v0
	v_mov_b32_e32 v90, v0
	v_mov_b32_e32 v91, v0
	v_mov_b32_e32 v92, v0
	v_mov_b32_e32 v93, v0
	v_mov_b32_e32 v94, v0
	v_mov_b32_e32 v95, v0
	v_mov_b32_e32 v104, v0
	v_mov_b32_e32 v105, v0
	v_mov_b32_e32 v106, v0
	v_mov_b32_e32 v107, v0
	v_mov_b32_e32 v108, v0
	v_mov_b32_e32 v109, v0
	v_mov_b32_e32 v110, v0
	v_mov_b32_e32 v111, v0
	v_mov_b32_e32 v120, v0
	v_mov_b32_e32 v121, v0
	v_mov_b32_e32 v122, v0
	v_mov_b32_e32 v123, v0
	v_mov_b32_e32 v124, v0
	v_mov_b32_e32 v125, v0
	v_mov_b32_e32 v126, v0
	v_mov_b32_e32 v127, v0
	v_readlane_b32 s100, v252, 21
	s_sub_u32 s100, s100, 0
	s_cmp_lt_u32 s100, 4
	s_cbranch_scc0 .Lprio_2
	s_setprio 1
.Lprio_2:
.LBB0_127:
	s_add_u32 s24, s22, 0xfffe0080
	s_addc_u32 s25, s23, -1
	s_add_i32 s47, 0, 0x10000
	s_cmp_eq_u32 s46, 4
	s_cselect_b32 s27, s17, s25
	s_cselect_b32 s26, s42, s24
	v_add_u32_e32 v142, s47, v145
	s_cselect_b32 s25, s15, s45
	s_cselect_b32 s24, s43, s44
	s_add_i32 s50, 0, 0x14000
	ds_read_b128 v[138:141], v142
	ds_read_b128 v[148:151], v142 offset:1024
	ds_read_b128 v[152:155], v142 offset:2048
	ds_read_b128 v[156:159], v142 offset:3072
	v_add_u32_e32 v142, s50, v145
	ds_read_b128 v[170:173], v142
	ds_read_b128 v[174:177], v142 offset:1024
	ds_read_b128 v[178:181], v142 offset:2048
	ds_read_b128 v[182:185], v142 offset:3072
	v_lshl_add_u64 v[142:143], s[22:23], 0, v[136:137]
	s_add_i32 m0, s31, 0xc000
	ds_read_b128 v[186:189], v147
	ds_read_b128 v[190:193], v147 offset:1024
	ds_read_b128 v[194:197], v147 offset:2048
	ds_read_b128 v[198:201], v147 offset:3072
	ds_read_b128 v[202:205], v147 offset:4096
	ds_read_b128 v[228:231], v147 offset:5120
	ds_read_b128 v[232:235], v147 offset:6144
	ds_read_b128 v[236:239], v147 offset:7168
	global_load_lds_dwordx4 v[142:143], off
	v_lshl_add_u64 v[142:143], s[22:23], 0, v[134:135]
	s_add_i32 m0, s31, 0xe000
	s_nop 0
	global_load_lds_dwordx4 v[142:143], off
	s_waitcnt vmcnt(8)
	s_waitcnt lgkmcnt(0)
	s_barrier
	s_waitcnt lgkmcnt(0)
	v_mfma_f32_16x16x32_bf16 v[124:127], v[138:141], v[186:189], v[124:127]
	v_mfma_f32_16x16x32_bf16 v[120:123], v[152:155], v[186:189], v[120:123]
	v_mfma_f32_16x16x32_bf16 v[108:111], v[138:141], v[194:197], v[108:111]
	v_mfma_f32_16x16x32_bf16 v[104:107], v[152:155], v[194:197], v[104:107]
	v_mfma_f32_16x16x32_bf16 v[92:95], v[138:141], v[202:205], v[92:95]
	v_mfma_f32_16x16x32_bf16 v[88:91], v[152:155], v[202:205], v[88:91]
	v_mfma_f32_16x16x32_bf16 v[76:79], v[138:141], v[232:235], v[76:79]
	v_mfma_f32_16x16x32_bf16 v[72:75], v[152:155], v[232:235], v[72:75]
	v_mfma_f32_16x16x32_bf16 v[124:127], v[148:151], v[190:193], v[124:127]
	v_mfma_f32_16x16x32_bf16 v[120:123], v[156:159], v[190:193], v[120:123]
	v_mfma_f32_16x16x32_bf16 v[108:111], v[148:151], v[198:201], v[108:111]
	v_mfma_f32_16x16x32_bf16 v[104:107], v[156:159], v[198:201], v[104:107]
	v_mfma_f32_16x16x32_bf16 v[92:95], v[148:151], v[228:231], v[92:95]
	v_mfma_f32_16x16x32_bf16 v[88:91], v[156:159], v[228:231], v[88:91]
	v_mfma_f32_16x16x32_bf16 v[76:79], v[148:151], v[236:239], v[76:79]
	v_mfma_f32_16x16x32_bf16 v[72:75], v[156:159], v[236:239], v[72:75]
	v_mfma_f32_16x16x32_bf16 v[116:119], v[170:173], v[186:189], v[116:119]
	v_mfma_f32_16x16x32_bf16 v[112:115], v[178:181], v[186:189], v[112:115]
	v_mfma_f32_16x16x32_bf16 v[100:103], v[170:173], v[194:197], v[100:103]
	v_mfma_f32_16x16x32_bf16 v[96:99], v[178:181], v[194:197], v[96:99]
	v_mfma_f32_16x16x32_bf16 v[84:87], v[170:173], v[202:205], v[84:87]
	v_mfma_f32_16x16x32_bf16 v[80:83], v[178:181], v[202:205], v[80:83]
	v_mfma_f32_16x16x32_bf16 v[68:71], v[170:173], v[232:235], v[68:71]
	v_mfma_f32_16x16x32_bf16 v[64:67], v[178:181], v[232:235], v[64:67]
	v_mfma_f32_16x16x32_bf16 v[116:119], v[174:177], v[190:193], v[116:119]
	v_mfma_f32_16x16x32_bf16 v[112:115], v[182:185], v[190:193], v[112:115]
	v_mfma_f32_16x16x32_bf16 v[100:103], v[174:177], v[198:201], v[100:103]
	v_mfma_f32_16x16x32_bf16 v[96:99], v[182:185], v[198:201], v[96:99]
	v_mfma_f32_16x16x32_bf16 v[84:87], v[174:177], v[228:231], v[84:87]
	v_mfma_f32_16x16x32_bf16 v[80:83], v[182:185], v[228:231], v[80:83]
	v_mfma_f32_16x16x32_bf16 v[68:71], v[174:177], v[236:239], v[68:71]
	v_mfma_f32_16x16x32_bf16 v[64:67], v[182:185], v[236:239], v[64:67]
	s_barrier
	s_add_i32 s47, s47, s77
	v_lshl_add_u64 v[142:143], s[24:25], 0, v[160:161]
	s_mov_b32 m0, s47
	ds_read_b128 v[186:189], v147 offset:16384
	ds_read_b128 v[190:193], v147 offset:17408
	ds_read_b128 v[194:197], v147 offset:18432
	ds_read_b128 v[198:201], v147 offset:19456
	ds_read_b128 v[202:205], v147 offset:20480
	ds_read_b128 v[228:231], v147 offset:21504
	ds_read_b128 v[232:235], v147 offset:22528
	ds_read_b128 v[236:239], v147 offset:23552
	global_load_lds_dwordx4 v[142:143], off
	s_add_i32 m0, s47, 0x2000
	s_add_u32 s48, s24, 0x20000
	v_lshl_add_u64 v[166:167], s[24:25], 0, v[128:129]
	s_addc_u32 s49, s25, 0
	s_add_i32 s47, s50, s77
	global_load_lds_dwordx4 v[166:167], off
	v_lshl_add_u64 v[168:169], s[48:49], 0, v[160:161]
	s_mov_b32 m0, s47
	v_lshl_add_u64 v[206:207], s[26:27], 0, v[130:131]
	global_load_lds_dwordx4 v[168:169], off
	v_lshl_add_u64 v[168:169], s[48:49], 0, v[128:129]
	s_add_i32 m0, s47, 0x2000
	s_nop 0
	global_load_lds_dwordx4 v[168:169], off
	v_lshl_add_u64 v[168:169], s[26:27], 0, v[132:133]
	s_mov_b32 m0, s31
	s_nop 0
	global_load_lds_dwordx4 v[168:169], off
	s_mov_b32 m0, s34
	s_nop 0
	global_load_lds_dwordx4 v[206:207], off
	s_waitcnt vmcnt(8)
	s_waitcnt lgkmcnt(0)
	s_barrier
	s_waitcnt lgkmcnt(0)
	v_mfma_f32_16x16x32_bf16 v[60:63], v[138:141], v[186:189], v[60:63]
	v_mfma_f32_16x16x32_bf16 v[56:59], v[152:155], v[186:189], v[56:59]
	v_mfma_f32_16x16x32_bf16 v[44:47], v[138:141], v[194:197], v[44:47]
	v_mfma_f32_16x16x32_bf16 v[40:43], v[152:155], v[194:197], v[40:43]
	v_mfma_f32_16x16x32_bf16 v[28:31], v[138:141], v[202:205], v[28:31]
	v_mfma_f32_16x16x32_bf16 v[24:27], v[152:155], v[202:205], v[24:27]
	v_mfma_f32_16x16x32_bf16 v[12:15], v[138:141], v[232:235], v[12:15]
	v_mfma_f32_16x16x32_bf16 v[8:11], v[152:155], v[232:235], v[8:11]
	v_mfma_f32_16x16x32_bf16 v[60:63], v[148:151], v[190:193], v[60:63]
	v_mfma_f32_16x16x32_bf16 v[56:59], v[156:159], v[190:193], v[56:59]
	v_mfma_f32_16x16x32_bf16 v[44:47], v[148:151], v[198:201], v[44:47]
	v_mfma_f32_16x16x32_bf16 v[40:43], v[156:159], v[198:201], v[40:43]
	v_mfma_f32_16x16x32_bf16 v[28:31], v[148:151], v[228:231], v[28:31]
	v_mfma_f32_16x16x32_bf16 v[24:27], v[156:159], v[228:231], v[24:27]
	v_mfma_f32_16x16x32_bf16 v[12:15], v[148:151], v[236:239], v[12:15]
	v_mfma_f32_16x16x32_bf16 v[8:11], v[156:159], v[236:239], v[8:11]
	v_mfma_f32_16x16x32_bf16 v[52:55], v[170:173], v[186:189], v[52:55]
	v_mfma_f32_16x16x32_bf16 v[48:51], v[178:181], v[186:189], v[48:51]
	v_mfma_f32_16x16x32_bf16 v[36:39], v[170:173], v[194:197], v[36:39]
	v_mfma_f32_16x16x32_bf16 v[32:35], v[178:181], v[194:197], v[32:35]
	v_mfma_f32_16x16x32_bf16 v[20:23], v[170:173], v[202:205], v[20:23]
	v_mfma_f32_16x16x32_bf16 v[16:19], v[178:181], v[202:205], v[16:19]
	v_mfma_f32_16x16x32_bf16 v[4:7], v[170:173], v[232:235], v[4:7]
	v_mfma_f32_16x16x32_bf16 v[0:3], v[178:181], v[232:235], v[0:3]
	v_mfma_f32_16x16x32_bf16 v[52:55], v[174:177], v[190:193], v[52:55]
	v_mfma_f32_16x16x32_bf16 v[48:51], v[182:185], v[190:193], v[48:51]
	v_mfma_f32_16x16x32_bf16 v[36:39], v[174:177], v[198:201], v[36:39]
	v_mfma_f32_16x16x32_bf16 v[32:35], v[182:185], v[198:201], v[32:35]
	v_mfma_f32_16x16x32_bf16 v[20:23], v[174:177], v[228:231], v[20:23]
	v_mfma_f32_16x16x32_bf16 v[16:19], v[182:185], v[228:231], v[16:19]
	v_mfma_f32_16x16x32_bf16 v[4:7], v[174:177], v[236:239], v[4:7]
	v_mfma_f32_16x16x32_bf16 v[0:3], v[182:185], v[236:239], v[0:3]
	s_barrier
	s_add_i32 s47, 0, 0x18000
	s_add_i32 s48, 0, 0x1c000
	v_add_u32_e32 v156, s47, v145
	v_add_u32_e32 v182, s48, v145
	ds_read_b128 v[138:141], v156
	ds_read_b128 v[148:151], v156 offset:1024
	ds_read_b128 v[152:155], v156 offset:2048
	ds_read_b128 v[156:159], v156 offset:3072
	ds_read_b128 v[170:173], v182
	ds_read_b128 v[174:177], v182 offset:1024
	ds_read_b128 v[178:181], v182 offset:2048
	ds_read_b128 v[182:185], v182 offset:3072
	s_add_u32 s26, s26, 0x20000
	s_addc_u32 s27, s27, 0
	s_mov_b32 m0, s35
	v_lshl_add_u64 v[240:241], s[26:27], 0, v[132:133]
	ds_read_b128 v[186:189], v147 offset:32768
	ds_read_b128 v[190:193], v147 offset:33792
	ds_read_b128 v[194:197], v147 offset:34816
	ds_read_b128 v[198:201], v147 offset:35840
	ds_read_b128 v[202:205], v147 offset:36864
	ds_read_b128 v[228:231], v147 offset:37888
	ds_read_b128 v[232:235], v147 offset:38912
	ds_read_b128 v[236:239], v147 offset:39936
	global_load_lds_dwordx4 v[240:241], off
	v_lshl_add_u64 v[240:241], s[26:27], 0, v[130:131]
	s_mov_b32 m0, s36
	s_nop 0
	global_load_lds_dwordx4 v[240:241], off
	s_waitcnt vmcnt(8)
	s_waitcnt lgkmcnt(0)
	s_barrier
	s_waitcnt lgkmcnt(0)
	v_mfma_f32_16x16x32_bf16 v[124:127], v[138:141], v[186:189], v[124:127]
	v_mfma_f32_16x16x32_bf16 v[120:123], v[152:155], v[186:189], v[120:123]
	v_mfma_f32_16x16x32_bf16 v[108:111], v[138:141], v[194:197], v[108:111]
	v_mfma_f32_16x16x32_bf16 v[104:107], v[152:155], v[194:197], v[104:107]
	v_mfma_f32_16x16x32_bf16 v[92:95], v[138:141], v[202:205], v[92:95]
	v_mfma_f32_16x16x32_bf16 v[88:91], v[152:155], v[202:205], v[88:91]
	v_mfma_f32_16x16x32_bf16 v[76:79], v[138:141], v[232:235], v[76:79]
	v_mfma_f32_16x16x32_bf16 v[72:75], v[152:155], v[232:235], v[72:75]
	v_mfma_f32_16x16x32_bf16 v[124:127], v[148:151], v[190:193], v[124:127]
	v_mfma_f32_16x16x32_bf16 v[120:123], v[156:159], v[190:193], v[120:123]
	v_mfma_f32_16x16x32_bf16 v[108:111], v[148:151], v[198:201], v[108:111]
	v_mfma_f32_16x16x32_bf16 v[104:107], v[156:159], v[198:201], v[104:107]
	v_mfma_f32_16x16x32_bf16 v[92:95], v[148:151], v[228:231], v[92:95]
	v_mfma_f32_16x16x32_bf16 v[88:91], v[156:159], v[228:231], v[88:91]
	v_mfma_f32_16x16x32_bf16 v[76:79], v[148:151], v[236:239], v[76:79]
	v_mfma_f32_16x16x32_bf16 v[72:75], v[156:159], v[236:239], v[72:75]
	v_mfma_f32_16x16x32_bf16 v[116:119], v[170:173], v[186:189], v[116:119]
	v_mfma_f32_16x16x32_bf16 v[112:115], v[178:181], v[186:189], v[112:115]
	v_mfma_f32_16x16x32_bf16 v[100:103], v[170:173], v[194:197], v[100:103]
	v_mfma_f32_16x16x32_bf16 v[96:99], v[178:181], v[194:197], v[96:99]
	v_mfma_f32_16x16x32_bf16 v[84:87], v[170:173], v[202:205], v[84:87]
	v_mfma_f32_16x16x32_bf16 v[80:83], v[178:181], v[202:205], v[80:83]
	v_mfma_f32_16x16x32_bf16 v[68:71], v[170:173], v[232:235], v[68:71]
	v_mfma_f32_16x16x32_bf16 v[64:67], v[178:181], v[232:235], v[64:67]
	v_mfma_f32_16x16x32_bf16 v[116:119], v[174:177], v[190:193], v[116:119]
	v_mfma_f32_16x16x32_bf16 v[112:115], v[182:185], v[190:193], v[112:115]
	v_mfma_f32_16x16x32_bf16 v[100:103], v[174:177], v[198:201], v[100:103]
	v_mfma_f32_16x16x32_bf16 v[96:99], v[182:185], v[198:201], v[96:99]
	v_mfma_f32_16x16x32_bf16 v[84:87], v[174:177], v[228:231], v[84:87]
	v_mfma_f32_16x16x32_bf16 v[80:83], v[182:185], v[228:231], v[80:83]
	v_mfma_f32_16x16x32_bf16 v[68:71], v[174:177], v[236:239], v[68:71]
	v_mfma_f32_16x16x32_bf16 v[64:67], v[182:185], v[236:239], v[64:67]
	s_barrier
	s_add_i32 s26, s47, s77
	v_lshl_add_u64 v[142:143], v[142:143], 0, s[96:97]
	s_mov_b32 m0, s26
	ds_read_b128 v[186:189], v147 offset:49152
	ds_read_b128 v[190:193], v147 offset:50176
	ds_read_b128 v[194:197], v147 offset:51200
	ds_read_b128 v[198:201], v147 offset:52224
	ds_read_b128 v[202:205], v147 offset:53248
	ds_read_b128 v[228:231], v147 offset:54272
	ds_read_b128 v[232:235], v147 offset:55296
	ds_read_b128 v[236:239], v147 offset:56320
	global_load_lds_dwordx4 v[142:143], off
	s_add_i32 m0, s26, 0x2000
	s_add_u32 s24, s24, 0x20080
	v_lshl_add_u64 v[142:143], v[166:167], 0, s[96:97]
	s_addc_u32 s25, s25, 0
	s_add_i32 s26, s48, s77
	global_load_lds_dwordx4 v[142:143], off
	v_lshl_add_u64 v[142:143], s[24:25], 0, v[160:161]
	s_mov_b32 m0, s26
	s_nop 0
	global_load_lds_dwordx4 v[142:143], off
	v_lshl_add_u64 v[142:143], s[24:25], 0, v[128:129]
	s_add_i32 m0, s26, 0x2000
	s_nop 0
	global_load_lds_dwordx4 v[142:143], off
	v_lshl_add_u64 v[142:143], v[168:169], 0, s[96:97]
	s_mov_b32 m0, s37
	s_nop 0
	global_load_lds_dwordx4 v[142:143], off
	v_lshl_add_u64 v[142:143], v[206:207], 0, s[96:97]
	s_mov_b32 m0, s38
	s_nop 0
	global_load_lds_dwordx4 v[142:143], off
	s_waitcnt vmcnt(8)
	s_waitcnt lgkmcnt(0)
	s_barrier
	s_waitcnt lgkmcnt(0)
	v_mfma_f32_16x16x32_bf16 v[60:63], v[138:141], v[186:189], v[60:63]
	v_mfma_f32_16x16x32_bf16 v[56:59], v[152:155], v[186:189], v[56:59]
	v_mfma_f32_16x16x32_bf16 v[44:47], v[138:141], v[194:197], v[44:47]
	v_mfma_f32_16x16x32_bf16 v[40:43], v[152:155], v[194:197], v[40:43]
	v_mfma_f32_16x16x32_bf16 v[28:31], v[138:141], v[202:205], v[28:31]
	v_mfma_f32_16x16x32_bf16 v[24:27], v[152:155], v[202:205], v[24:27]
	v_mfma_f32_16x16x32_bf16 v[12:15], v[138:141], v[232:235], v[12:15]
	v_mfma_f32_16x16x32_bf16 v[8:11], v[152:155], v[232:235], v[8:11]
	v_mfma_f32_16x16x32_bf16 v[60:63], v[148:151], v[190:193], v[60:63]
	v_mfma_f32_16x16x32_bf16 v[56:59], v[156:159], v[190:193], v[56:59]
	v_mfma_f32_16x16x32_bf16 v[44:47], v[148:151], v[198:201], v[44:47]
	v_mfma_f32_16x16x32_bf16 v[40:43], v[156:159], v[198:201], v[40:43]
	v_mfma_f32_16x16x32_bf16 v[28:31], v[148:151], v[228:231], v[28:31]
	v_mfma_f32_16x16x32_bf16 v[24:27], v[156:159], v[228:231], v[24:27]
	v_mfma_f32_16x16x32_bf16 v[12:15], v[148:151], v[236:239], v[12:15]
	v_mfma_f32_16x16x32_bf16 v[8:11], v[156:159], v[236:239], v[8:11]
	v_mfma_f32_16x16x32_bf16 v[52:55], v[170:173], v[186:189], v[52:55]
	v_mfma_f32_16x16x32_bf16 v[48:51], v[178:181], v[186:189], v[48:51]
	v_mfma_f32_16x16x32_bf16 v[36:39], v[170:173], v[194:197], v[36:39]
	v_mfma_f32_16x16x32_bf16 v[32:35], v[178:181], v[194:197], v[32:35]
	v_mfma_f32_16x16x32_bf16 v[20:23], v[170:173], v[202:205], v[20:23]
	v_mfma_f32_16x16x32_bf16 v[16:19], v[178:181], v[202:205], v[16:19]
	v_mfma_f32_16x16x32_bf16 v[4:7], v[170:173], v[232:235], v[4:7]
	v_mfma_f32_16x16x32_bf16 v[0:3], v[178:181], v[232:235], v[0:3]
	v_mfma_f32_16x16x32_bf16 v[52:55], v[174:177], v[190:193], v[52:55]
	v_mfma_f32_16x16x32_bf16 v[48:51], v[182:185], v[190:193], v[48:51]
	v_mfma_f32_16x16x32_bf16 v[36:39], v[174:177], v[198:201], v[36:39]
	v_mfma_f32_16x16x32_bf16 v[32:35], v[182:185], v[198:201], v[32:35]
	v_mfma_f32_16x16x32_bf16 v[20:23], v[174:177], v[228:231], v[20:23]
	v_mfma_f32_16x16x32_bf16 v[16:19], v[182:185], v[228:231], v[16:19]
	v_mfma_f32_16x16x32_bf16 v[4:7], v[174:177], v[236:239], v[4:7]
	v_mfma_f32_16x16x32_bf16 v[0:3], v[182:185], v[236:239], v[0:3]
	s_barrier
	s_add_i32 s46, s46, 2
	s_add_u32 s44, s44, 0x100
	s_addc_u32 s45, s45, 0
	s_add_u32 s22, s22, 0x100
	s_addc_u32 s23, s23, 0
	s_cmp_gt_u32 s46, 5
	s_cbranch_scc0 .LBB0_127
	s_setprio 0
	v_readlane_b32 s22, v253, 23
	v_readlane_b32 s23, v253, 24
	s_and_b64 vcc, exec, s[22:23]
	s_cbranch_vccz .LBB0_130
	s_barrier

.LBB0_146:
	s_ashr_i32 s17, s16, 31
	s_lshl_b64 s[18:19], s[16:17], 18
	s_add_u32 s18, s28, s18
	s_addc_u32 s19, s29, s19
	s_and_b64 s[20:21], s[8:9], exec
	s_cselect_b32 s17, s19, s25
	s_cselect_b32 s42, s18, s24
	s_ashr_i32 s15, s14, 31
	s_lshl_b64 s[20:21], s[14:15], 18
	s_add_u32 s20, s30, s20
	s_addc_u32 s21, s31, s21
	s_and_b64 s[26:27], s[8:9], exec
	s_cselect_b32 s15, s21, s23
	s_cselect_b32 s43, s20, s22
	s_add_u32 s44, s22, 0x100
	s_addc_u32 s45, s23, 0
	s_add_u32 s22, s24, 0x20080
	v_mov_b32_e32 v0, 0
	s_addc_u32 s23, s25, 0
	s_mov_b32 s46, -2
	v_mov_b32_e32 v1, v0
	v_mov_b32_e32 v2, v0
	v_mov_b32_e32 v3, v0
	v_mov_b32_e32 v4, v0
	v_mov_b32_e32 v5, v0
	v_mov_b32_e32 v6, v0
	v_mov_b32_e32 v7, v0
	v_mov_b32_e32 v16, v0
	v_mov_b32_e32 v17, v0
	v_mov_b32_e32 v18, v0
	v_mov_b32_e32 v19, v0
	v_mov_b32_e32 v20, v0
	v_mov_b32_e32 v21, v0
	v_mov_b32_e32 v22, v0
	v_mov_b32_e32 v23, v0
	v_mov_b32_e32 v32, v0
	v_mov_b32_e32 v33, v0
	v_mov_b32_e32 v34, v0
	v_mov_b32_e32 v35, v0
	v_mov_b32_e32 v36, v0
	v_mov_b32_e32 v37, v0
	v_mov_b32_e32 v38, v0
	v_mov_b32_e32 v39, v0
	v_mov_b32_e32 v48, v0
	v_mov_b32_e32 v49, v0
	v_mov_b32_e32 v50, v0
	v_mov_b32_e32 v51, v0
	v_mov_b32_e32 v52, v0
	v_mov_b32_e32 v53, v0
	v_mov_b32_e32 v54, v0
	v_mov_b32_e32 v55, v0
	v_mov_b32_e32 v8, v0
	v_mov_b32_e32 v9, v0
	v_mov_b32_e32 v10, v0
	v_mov_b32_e32 v11, v0
	v_mov_b32_e32 v12, v0
	v_mov_b32_e32 v13, v0
	v_mov_b32_e32 v14, v0
	v_mov_b32_e32 v15, v0
	v_mov_b32_e32 v24, v0
	v_mov_b32_e32 v25, v0
	v_mov_b32_e32 v26, v0
	v_mov_b32_e32 v27, v0
	v_mov_b32_e32 v28, v0
	v_mov_b32_e32 v29, v0
	v_mov_b32_e32 v30, v0
	v_mov_b32_e32 v31, v0
	v_mov_b32_e32 v40, v0
	v_mov_b32_e32 v41, v0
	v_mov_b32_e32 v42, v0
	v_mov_b32_e32 v43, v0
	v_mov_b32_e32 v44, v0
	v_mov_b32_e32 v45, v0
	v_mov_b32_e32 v46, v0
	v_mov_b32_e32 v47, v0
	v_mov_b32_e32 v56, v0
	v_mov_b32_e32 v57, v0
	v_mov_b32_e32 v58, v0
	v_mov_b32_e32 v59, v0
	v_mov_b32_e32 v60, v0
	v_mov_b32_e32 v61, v0
	v_mov_b32_e32 v62, v0
	v_mov_b32_e32 v63, v0
	v_mov_b32_e32 v64, v0
	v_mov_b32_e32 v65, v0
	v_mov_b32_e32 v66, v0
	v_mov_b32_e32 v67, v0
	v_mov_b32_e32 v68, v0
	v_mov_b32_e32 v69, v0
	v_mov_b32_e32 v70, v0
	v_mov_b32_e32 v71, v0
	v_mov_b32_e32 v80, v0
	v_mov_b32_e32 v81, v0
	v_mov_b32_e32 v82, v0
	v_mov_b32_e32 v83, v0
	v_mov_b32_e32 v84, v0
	v_mov_b32_e32 v85, v0
	v_mov_b32_e32 v86, v0
	v_mov_b32_e32 v87, v0
	v_mov_b32_e32 v96, v0
	v_mov_b32_e32 v97, v0
	v_mov_b32_e32 v98, v0
	v_mov_b32_e32 v99, v0
	v_mov_b32_e32 v100, v0
	v_mov_b32_e32 v101, v0
	v_mov_b32_e32 v102, v0
	v_mov_b32_e32 v103, v0
	v_mov_b32_e32 v112, v0
	v_mov_b32_e32 v113, v0
	v_mov_b32_e32 v114, v0
	v_mov_b32_e32 v115, v0
	v_mov_b32_e32 v116, v0
	v_mov_b32_e32 v117, v0
	v_mov_b32_e32 v118, v0
	v_mov_b32_e32 v119, v0
	v_mov_b32_e32 v72, v0
	v_mov_b32_e32 v73, v0
	v_mov_b32_e32 v74, v0
	v_mov_b32_e32 v75, v0
	v_mov_b32_e32 v76, v0
	v_mov_b32_e32 v77, v0
	v_mov_b32_e32 v78, v0
	v_mov_b32_e32 v79, v0
	v_mov_b32_e32 v88, v0
	v_mov_b32_e32 v89, v0
	v_mov_b32_e32 v90, v0
	v_mov_b32_e32 v91, v0
	v_mov_b32_e32 v92, v0
	v_mov_b32_e32 v93, v0
	v_mov_b32_e32 v94, v0
	v_mov_b32_e32 v95, v0
	v_mov_b32_e32 v104, v0
	v_mov_b32_e32 v105, v0
	v_mov_b32_e32 v106, v0
	v_mov_b32_e32 v107, v0
	v_mov_b32_e32 v108, v0
	v_mov_b32_e32 v109, v0
	v_mov_b32_e32 v110, v0
	v_mov_b32_e32 v111, v0
	v_mov_b32_e32 v120, v0
	v_mov_b32_e32 v121, v0
	v_mov_b32_e32 v122, v0
	v_mov_b32_e32 v123, v0
	v_mov_b32_e32 v124, v0
	v_mov_b32_e32 v125, v0
	v_mov_b32_e32 v126, v0
	v_mov_b32_e32 v127, v0
	v_readlane_b32 s100, v252, 21
	s_sub_u32 s100, s100, 0
	s_cmp_lt_u32 s100, 4
	s_cbranch_scc0 .Lprio_3
	s_setprio 1
.Lprio_3:
.LBB0_147:
	s_add_u32 s24, s22, 0xfffe0080
	s_addc_u32 s25, s23, -1
	s_add_i32 s47, 0, 0x10000
	s_cmp_eq_u32 s46, 4
	s_cselect_b32 s27, s17, s25
	s_cselect_b32 s26, s42, s24
	v_add_u32_e32 v142, s47, v145
	s_cselect_b32 s25, s15, s45
	s_cselect_b32 s24, s43, s44
	s_add_i32 s50, 0, 0x14000
	ds_read_b128 v[138:141], v142
	ds_read_b128 v[148:151], v142 offset:1024
	ds_read_b128 v[152:155], v142 offset:2048
	ds_read_b128 v[156:159], v142 offset:3072
	v_add_u32_e32 v142, s50, v145
	ds_read_b128 v[170:173], v142
	ds_read_b128 v[174:177], v142 offset:1024
	ds_read_b128 v[178:181], v142 offset:2048
	ds_read_b128 v[182:185], v142 offset:3072
	v_lshl_add_u64 v[142:143], s[22:23], 0, v[136:137]
	s_add_i32 m0, s34, 0xc000
	ds_read_b128 v[186:189], v147
	ds_read_b128 v[190:193], v147 offset:1024
	ds_read_b128 v[194:197], v147 offset:2048
	ds_read_b128 v[198:201], v147 offset:3072
	ds_read_b128 v[202:205], v147 offset:4096
	ds_read_b128 v[228:231], v147 offset:5120
	ds_read_b128 v[232:235], v147 offset:6144
	ds_read_b128 v[236:239], v147 offset:7168
	global_load_lds_dwordx4 v[142:143], off
	v_lshl_add_u64 v[142:143], s[22:23], 0, v[134:135]
	s_add_i32 m0, s34, 0xe000
	s_nop 0
	global_load_lds_dwordx4 v[142:143], off
	s_waitcnt vmcnt(8)
	s_waitcnt lgkmcnt(0)
	s_barrier
	s_waitcnt lgkmcnt(0)
	v_mfma_f32_16x16x32_bf16 v[124:127], v[138:141], v[186:189], v[124:127]
	v_mfma_f32_16x16x32_bf16 v[120:123], v[152:155], v[186:189], v[120:123]
	v_mfma_f32_16x16x32_bf16 v[108:111], v[138:141], v[194:197], v[108:111]
	v_mfma_f32_16x16x32_bf16 v[104:107], v[152:155], v[194:197], v[104:107]
	v_mfma_f32_16x16x32_bf16 v[92:95], v[138:141], v[202:205], v[92:95]
	v_mfma_f32_16x16x32_bf16 v[88:91], v[152:155], v[202:205], v[88:91]
	v_mfma_f32_16x16x32_bf16 v[76:79], v[138:141], v[232:235], v[76:79]
	v_mfma_f32_16x16x32_bf16 v[72:75], v[152:155], v[232:235], v[72:75]
	v_mfma_f32_16x16x32_bf16 v[124:127], v[148:151], v[190:193], v[124:127]
	v_mfma_f32_16x16x32_bf16 v[120:123], v[156:159], v[190:193], v[120:123]
	v_mfma_f32_16x16x32_bf16 v[108:111], v[148:151], v[198:201], v[108:111]
	v_mfma_f32_16x16x32_bf16 v[104:107], v[156:159], v[198:201], v[104:107]
	v_mfma_f32_16x16x32_bf16 v[92:95], v[148:151], v[228:231], v[92:95]
	v_mfma_f32_16x16x32_bf16 v[88:91], v[156:159], v[228:231], v[88:91]
	v_mfma_f32_16x16x32_bf16 v[76:79], v[148:151], v[236:239], v[76:79]
	v_mfma_f32_16x16x32_bf16 v[72:75], v[156:159], v[236:239], v[72:75]
	v_mfma_f32_16x16x32_bf16 v[116:119], v[170:173], v[186:189], v[116:119]
	v_mfma_f32_16x16x32_bf16 v[112:115], v[178:181], v[186:189], v[112:115]
	v_mfma_f32_16x16x32_bf16 v[100:103], v[170:173], v[194:197], v[100:103]
	v_mfma_f32_16x16x32_bf16 v[96:99], v[178:181], v[194:197], v[96:99]
	v_mfma_f32_16x16x32_bf16 v[84:87], v[170:173], v[202:205], v[84:87]
	v_mfma_f32_16x16x32_bf16 v[80:83], v[178:181], v[202:205], v[80:83]
	v_mfma_f32_16x16x32_bf16 v[68:71], v[170:173], v[232:235], v[68:71]
	v_mfma_f32_16x16x32_bf16 v[64:67], v[178:181], v[232:235], v[64:67]
	v_mfma_f32_16x16x32_bf16 v[116:119], v[174:177], v[190:193], v[116:119]
	v_mfma_f32_16x16x32_bf16 v[112:115], v[182:185], v[190:193], v[112:115]
	v_mfma_f32_16x16x32_bf16 v[100:103], v[174:177], v[198:201], v[100:103]
	v_mfma_f32_16x16x32_bf16 v[96:99], v[182:185], v[198:201], v[96:99]
	v_mfma_f32_16x16x32_bf16 v[84:87], v[174:177], v[228:231], v[84:87]
	v_mfma_f32_16x16x32_bf16 v[80:83], v[182:185], v[228:231], v[80:83]
	v_mfma_f32_16x16x32_bf16 v[68:71], v[174:177], v[236:239], v[68:71]
	v_mfma_f32_16x16x32_bf16 v[64:67], v[182:185], v[236:239], v[64:67]
	s_barrier
	s_add_i32 s47, s47, s77
	v_lshl_add_u64 v[142:143], s[24:25], 0, v[160:161]
	s_mov_b32 m0, s47
	ds_read_b128 v[186:189], v147 offset:16384
	ds_read_b128 v[190:193], v147 offset:17408
	ds_read_b128 v[194:197], v147 offset:18432
	ds_read_b128 v[198:201], v147 offset:19456
	ds_read_b128 v[202:205], v147 offset:20480
	ds_read_b128 v[228:231], v147 offset:21504
	ds_read_b128 v[232:235], v147 offset:22528
	ds_read_b128 v[236:239], v147 offset:23552
	global_load_lds_dwordx4 v[142:143], off
	s_add_i32 m0, s47, 0x2000
	s_add_u32 s48, s24, 0x20000
	v_lshl_add_u64 v[166:167], s[24:25], 0, v[128:129]
	s_addc_u32 s49, s25, 0
	s_add_i32 s47, s50, s77
	global_load_lds_dwordx4 v[166:167], off
	v_lshl_add_u64 v[168:169], s[48:49], 0, v[160:161]
	s_mov_b32 m0, s47
	v_lshl_add_u64 v[206:207], s[26:27], 0, v[130:131]
	global_load_lds_dwordx4 v[168:169], off
	v_lshl_add_u64 v[168:169], s[48:49], 0, v[128:129]
	s_add_i32 m0, s47, 0x2000
	s_nop 0
	global_load_lds_dwordx4 v[168:169], off
	v_lshl_add_u64 v[168:169], s[26:27], 0, v[132:133]
	s_mov_b32 m0, s34
	s_nop 0
	global_load_lds_dwordx4 v[168:169], off
	s_mov_b32 m0, s35
	s_nop 0
	global_load_lds_dwordx4 v[206:207], off
	s_waitcnt vmcnt(8)
	s_waitcnt lgkmcnt(0)
	s_barrier
	s_waitcnt lgkmcnt(0)
	v_mfma_f32_16x16x32_bf16 v[60:63], v[138:141], v[186:189], v[60:63]
	v_mfma_f32_16x16x32_bf16 v[56:59], v[152:155], v[186:189], v[56:59]
	v_mfma_f32_16x16x32_bf16 v[44:47], v[138:141], v[194:197], v[44:47]
	v_mfma_f32_16x16x32_bf16 v[40:43], v[152:155], v[194:197], v[40:43]
	v_mfma_f32_16x16x32_bf16 v[28:31], v[138:141], v[202:205], v[28:31]
	v_mfma_f32_16x16x32_bf16 v[24:27], v[152:155], v[202:205], v[24:27]
	v_mfma_f32_16x16x32_bf16 v[12:15], v[138:141], v[232:235], v[12:15]
	v_mfma_f32_16x16x32_bf16 v[8:11], v[152:155], v[232:235], v[8:11]
	v_mfma_f32_16x16x32_bf16 v[60:63], v[148:151], v[190:193], v[60:63]
	v_mfma_f32_16x16x32_bf16 v[56:59], v[156:159], v[190:193], v[56:59]
	v_mfma_f32_16x16x32_bf16 v[44:47], v[148:151], v[198:201], v[44:47]
	v_mfma_f32_16x16x32_bf16 v[40:43], v[156:159], v[198:201], v[40:43]
	v_mfma_f32_16x16x32_bf16 v[28:31], v[148:151], v[228:231], v[28:31]
	v_mfma_f32_16x16x32_bf16 v[24:27], v[156:159], v[228:231], v[24:27]
	v_mfma_f32_16x16x32_bf16 v[12:15], v[148:151], v[236:239], v[12:15]
	v_mfma_f32_16x16x32_bf16 v[8:11], v[156:159], v[236:239], v[8:11]
	v_mfma_f32_16x16x32_bf16 v[52:55], v[170:173], v[186:189], v[52:55]
	v_mfma_f32_16x16x32_bf16 v[48:51], v[178:181], v[186:189], v[48:51]
	v_mfma_f32_16x16x32_bf16 v[36:39], v[170:173], v[194:197], v[36:39]
	v_mfma_f32_16x16x32_bf16 v[32:35], v[178:181], v[194:197], v[32:35]
	v_mfma_f32_16x16x32_bf16 v[20:23], v[170:173], v[202:205], v[20:23]
	v_mfma_f32_16x16x32_bf16 v[16:19], v[178:181], v[202:205], v[16:19]
	v_mfma_f32_16x16x32_bf16 v[4:7], v[170:173], v[232:235], v[4:7]
	v_mfma_f32_16x16x32_bf16 v[0:3], v[178:181], v[232:235], v[0:3]
	v_mfma_f32_16x16x32_bf16 v[52:55], v[174:177], v[190:193], v[52:55]
	v_mfma_f32_16x16x32_bf16 v[48:51], v[182:185], v[190:193], v[48:51]
	v_mfma_f32_16x16x32_bf16 v[36:39], v[174:177], v[198:201], v[36:39]
	v_mfma_f32_16x16x32_bf16 v[32:35], v[182:185], v[198:201], v[32:35]
	v_mfma_f32_16x16x32_bf16 v[20:23], v[174:177], v[228:231], v[20:23]
	v_mfma_f32_16x16x32_bf16 v[16:19], v[182:185], v[228:231], v[16:19]
	v_mfma_f32_16x16x32_bf16 v[4:7], v[174:177], v[236:239], v[4:7]
	v_mfma_f32_16x16x32_bf16 v[0:3], v[182:185], v[236:239], v[0:3]
	s_barrier
	s_add_i32 s47, 0, 0x18000
	s_add_i32 s48, 0, 0x1c000
	v_add_u32_e32 v156, s47, v145
	v_add_u32_e32 v182, s48, v145
	ds_read_b128 v[138:141], v156
	ds_read_b128 v[148:151], v156 offset:1024
	ds_read_b128 v[152:155], v156 offset:2048
	ds_read_b128 v[156:159], v156 offset:3072
	ds_read_b128 v[170:173], v182
	ds_read_b128 v[174:177], v182 offset:1024
	ds_read_b128 v[178:181], v182 offset:2048
	ds_read_b128 v[182:185], v182 offset:3072
	s_add_u32 s26, s26, 0x20000
	s_addc_u32 s27, s27, 0
	s_mov_b32 m0, s36
	v_lshl_add_u64 v[240:241], s[26:27], 0, v[132:133]
	ds_read_b128 v[186:189], v147 offset:32768
	ds_read_b128 v[190:193], v147 offset:33792
	ds_read_b128 v[194:197], v147 offset:34816
	ds_read_b128 v[198:201], v147 offset:35840
	ds_read_b128 v[202:205], v147 offset:36864
	ds_read_b128 v[228:231], v147 offset:37888
	ds_read_b128 v[232:235], v147 offset:38912
	ds_read_b128 v[236:239], v147 offset:39936
	global_load_lds_dwordx4 v[240:241], off
	v_lshl_add_u64 v[240:241], s[26:27], 0, v[130:131]
	s_mov_b32 m0, s37
	s_nop 0
	global_load_lds_dwordx4 v[240:241], off
	s_waitcnt vmcnt(8)
	s_waitcnt lgkmcnt(0)
	s_barrier
	s_waitcnt lgkmcnt(0)
	v_mfma_f32_16x16x32_bf16 v[124:127], v[138:141], v[186:189], v[124:127]
	v_mfma_f32_16x16x32_bf16 v[120:123], v[152:155], v[186:189], v[120:123]
	v_mfma_f32_16x16x32_bf16 v[108:111], v[138:141], v[194:197], v[108:111]
	v_mfma_f32_16x16x32_bf16 v[104:107], v[152:155], v[194:197], v[104:107]
	v_mfma_f32_16x16x32_bf16 v[92:95], v[138:141], v[202:205], v[92:95]
	v_mfma_f32_16x16x32_bf16 v[88:91], v[152:155], v[202:205], v[88:91]
	v_mfma_f32_16x16x32_bf16 v[76:79], v[138:141], v[232:235], v[76:79]
	v_mfma_f32_16x16x32_bf16 v[72:75], v[152:155], v[232:235], v[72:75]
	v_mfma_f32_16x16x32_bf16 v[124:127], v[148:151], v[190:193], v[124:127]
	v_mfma_f32_16x16x32_bf16 v[120:123], v[156:159], v[190:193], v[120:123]
	v_mfma_f32_16x16x32_bf16 v[108:111], v[148:151], v[198:201], v[108:111]
	v_mfma_f32_16x16x32_bf16 v[104:107], v[156:159], v[198:201], v[104:107]
	v_mfma_f32_16x16x32_bf16 v[92:95], v[148:151], v[228:231], v[92:95]
	v_mfma_f32_16x16x32_bf16 v[88:91], v[156:159], v[228:231], v[88:91]
	v_mfma_f32_16x16x32_bf16 v[76:79], v[148:151], v[236:239], v[76:79]
	v_mfma_f32_16x16x32_bf16 v[72:75], v[156:159], v[236:239], v[72:75]
	v_mfma_f32_16x16x32_bf16 v[116:119], v[170:173], v[186:189], v[116:119]
	v_mfma_f32_16x16x32_bf16 v[112:115], v[178:181], v[186:189], v[112:115]
	v_mfma_f32_16x16x32_bf16 v[100:103], v[170:173], v[194:197], v[100:103]
	v_mfma_f32_16x16x32_bf16 v[96:99], v[178:181], v[194:197], v[96:99]
	v_mfma_f32_16x16x32_bf16 v[84:87], v[170:173], v[202:205], v[84:87]
	v_mfma_f32_16x16x32_bf16 v[80:83], v[178:181], v[202:205], v[80:83]
	v_mfma_f32_16x16x32_bf16 v[68:71], v[170:173], v[232:235], v[68:71]
	v_mfma_f32_16x16x32_bf16 v[64:67], v[178:181], v[232:235], v[64:67]
	v_mfma_f32_16x16x32_bf16 v[116:119], v[174:177], v[190:193], v[116:119]
	v_mfma_f32_16x16x32_bf16 v[112:115], v[182:185], v[190:193], v[112:115]
	v_mfma_f32_16x16x32_bf16 v[100:103], v[174:177], v[198:201], v[100:103]
	v_mfma_f32_16x16x32_bf16 v[96:99], v[182:185], v[198:201], v[96:99]
	v_mfma_f32_16x16x32_bf16 v[84:87], v[174:177], v[228:231], v[84:87]
	v_mfma_f32_16x16x32_bf16 v[80:83], v[182:185], v[228:231], v[80:83]
	v_mfma_f32_16x16x32_bf16 v[68:71], v[174:177], v[236:239], v[68:71]
	v_mfma_f32_16x16x32_bf16 v[64:67], v[182:185], v[236:239], v[64:67]
	s_barrier
	s_add_i32 s26, s47, s77
	v_lshl_add_u64 v[142:143], v[142:143], 0, s[96:97]
	s_mov_b32 m0, s26
	ds_read_b128 v[186:189], v147 offset:49152
	ds_read_b128 v[190:193], v147 offset:50176
	ds_read_b128 v[194:197], v147 offset:51200
	ds_read_b128 v[198:201], v147 offset:52224
	ds_read_b128 v[202:205], v147 offset:53248
	ds_read_b128 v[228:231], v147 offset:54272
	ds_read_b128 v[232:235], v147 offset:55296
	ds_read_b128 v[236:239], v147 offset:56320
	global_load_lds_dwordx4 v[142:143], off
	s_add_i32 m0, s26, 0x2000
	s_add_u32 s24, s24, 0x20080
	v_lshl_add_u64 v[142:143], v[166:167], 0, s[96:97]
	s_addc_u32 s25, s25, 0
	s_add_i32 s26, s48, s77
	global_load_lds_dwordx4 v[142:143], off
	v_lshl_add_u64 v[142:143], s[24:25], 0, v[160:161]
	s_mov_b32 m0, s26
	s_nop 0
	global_load_lds_dwordx4 v[142:143], off
	v_lshl_add_u64 v[142:143], s[24:25], 0, v[128:129]
	s_add_i32 m0, s26, 0x2000
	s_nop 0
	global_load_lds_dwordx4 v[142:143], off
	v_lshl_add_u64 v[142:143], v[168:169], 0, s[96:97]
	s_mov_b32 m0, s38
	s_nop 0
	global_load_lds_dwordx4 v[142:143], off
	v_lshl_add_u64 v[142:143], v[206:207], 0, s[96:97]
	s_mov_b32 m0, s39
	s_nop 0
	global_load_lds_dwordx4 v[142:143], off
	s_waitcnt vmcnt(8)
	s_waitcnt lgkmcnt(0)
	s_barrier
	s_waitcnt lgkmcnt(0)
	v_mfma_f32_16x16x32_bf16 v[60:63], v[138:141], v[186:189], v[60:63]
	v_mfma_f32_16x16x32_bf16 v[56:59], v[152:155], v[186:189], v[56:59]
	v_mfma_f32_16x16x32_bf16 v[44:47], v[138:141], v[194:197], v[44:47]
	v_mfma_f32_16x16x32_bf16 v[40:43], v[152:155], v[194:197], v[40:43]
	v_mfma_f32_16x16x32_bf16 v[28:31], v[138:141], v[202:205], v[28:31]
	v_mfma_f32_16x16x32_bf16 v[24:27], v[152:155], v[202:205], v[24:27]
	v_mfma_f32_16x16x32_bf16 v[12:15], v[138:141], v[232:235], v[12:15]
	v_mfma_f32_16x16x32_bf16 v[8:11], v[152:155], v[232:235], v[8:11]
	v_mfma_f32_16x16x32_bf16 v[60:63], v[148:151], v[190:193], v[60:63]
	v_mfma_f32_16x16x32_bf16 v[56:59], v[156:159], v[190:193], v[56:59]
	v_mfma_f32_16x16x32_bf16 v[44:47], v[148:151], v[198:201], v[44:47]
	v_mfma_f32_16x16x32_bf16 v[40:43], v[156:159], v[198:201], v[40:43]
	v_mfma_f32_16x16x32_bf16 v[28:31], v[148:151], v[228:231], v[28:31]
	v_mfma_f32_16x16x32_bf16 v[24:27], v[156:159], v[228:231], v[24:27]
	v_mfma_f32_16x16x32_bf16 v[12:15], v[148:151], v[236:239], v[12:15]
	v_mfma_f32_16x16x32_bf16 v[8:11], v[156:159], v[236:239], v[8:11]
	v_mfma_f32_16x16x32_bf16 v[52:55], v[170:173], v[186:189], v[52:55]
	v_mfma_f32_16x16x32_bf16 v[48:51], v[178:181], v[186:189], v[48:51]
	v_mfma_f32_16x16x32_bf16 v[36:39], v[170:173], v[194:197], v[36:39]
	v_mfma_f32_16x16x32_bf16 v[32:35], v[178:181], v[194:197], v[32:35]
	v_mfma_f32_16x16x32_bf16 v[20:23], v[170:173], v[202:205], v[20:23]
	v_mfma_f32_16x16x32_bf16 v[16:19], v[178:181], v[202:205], v[16:19]
	v_mfma_f32_16x16x32_bf16 v[4:7], v[170:173], v[232:235], v[4:7]
	v_mfma_f32_16x16x32_bf16 v[0:3], v[178:181], v[232:235], v[0:3]
	v_mfma_f32_16x16x32_bf16 v[52:55], v[174:177], v[190:193], v[52:55]
	v_mfma_f32_16x16x32_bf16 v[48:51], v[182:185], v[190:193], v[48:51]
	v_mfma_f32_16x16x32_bf16 v[36:39], v[174:177], v[198:201], v[36:39]
	v_mfma_f32_16x16x32_bf16 v[32:35], v[182:185], v[198:201], v[32:35]
	v_mfma_f32_16x16x32_bf16 v[20:23], v[174:177], v[228:231], v[20:23]
	v_mfma_f32_16x16x32_bf16 v[16:19], v[182:185], v[228:231], v[16:19]
	v_mfma_f32_16x16x32_bf16 v[4:7], v[174:177], v[236:239], v[4:7]
	v_mfma_f32_16x16x32_bf16 v[0:3], v[182:185], v[236:239], v[0:3]
	s_barrier
	s_add_i32 s46, s46, 2
	s_add_u32 s44, s44, 0x100
	s_addc_u32 s45, s45, 0
	s_add_u32 s22, s22, 0x100
	s_addc_u32 s23, s23, 0
	s_cmp_gt_u32 s46, 5
	s_cbranch_scc0 .LBB0_147
	s_setprio 0
	v_readlane_b32 s22, v253, 23
	v_readlane_b32 s23, v253, 24
	s_and_b64 vcc, exec, s[22:23]
	s_cbranch_vccz .LBB0_150
	s_barrier

.LBB0_166:
	s_ashr_i32 s15, s14, 31
	s_lshl_b64 s[16:17], s[14:15], 18
	s_add_u32 s16, s26, s16
	s_addc_u32 s17, s27, s17
	s_and_b64 s[18:19], s[6:7], exec
	s_cselect_b32 s15, s17, s23
	s_cselect_b32 s40, s16, s22
	s_ashr_i32 s13, s12, 31
	s_lshl_b64 s[18:19], s[12:13], 18
	s_add_u32 s18, s28, s18
	s_addc_u32 s19, s29, s19
	s_and_b64 s[24:25], s[6:7], exec
	s_cselect_b32 s13, s19, s21
	s_cselect_b32 s41, s18, s20
	s_add_u32 s42, s20, 0x100
	s_addc_u32 s43, s21, 0
	s_add_u32 s20, s22, 0x20080
	v_mov_b32_e32 v0, 0
	s_addc_u32 s21, s23, 0
	s_mov_b32 s44, -2
	v_mov_b32_e32 v1, v0
	v_mov_b32_e32 v2, v0
	v_mov_b32_e32 v3, v0
	v_mov_b32_e32 v4, v0
	v_mov_b32_e32 v5, v0
	v_mov_b32_e32 v6, v0
	v_mov_b32_e32 v7, v0
	v_mov_b32_e32 v16, v0
	v_mov_b32_e32 v17, v0
	v_mov_b32_e32 v18, v0
	v_mov_b32_e32 v19, v0
	v_mov_b32_e32 v20, v0
	v_mov_b32_e32 v21, v0
	v_mov_b32_e32 v22, v0
	v_mov_b32_e32 v23, v0
	v_mov_b32_e32 v32, v0
	v_mov_b32_e32 v33, v0
	v_mov_b32_e32 v34, v0
	v_mov_b32_e32 v35, v0
	v_mov_b32_e32 v36, v0
	v_mov_b32_e32 v37, v0
	v_mov_b32_e32 v38, v0
	v_mov_b32_e32 v39, v0
	v_mov_b32_e32 v48, v0
	v_mov_b32_e32 v49, v0
	v_mov_b32_e32 v50, v0
	v_mov_b32_e32 v51, v0
	v_mov_b32_e32 v52, v0
	v_mov_b32_e32 v53, v0
	v_mov_b32_e32 v54, v0
	v_mov_b32_e32 v55, v0
	v_mov_b32_e32 v8, v0
	v_mov_b32_e32 v9, v0
	v_mov_b32_e32 v10, v0
	v_mov_b32_e32 v11, v0
	v_mov_b32_e32 v12, v0
	v_mov_b32_e32 v13, v0
	v_mov_b32_e32 v14, v0
	v_mov_b32_e32 v15, v0
	v_mov_b32_e32 v24, v0
	v_mov_b32_e32 v25, v0
	v_mov_b32_e32 v26, v0
	v_mov_b32_e32 v27, v0
	v_mov_b32_e32 v28, v0
	v_mov_b32_e32 v29, v0
	v_mov_b32_e32 v30, v0
	v_mov_b32_e32 v31, v0
	v_mov_b32_e32 v40, v0
	v_mov_b32_e32 v41, v0
	v_mov_b32_e32 v42, v0
	v_mov_b32_e32 v43, v0
	v_mov_b32_e32 v44, v0
	v_mov_b32_e32 v45, v0
	v_mov_b32_e32 v46, v0
	v_mov_b32_e32 v47, v0
	v_mov_b32_e32 v56, v0
	v_mov_b32_e32 v57, v0
	v_mov_b32_e32 v58, v0
	v_mov_b32_e32 v59, v0
	v_mov_b32_e32 v60, v0
	v_mov_b32_e32 v61, v0
	v_mov_b32_e32 v62, v0
	v_mov_b32_e32 v63, v0
	v_mov_b32_e32 v64, v0
	v_mov_b32_e32 v65, v0
	v_mov_b32_e32 v66, v0
	v_mov_b32_e32 v67, v0
	v_mov_b32_e32 v68, v0
	v_mov_b32_e32 v69, v0
	v_mov_b32_e32 v70, v0
	v_mov_b32_e32 v71, v0
	v_mov_b32_e32 v80, v0
	v_mov_b32_e32 v81, v0
	v_mov_b32_e32 v82, v0
	v_mov_b32_e32 v83, v0
	v_mov_b32_e32 v84, v0
	v_mov_b32_e32 v85, v0
	v_mov_b32_e32 v86, v0
	v_mov_b32_e32 v87, v0
	v_mov_b32_e32 v96, v0
	v_mov_b32_e32 v97, v0
	v_mov_b32_e32 v98, v0
	v_mov_b32_e32 v99, v0
	v_mov_b32_e32 v100, v0
	v_mov_b32_e32 v101, v0
	v_mov_b32_e32 v102, v0
	v_mov_b32_e32 v103, v0
	v_mov_b32_e32 v112, v0
	v_mov_b32_e32 v113, v0
	v_mov_b32_e32 v114, v0
	v_mov_b32_e32 v115, v0
	v_mov_b32_e32 v116, v0
	v_mov_b32_e32 v117, v0
	v_mov_b32_e32 v118, v0
	v_mov_b32_e32 v119, v0
	v_mov_b32_e32 v72, v0
	v_mov_b32_e32 v73, v0
	v_mov_b32_e32 v74, v0
	v_mov_b32_e32 v75, v0
	v_mov_b32_e32 v76, v0
	v_mov_b32_e32 v77, v0
	v_mov_b32_e32 v78, v0
	v_mov_b32_e32 v79, v0
	v_mov_b32_e32 v88, v0
	v_mov_b32_e32 v89, v0
	v_mov_b32_e32 v90, v0
	v_mov_b32_e32 v91, v0
	v_mov_b32_e32 v92, v0
	v_mov_b32_e32 v93, v0
	v_mov_b32_e32 v94, v0
	v_mov_b32_e32 v95, v0
	v_mov_b32_e32 v104, v0
	v_mov_b32_e32 v105, v0
	v_mov_b32_e32 v106, v0
	v_mov_b32_e32 v107, v0
	v_mov_b32_e32 v108, v0
	v_mov_b32_e32 v109, v0
	v_mov_b32_e32 v110, v0
	v_mov_b32_e32 v111, v0
	v_mov_b32_e32 v120, v0
	v_mov_b32_e32 v121, v0
	v_mov_b32_e32 v122, v0
	v_mov_b32_e32 v123, v0
	v_mov_b32_e32 v124, v0
	v_mov_b32_e32 v125, v0
	v_mov_b32_e32 v126, v0
	v_mov_b32_e32 v127, v0
	v_readlane_b32 s100, v252, 21
	s_sub_u32 s100, s100, 0
	s_cmp_lt_u32 s100, 4
	s_cbranch_scc0 .Lprio_4
	s_setprio 1
.Lprio_4:
.LBB0_167:
	s_add_u32 s22, s20, 0xfffe0080
	s_addc_u32 s23, s21, -1
	s_add_i32 s45, 0, 0x10000
	s_cmp_eq_u32 s44, 4
	s_cselect_b32 s25, s15, s23
	s_cselect_b32 s24, s40, s22
	v_add_u32_e32 v142, s45, v145
	s_cselect_b32 s23, s13, s43
	s_cselect_b32 s22, s41, s42
	s_add_i32 s48, 0, 0x14000
	ds_read_b128 v[138:141], v142
	ds_read_b128 v[148:151], v142 offset:1024
	ds_read_b128 v[152:155], v142 offset:2048
	ds_read_b128 v[156:159], v142 offset:3072
	v_add_u32_e32 v142, s48, v145
	ds_read_b128 v[170:173], v142
	ds_read_b128 v[174:177], v142 offset:1024
	ds_read_b128 v[178:181], v142 offset:2048
	ds_read_b128 v[182:185], v142 offset:3072
	v_lshl_add_u64 v[142:143], s[20:21], 0, v[136:137]
	s_add_i32 m0, s30, 0xc000
	ds_read_b128 v[186:189], v147
	ds_read_b128 v[190:193], v147 offset:1024
	ds_read_b128 v[194:197], v147 offset:2048
	ds_read_b128 v[198:201], v147 offset:3072
	ds_read_b128 v[202:205], v147 offset:4096
	ds_read_b128 v[228:231], v147 offset:5120
	ds_read_b128 v[232:235], v147 offset:6144
	ds_read_b128 v[236:239], v147 offset:7168
	global_load_lds_dwordx4 v[142:143], off
	v_lshl_add_u64 v[142:143], s[20:21], 0, v[134:135]
	s_add_i32 m0, s30, 0xe000
	s_nop 0
	global_load_lds_dwordx4 v[142:143], off
	s_waitcnt vmcnt(8)
	s_waitcnt lgkmcnt(0)
	s_barrier
	s_waitcnt lgkmcnt(0)
	v_mfma_f32_16x16x32_bf16 v[124:127], v[138:141], v[186:189], v[124:127]
	v_mfma_f32_16x16x32_bf16 v[120:123], v[152:155], v[186:189], v[120:123]
	v_mfma_f32_16x16x32_bf16 v[108:111], v[138:141], v[194:197], v[108:111]
	v_mfma_f32_16x16x32_bf16 v[104:107], v[152:155], v[194:197], v[104:107]
	v_mfma_f32_16x16x32_bf16 v[92:95], v[138:141], v[202:205], v[92:95]
	v_mfma_f32_16x16x32_bf16 v[88:91], v[152:155], v[202:205], v[88:91]
	v_mfma_f32_16x16x32_bf16 v[76:79], v[138:141], v[232:235], v[76:79]
	v_mfma_f32_16x16x32_bf16 v[72:75], v[152:155], v[232:235], v[72:75]
	v_mfma_f32_16x16x32_bf16 v[124:127], v[148:151], v[190:193], v[124:127]
	v_mfma_f32_16x16x32_bf16 v[120:123], v[156:159], v[190:193], v[120:123]
	v_mfma_f32_16x16x32_bf16 v[108:111], v[148:151], v[198:201], v[108:111]
	v_mfma_f32_16x16x32_bf16 v[104:107], v[156:159], v[198:201], v[104:107]
	v_mfma_f32_16x16x32_bf16 v[92:95], v[148:151], v[228:231], v[92:95]
	v_mfma_f32_16x16x32_bf16 v[88:91], v[156:159], v[228:231], v[88:91]
	v_mfma_f32_16x16x32_bf16 v[76:79], v[148:151], v[236:239], v[76:79]
	v_mfma_f32_16x16x32_bf16 v[72:75], v[156:159], v[236:239], v[72:75]
	v_mfma_f32_16x16x32_bf16 v[116:119], v[170:173], v[186:189], v[116:119]
	v_mfma_f32_16x16x32_bf16 v[112:115], v[178:181], v[186:189], v[112:115]
	v_mfma_f32_16x16x32_bf16 v[100:103], v[170:173], v[194:197], v[100:103]
	v_mfma_f32_16x16x32_bf16 v[96:99], v[178:181], v[194:197], v[96:99]
	v_mfma_f32_16x16x32_bf16 v[84:87], v[170:173], v[202:205], v[84:87]
	v_mfma_f32_16x16x32_bf16 v[80:83], v[178:181], v[202:205], v[80:83]
	v_mfma_f32_16x16x32_bf16 v[68:71], v[170:173], v[232:235], v[68:71]
	v_mfma_f32_16x16x32_bf16 v[64:67], v[178:181], v[232:235], v[64:67]
	v_mfma_f32_16x16x32_bf16 v[116:119], v[174:177], v[190:193], v[116:119]
	v_mfma_f32_16x16x32_bf16 v[112:115], v[182:185], v[190:193], v[112:115]
	v_mfma_f32_16x16x32_bf16 v[100:103], v[174:177], v[198:201], v[100:103]
	v_mfma_f32_16x16x32_bf16 v[96:99], v[182:185], v[198:201], v[96:99]
	v_mfma_f32_16x16x32_bf16 v[84:87], v[174:177], v[228:231], v[84:87]
	v_mfma_f32_16x16x32_bf16 v[80:83], v[182:185], v[228:231], v[80:83]
	v_mfma_f32_16x16x32_bf16 v[68:71], v[174:177], v[236:239], v[68:71]
	v_mfma_f32_16x16x32_bf16 v[64:67], v[182:185], v[236:239], v[64:67]
	s_barrier
	s_add_i32 s45, s45, s77
	v_lshl_add_u64 v[142:143], s[22:23], 0, v[160:161]
	s_mov_b32 m0, s45
	ds_read_b128 v[186:189], v147 offset:16384
	ds_read_b128 v[190:193], v147 offset:17408
	ds_read_b128 v[194:197], v147 offset:18432
	ds_read_b128 v[198:201], v147 offset:19456
	ds_read_b128 v[202:205], v147 offset:20480
	ds_read_b128 v[228:231], v147 offset:21504
	ds_read_b128 v[232:235], v147 offset:22528
	ds_read_b128 v[236:239], v147 offset:23552
	global_load_lds_dwordx4 v[142:143], off
	s_add_i32 m0, s45, 0x2000
	s_add_u32 s46, s22, 0x20000
	v_lshl_add_u64 v[166:167], s[22:23], 0, v[128:129]
	s_addc_u32 s47, s23, 0
	s_add_i32 s45, s48, s77
	global_load_lds_dwordx4 v[166:167], off
	v_lshl_add_u64 v[168:169], s[46:47], 0, v[160:161]
	s_mov_b32 m0, s45
	v_lshl_add_u64 v[206:207], s[24:25], 0, v[130:131]
	global_load_lds_dwordx4 v[168:169], off
	v_lshl_add_u64 v[168:169], s[46:47], 0, v[128:129]
	s_add_i32 m0, s45, 0x2000
	s_nop 0
	global_load_lds_dwordx4 v[168:169], off
	v_lshl_add_u64 v[168:169], s[24:25], 0, v[132:133]
	s_mov_b32 m0, s30
	s_nop 0
	global_load_lds_dwordx4 v[168:169], off
	s_mov_b32 m0, s31
	s_nop 0
	global_load_lds_dwordx4 v[206:207], off
	s_waitcnt vmcnt(8)
	s_waitcnt lgkmcnt(0)
	s_barrier
	s_waitcnt lgkmcnt(0)
	v_mfma_f32_16x16x32_bf16 v[60:63], v[138:141], v[186:189], v[60:63]
	v_mfma_f32_16x16x32_bf16 v[56:59], v[152:155], v[186:189], v[56:59]
	v_mfma_f32_16x16x32_bf16 v[44:47], v[138:141], v[194:197], v[44:47]
	v_mfma_f32_16x16x32_bf16 v[40:43], v[152:155], v[194:197], v[40:43]
	v_mfma_f32_16x16x32_bf16 v[28:31], v[138:141], v[202:205], v[28:31]
	v_mfma_f32_16x16x32_bf16 v[24:27], v[152:155], v[202:205], v[24:27]
	v_mfma_f32_16x16x32_bf16 v[12:15], v[138:141], v[232:235], v[12:15]
	v_mfma_f32_16x16x32_bf16 v[8:11], v[152:155], v[232:235], v[8:11]
	v_mfma_f32_16x16x32_bf16 v[60:63], v[148:151], v[190:193], v[60:63]
	v_mfma_f32_16x16x32_bf16 v[56:59], v[156:159], v[190:193], v[56:59]
	v_mfma_f32_16x16x32_bf16 v[44:47], v[148:151], v[198:201], v[44:47]
	v_mfma_f32_16x16x32_bf16 v[40:43], v[156:159], v[198:201], v[40:43]
	v_mfma_f32_16x16x32_bf16 v[28:31], v[148:151], v[228:231], v[28:31]
	v_mfma_f32_16x16x32_bf16 v[24:27], v[156:159], v[228:231], v[24:27]
	v_mfma_f32_16x16x32_bf16 v[12:15], v[148:151], v[236:239], v[12:15]
	v_mfma_f32_16x16x32_bf16 v[8:11], v[156:159], v[236:239], v[8:11]
	v_mfma_f32_16x16x32_bf16 v[52:55], v[170:173], v[186:189], v[52:55]
	v_mfma_f32_16x16x32_bf16 v[48:51], v[178:181], v[186:189], v[48:51]
	v_mfma_f32_16x16x32_bf16 v[36:39], v[170:173], v[194:197], v[36:39]
	v_mfma_f32_16x16x32_bf16 v[32:35], v[178:181], v[194:197], v[32:35]
	v_mfma_f32_16x16x32_bf16 v[20:23], v[170:173], v[202:205], v[20:23]
	v_mfma_f32_16x16x32_bf16 v[16:19], v[178:181], v[202:205], v[16:19]
	v_mfma_f32_16x16x32_bf16 v[4:7], v[170:173], v[232:235], v[4:7]
	v_mfma_f32_16x16x32_bf16 v[0:3], v[178:181], v[232:235], v[0:3]
	v_mfma_f32_16x16x32_bf16 v[52:55], v[174:177], v[190:193], v[52:55]
	v_mfma_f32_16x16x32_bf16 v[48:51], v[182:185], v[190:193], v[48:51]
	v_mfma_f32_16x16x32_bf16 v[36:39], v[174:177], v[198:201], v[36:39]
	v_mfma_f32_16x16x32_bf16 v[32:35], v[182:185], v[198:201], v[32:35]
	v_mfma_f32_16x16x32_bf16 v[20:23], v[174:177], v[228:231], v[20:23]
	v_mfma_f32_16x16x32_bf16 v[16:19], v[182:185], v[228:231], v[16:19]
	v_mfma_f32_16x16x32_bf16 v[4:7], v[174:177], v[236:239], v[4:7]
	v_mfma_f32_16x16x32_bf16 v[0:3], v[182:185], v[236:239], v[0:3]
	s_barrier
	s_add_i32 s45, 0, 0x18000
	s_add_i32 s46, 0, 0x1c000
	v_add_u32_e32 v156, s45, v145
	v_add_u32_e32 v182, s46, v145
	ds_read_b128 v[138:141], v156
	ds_read_b128 v[148:151], v156 offset:1024
	ds_read_b128 v[152:155], v156 offset:2048
	ds_read_b128 v[156:159], v156 offset:3072
	ds_read_b128 v[170:173], v182
	ds_read_b128 v[174:177], v182 offset:1024
	ds_read_b128 v[178:181], v182 offset:2048
	ds_read_b128 v[182:185], v182 offset:3072
	s_add_u32 s24, s24, 0x20000
	s_addc_u32 s25, s25, 0
	s_mov_b32 m0, s34
	v_lshl_add_u64 v[240:241], s[24:25], 0, v[132:133]
	ds_read_b128 v[186:189], v147 offset:32768
	ds_read_b128 v[190:193], v147 offset:33792
	ds_read_b128 v[194:197], v147 offset:34816
	ds_read_b128 v[198:201], v147 offset:35840
	ds_read_b128 v[202:205], v147 offset:36864
	ds_read_b128 v[228:231], v147 offset:37888
	ds_read_b128 v[232:235], v147 offset:38912
	ds_read_b128 v[236:239], v147 offset:39936
	global_load_lds_dwordx4 v[240:241], off
	v_lshl_add_u64 v[240:241], s[24:25], 0, v[130:131]
	s_mov_b32 m0, s35
	s_nop 0
	global_load_lds_dwordx4 v[240:241], off
	s_waitcnt vmcnt(8)
	s_waitcnt lgkmcnt(0)
	s_barrier
	s_waitcnt lgkmcnt(0)
	v_mfma_f32_16x16x32_bf16 v[124:127], v[138:141], v[186:189], v[124:127]
	v_mfma_f32_16x16x32_bf16 v[120:123], v[152:155], v[186:189], v[120:123]
	v_mfma_f32_16x16x32_bf16 v[108:111], v[138:141], v[194:197], v[108:111]
	v_mfma_f32_16x16x32_bf16 v[104:107], v[152:155], v[194:197], v[104:107]
	v_mfma_f32_16x16x32_bf16 v[92:95], v[138:141], v[202:205], v[92:95]
	v_mfma_f32_16x16x32_bf16 v[88:91], v[152:155], v[202:205], v[88:91]
	v_mfma_f32_16x16x32_bf16 v[76:79], v[138:141], v[232:235], v[76:79]
	v_mfma_f32_16x16x32_bf16 v[72:75], v[152:155], v[232:235], v[72:75]
	v_mfma_f32_16x16x32_bf16 v[124:127], v[148:151], v[190:193], v[124:127]
	v_mfma_f32_16x16x32_bf16 v[120:123], v[156:159], v[190:193], v[120:123]
	v_mfma_f32_16x16x32_bf16 v[108:111], v[148:151], v[198:201], v[108:111]
	v_mfma_f32_16x16x32_bf16 v[104:107], v[156:159], v[198:201], v[104:107]
	v_mfma_f32_16x16x32_bf16 v[92:95], v[148:151], v[228:231], v[92:95]
	v_mfma_f32_16x16x32_bf16 v[88:91], v[156:159], v[228:231], v[88:91]
	v_mfma_f32_16x16x32_bf16 v[76:79], v[148:151], v[236:239], v[76:79]
	v_mfma_f32_16x16x32_bf16 v[72:75], v[156:159], v[236:239], v[72:75]
	v_mfma_f32_16x16x32_bf16 v[116:119], v[170:173], v[186:189], v[116:119]
	v_mfma_f32_16x16x32_bf16 v[112:115], v[178:181], v[186:189], v[112:115]
	v_mfma_f32_16x16x32_bf16 v[100:103], v[170:173], v[194:197], v[100:103]
	v_mfma_f32_16x16x32_bf16 v[96:99], v[178:181], v[194:197], v[96:99]
	v_mfma_f32_16x16x32_bf16 v[84:87], v[170:173], v[202:205], v[84:87]
	v_mfma_f32_16x16x32_bf16 v[80:83], v[178:181], v[202:205], v[80:83]
	v_mfma_f32_16x16x32_bf16 v[68:71], v[170:173], v[232:235], v[68:71]
	v_mfma_f32_16x16x32_bf16 v[64:67], v[178:181], v[232:235], v[64:67]
	v_mfma_f32_16x16x32_bf16 v[116:119], v[174:177], v[190:193], v[116:119]
	v_mfma_f32_16x16x32_bf16 v[112:115], v[182:185], v[190:193], v[112:115]
	v_mfma_f32_16x16x32_bf16 v[100:103], v[174:177], v[198:201], v[100:103]
	v_mfma_f32_16x16x32_bf16 v[96:99], v[182:185], v[198:201], v[96:99]
	v_mfma_f32_16x16x32_bf16 v[84:87], v[174:177], v[228:231], v[84:87]
	v_mfma_f32_16x16x32_bf16 v[80:83], v[182:185], v[228:231], v[80:83]
	v_mfma_f32_16x16x32_bf16 v[68:71], v[174:177], v[236:239], v[68:71]
	v_mfma_f32_16x16x32_bf16 v[64:67], v[182:185], v[236:239], v[64:67]
	s_barrier
	s_add_i32 s24, s45, s77
	v_lshl_add_u64 v[142:143], v[142:143], 0, s[96:97]
	s_mov_b32 m0, s24
	ds_read_b128 v[186:189], v147 offset:49152
	ds_read_b128 v[190:193], v147 offset:50176
	ds_read_b128 v[194:197], v147 offset:51200
	ds_read_b128 v[198:201], v147 offset:52224
	ds_read_b128 v[202:205], v147 offset:53248
	ds_read_b128 v[228:231], v147 offset:54272
	ds_read_b128 v[232:235], v147 offset:55296
	ds_read_b128 v[236:239], v147 offset:56320
	global_load_lds_dwordx4 v[142:143], off
	s_add_i32 m0, s24, 0x2000
	s_add_u32 s22, s22, 0x20080
	v_lshl_add_u64 v[142:143], v[166:167], 0, s[96:97]
	s_addc_u32 s23, s23, 0
	s_add_i32 s24, s46, s77
	global_load_lds_dwordx4 v[142:143], off
	v_lshl_add_u64 v[142:143], s[22:23], 0, v[160:161]
	s_mov_b32 m0, s24
	s_nop 0
	global_load_lds_dwordx4 v[142:143], off
	v_lshl_add_u64 v[142:143], s[22:23], 0, v[128:129]
	s_add_i32 m0, s24, 0x2000
	s_nop 0
	global_load_lds_dwordx4 v[142:143], off
	v_lshl_add_u64 v[142:143], v[168:169], 0, s[96:97]
	s_mov_b32 m0, s36
	s_nop 0
	global_load_lds_dwordx4 v[142:143], off
	v_lshl_add_u64 v[142:143], v[206:207], 0, s[96:97]
	s_mov_b32 m0, s37
	s_nop 0
	global_load_lds_dwordx4 v[142:143], off
	s_waitcnt vmcnt(8)
	s_waitcnt lgkmcnt(0)
	s_barrier
	s_waitcnt lgkmcnt(0)
	v_mfma_f32_16x16x32_bf16 v[60:63], v[138:141], v[186:189], v[60:63]
	v_mfma_f32_16x16x32_bf16 v[56:59], v[152:155], v[186:189], v[56:59]
	v_mfma_f32_16x16x32_bf16 v[44:47], v[138:141], v[194:197], v[44:47]
	v_mfma_f32_16x16x32_bf16 v[40:43], v[152:155], v[194:197], v[40:43]
	v_mfma_f32_16x16x32_bf16 v[28:31], v[138:141], v[202:205], v[28:31]
	v_mfma_f32_16x16x32_bf16 v[24:27], v[152:155], v[202:205], v[24:27]
	v_mfma_f32_16x16x32_bf16 v[12:15], v[138:141], v[232:235], v[12:15]
	v_mfma_f32_16x16x32_bf16 v[8:11], v[152:155], v[232:235], v[8:11]
	v_mfma_f32_16x16x32_bf16 v[60:63], v[148:151], v[190:193], v[60:63]
	v_mfma_f32_16x16x32_bf16 v[56:59], v[156:159], v[190:193], v[56:59]
	v_mfma_f32_16x16x32_bf16 v[44:47], v[148:151], v[198:201], v[44:47]
	v_mfma_f32_16x16x32_bf16 v[40:43], v[156:159], v[198:201], v[40:43]
	v_mfma_f32_16x16x32_bf16 v[28:31], v[148:151], v[228:231], v[28:31]
	v_mfma_f32_16x16x32_bf16 v[24:27], v[156:159], v[228:231], v[24:27]
	v_mfma_f32_16x16x32_bf16 v[12:15], v[148:151], v[236:239], v[12:15]
	v_mfma_f32_16x16x32_bf16 v[8:11], v[156:159], v[236:239], v[8:11]
	v_mfma_f32_16x16x32_bf16 v[52:55], v[170:173], v[186:189], v[52:55]
	v_mfma_f32_16x16x32_bf16 v[48:51], v[178:181], v[186:189], v[48:51]
	v_mfma_f32_16x16x32_bf16 v[36:39], v[170:173], v[194:197], v[36:39]
	v_mfma_f32_16x16x32_bf16 v[32:35], v[178:181], v[194:197], v[32:35]
	v_mfma_f32_16x16x32_bf16 v[20:23], v[170:173], v[202:205], v[20:23]
	v_mfma_f32_16x16x32_bf16 v[16:19], v[178:181], v[202:205], v[16:19]
	v_mfma_f32_16x16x32_bf16 v[4:7], v[170:173], v[232:235], v[4:7]
	v_mfma_f32_16x16x32_bf16 v[0:3], v[178:181], v[232:235], v[0:3]
	v_mfma_f32_16x16x32_bf16 v[52:55], v[174:177], v[190:193], v[52:55]
	v_mfma_f32_16x16x32_bf16 v[48:51], v[182:185], v[190:193], v[48:51]
	v_mfma_f32_16x16x32_bf16 v[36:39], v[174:177], v[198:201], v[36:39]
	v_mfma_f32_16x16x32_bf16 v[32:35], v[182:185], v[198:201], v[32:35]
	v_mfma_f32_16x16x32_bf16 v[20:23], v[174:177], v[228:231], v[20:23]
	v_mfma_f32_16x16x32_bf16 v[16:19], v[182:185], v[228:231], v[16:19]
	v_mfma_f32_16x16x32_bf16 v[4:7], v[174:177], v[236:239], v[4:7]
	v_mfma_f32_16x16x32_bf16 v[0:3], v[182:185], v[236:239], v[0:3]
	s_barrier
	s_add_i32 s44, s44, 2
	s_add_u32 s42, s42, 0x100
	s_addc_u32 s43, s43, 0
	s_add_u32 s20, s20, 0x100
	s_addc_u32 s21, s21, 0
	s_cmp_gt_u32 s44, 5
	s_cbranch_scc0 .LBB0_167
	s_setprio 0
	v_readlane_b32 s20, v253, 23
	v_readlane_b32 s21, v253, 24
	s_and_b64 vcc, exec, s[20:21]
	s_cbranch_vccz .LBB0_170
	s_barrier

.LBB0_271:
	s_ashr_i32 s9, s8, 31
	s_lshl_b64 s[10:11], s[8:9], 19
	s_add_u32 s10, s2, s10
	s_addc_u32 s11, s20, s11
	s_and_b64 s[12:13], s[6:7], exec
	s_cselect_b32 s9, s11, s17
	s_cselect_b32 s38, s10, s16
	s_ashr_i32 s1, s0, 31
	s_lshl_b64 s[12:13], s[0:1], 19
	s_add_u32 s12, s21, s12
	s_addc_u32 s13, s22, s13
	s_and_b64 s[18:19], s[6:7], exec
	s_cselect_b32 s1, s13, s15
	s_cselect_b32 s39, s12, s14
	s_add_u32 s40, s14, 0x100
	s_addc_u32 s41, s15, 0
	s_add_u32 s14, s16, 0x40080
	v_mov_b32_e32 v0, 0
	s_addc_u32 s15, s17, 0
	s_mov_b32 s42, -2
	v_mov_b32_e32 v1, v0
	v_mov_b32_e32 v2, v0
	v_mov_b32_e32 v3, v0
	v_mov_b32_e32 v4, v0
	v_mov_b32_e32 v5, v0
	v_mov_b32_e32 v6, v0
	v_mov_b32_e32 v7, v0
	v_mov_b32_e32 v16, v0
	v_mov_b32_e32 v17, v0
	v_mov_b32_e32 v18, v0
	v_mov_b32_e32 v19, v0
	v_mov_b32_e32 v20, v0
	v_mov_b32_e32 v21, v0
	v_mov_b32_e32 v22, v0
	v_mov_b32_e32 v23, v0
	v_mov_b32_e32 v32, v0
	v_mov_b32_e32 v33, v0
	v_mov_b32_e32 v34, v0
	v_mov_b32_e32 v35, v0
	v_mov_b32_e32 v36, v0
	v_mov_b32_e32 v37, v0
	v_mov_b32_e32 v38, v0
	v_mov_b32_e32 v39, v0
	v_mov_b32_e32 v48, v0
	v_mov_b32_e32 v49, v0
	v_mov_b32_e32 v50, v0
	v_mov_b32_e32 v51, v0
	v_mov_b32_e32 v52, v0
	v_mov_b32_e32 v53, v0
	v_mov_b32_e32 v54, v0
	v_mov_b32_e32 v55, v0
	v_mov_b32_e32 v8, v0
	v_mov_b32_e32 v9, v0
	v_mov_b32_e32 v10, v0
	v_mov_b32_e32 v11, v0
	v_mov_b32_e32 v12, v0
	v_mov_b32_e32 v13, v0
	v_mov_b32_e32 v14, v0
	v_mov_b32_e32 v15, v0
	v_mov_b32_e32 v24, v0
	v_mov_b32_e32 v25, v0
	v_mov_b32_e32 v26, v0
	v_mov_b32_e32 v27, v0
	v_mov_b32_e32 v28, v0
	v_mov_b32_e32 v29, v0
	v_mov_b32_e32 v30, v0
	v_mov_b32_e32 v31, v0
	v_mov_b32_e32 v40, v0
	v_mov_b32_e32 v41, v0
	v_mov_b32_e32 v42, v0
	v_mov_b32_e32 v43, v0
	v_mov_b32_e32 v44, v0
	v_mov_b32_e32 v45, v0
	v_mov_b32_e32 v46, v0
	v_mov_b32_e32 v47, v0
	v_mov_b32_e32 v56, v0
	v_mov_b32_e32 v57, v0
	v_mov_b32_e32 v58, v0
	v_mov_b32_e32 v59, v0
	v_mov_b32_e32 v60, v0
	v_mov_b32_e32 v61, v0
	v_mov_b32_e32 v62, v0
	v_mov_b32_e32 v63, v0
	v_mov_b32_e32 v64, v0
	v_mov_b32_e32 v65, v0
	v_mov_b32_e32 v66, v0
	v_mov_b32_e32 v67, v0
	v_mov_b32_e32 v68, v0
	v_mov_b32_e32 v69, v0
	v_mov_b32_e32 v70, v0
	v_mov_b32_e32 v71, v0
	v_mov_b32_e32 v80, v0
	v_mov_b32_e32 v81, v0
	v_mov_b32_e32 v82, v0
	v_mov_b32_e32 v83, v0
	v_mov_b32_e32 v84, v0
	v_mov_b32_e32 v85, v0
	v_mov_b32_e32 v86, v0
	v_mov_b32_e32 v87, v0
	v_mov_b32_e32 v96, v0
	v_mov_b32_e32 v97, v0
	v_mov_b32_e32 v98, v0
	v_mov_b32_e32 v99, v0
	v_mov_b32_e32 v100, v0
	v_mov_b32_e32 v101, v0
	v_mov_b32_e32 v102, v0
	v_mov_b32_e32 v103, v0
	v_mov_b32_e32 v112, v0
	v_mov_b32_e32 v113, v0
	v_mov_b32_e32 v114, v0
	v_mov_b32_e32 v115, v0
	v_mov_b32_e32 v116, v0
	v_mov_b32_e32 v117, v0
	v_mov_b32_e32 v118, v0
	v_mov_b32_e32 v119, v0
	v_mov_b32_e32 v72, v0
	v_mov_b32_e32 v73, v0
	v_mov_b32_e32 v74, v0
	v_mov_b32_e32 v75, v0
	v_mov_b32_e32 v76, v0
	v_mov_b32_e32 v77, v0
	v_mov_b32_e32 v78, v0
	v_mov_b32_e32 v79, v0
	v_mov_b32_e32 v88, v0
	v_mov_b32_e32 v89, v0
	v_mov_b32_e32 v90, v0
	v_mov_b32_e32 v91, v0
	v_mov_b32_e32 v92, v0
	v_mov_b32_e32 v93, v0
	v_mov_b32_e32 v94, v0
	v_mov_b32_e32 v95, v0
	v_mov_b32_e32 v104, v0
	v_mov_b32_e32 v105, v0
	v_mov_b32_e32 v106, v0
	v_mov_b32_e32 v107, v0
	v_mov_b32_e32 v108, v0
	v_mov_b32_e32 v109, v0
	v_mov_b32_e32 v110, v0
	v_mov_b32_e32 v111, v0
	v_mov_b32_e32 v120, v0
	v_mov_b32_e32 v121, v0
	v_mov_b32_e32 v122, v0
	v_mov_b32_e32 v123, v0
	v_mov_b32_e32 v124, v0
	v_mov_b32_e32 v125, v0
	v_mov_b32_e32 v126, v0
	v_mov_b32_e32 v127, v0
	v_readlane_b32 s100, v252, 21
	s_sub_u32 s100, s100, 0
	s_cmp_lt_u32 s100, 4
	s_cbranch_scc0 .Lprio_5
	s_setprio 1
.Lprio_5:
.LBB0_272:
	s_add_u32 s16, s14, 0xfffc0080
	s_addc_u32 s17, s15, -1
	s_add_i32 s43, 0, 0x10000
	s_cmp_eq_u32 s42, 12
	s_cselect_b32 s19, s9, s17
	s_cselect_b32 s18, s38, s16
	v_add_u32_e32 v147, s43, v145
	s_cselect_b32 s17, s1, s41
	s_cselect_b32 s16, s39, s40
	s_add_i32 s46, 0, 0x14000
	ds_read_b128 v[140:143], v147
	ds_read_b128 v[148:151], v147 offset:1024
	ds_read_b128 v[152:155], v147 offset:2048
	ds_read_b128 v[156:159], v147 offset:3072
	v_add_u32_e32 v147, s46, v145
	ds_read_b128 v[170:173], v147
	ds_read_b128 v[174:177], v147 offset:1024
	ds_read_b128 v[178:181], v147 offset:2048
	ds_read_b128 v[182:185], v147 offset:3072
	v_lshl_add_u64 v[166:167], s[14:15], 0, v[138:139]
	s_add_i32 m0, s23, 0xc000
	ds_read_b128 v[186:189], v146
	ds_read_b128 v[190:193], v146 offset:1024
	ds_read_b128 v[194:197], v146 offset:2048
	ds_read_b128 v[198:201], v146 offset:3072
	ds_read_b128 v[202:205], v146 offset:4096
	ds_read_b128 v[228:231], v146 offset:5120
	ds_read_b128 v[232:235], v146 offset:6144
	ds_read_b128 v[236:239], v146 offset:7168
	global_load_lds_dwordx4 v[166:167], off
	v_lshl_add_u64 v[166:167], s[14:15], 0, v[136:137]
	s_add_i32 m0, s23, 0xe000
	s_nop 0
	global_load_lds_dwordx4 v[166:167], off
	s_waitcnt vmcnt(8)
	s_waitcnt lgkmcnt(0)
	s_barrier
	s_waitcnt lgkmcnt(0)
	v_mfma_f32_16x16x32_bf16 v[124:127], v[140:143], v[186:189], v[124:127]
	v_mfma_f32_16x16x32_bf16 v[120:123], v[152:155], v[186:189], v[120:123]
	v_mfma_f32_16x16x32_bf16 v[108:111], v[140:143], v[194:197], v[108:111]
	v_mfma_f32_16x16x32_bf16 v[104:107], v[152:155], v[194:197], v[104:107]
	v_mfma_f32_16x16x32_bf16 v[92:95], v[140:143], v[202:205], v[92:95]
	v_mfma_f32_16x16x32_bf16 v[88:91], v[152:155], v[202:205], v[88:91]
	v_mfma_f32_16x16x32_bf16 v[76:79], v[140:143], v[232:235], v[76:79]
	v_mfma_f32_16x16x32_bf16 v[72:75], v[152:155], v[232:235], v[72:75]
	v_mfma_f32_16x16x32_bf16 v[124:127], v[148:151], v[190:193], v[124:127]
	v_mfma_f32_16x16x32_bf16 v[120:123], v[156:159], v[190:193], v[120:123]
	v_mfma_f32_16x16x32_bf16 v[108:111], v[148:151], v[198:201], v[108:111]
	v_mfma_f32_16x16x32_bf16 v[104:107], v[156:159], v[198:201], v[104:107]
	v_mfma_f32_16x16x32_bf16 v[92:95], v[148:151], v[228:231], v[92:95]
	v_mfma_f32_16x16x32_bf16 v[88:91], v[156:159], v[228:231], v[88:91]
	v_mfma_f32_16x16x32_bf16 v[76:79], v[148:151], v[236:239], v[76:79]
	v_mfma_f32_16x16x32_bf16 v[72:75], v[156:159], v[236:239], v[72:75]
	v_mfma_f32_16x16x32_bf16 v[116:119], v[170:173], v[186:189], v[116:119]
	v_mfma_f32_16x16x32_bf16 v[112:115], v[178:181], v[186:189], v[112:115]
	v_mfma_f32_16x16x32_bf16 v[100:103], v[170:173], v[194:197], v[100:103]
	v_mfma_f32_16x16x32_bf16 v[96:99], v[178:181], v[194:197], v[96:99]
	v_mfma_f32_16x16x32_bf16 v[84:87], v[170:173], v[202:205], v[84:87]
	v_mfma_f32_16x16x32_bf16 v[80:83], v[178:181], v[202:205], v[80:83]
	v_mfma_f32_16x16x32_bf16 v[68:71], v[170:173], v[232:235], v[68:71]
	v_mfma_f32_16x16x32_bf16 v[64:67], v[178:181], v[232:235], v[64:67]
	v_mfma_f32_16x16x32_bf16 v[116:119], v[174:177], v[190:193], v[116:119]
	v_mfma_f32_16x16x32_bf16 v[112:115], v[182:185], v[190:193], v[112:115]
	v_mfma_f32_16x16x32_bf16 v[100:103], v[174:177], v[198:201], v[100:103]
	v_mfma_f32_16x16x32_bf16 v[96:99], v[182:185], v[198:201], v[96:99]
	v_mfma_f32_16x16x32_bf16 v[84:87], v[174:177], v[228:231], v[84:87]
	v_mfma_f32_16x16x32_bf16 v[80:83], v[182:185], v[228:231], v[80:83]
	v_mfma_f32_16x16x32_bf16 v[68:71], v[174:177], v[236:239], v[68:71]
	v_mfma_f32_16x16x32_bf16 v[64:67], v[182:185], v[236:239], v[64:67]
	s_barrier
	s_add_i32 s43, s43, s77
	v_lshl_add_u64 v[166:167], s[16:17], 0, v[160:161]
	s_mov_b32 m0, s43
	ds_read_b128 v[186:189], v146 offset:16384
	ds_read_b128 v[190:193], v146 offset:17408
	ds_read_b128 v[194:197], v146 offset:18432
	ds_read_b128 v[198:201], v146 offset:19456
	ds_read_b128 v[202:205], v146 offset:20480
	ds_read_b128 v[228:231], v146 offset:21504
	ds_read_b128 v[232:235], v146 offset:22528
	ds_read_b128 v[236:239], v146 offset:23552
	global_load_lds_dwordx4 v[166:167], off
	s_add_i32 m0, s43, 0x2000
	s_add_u32 s44, s16, 0x40000
	v_lshl_add_u64 v[168:169], s[16:17], 0, v[128:129]
	s_addc_u32 s45, s17, 0
	s_add_i32 s43, s46, s77
	global_load_lds_dwordx4 v[168:169], off
	v_lshl_add_u64 v[206:207], s[44:45], 0, v[160:161]
	s_mov_b32 m0, s43
	v_lshl_add_u64 v[240:241], s[18:19], 0, v[130:131]
	global_load_lds_dwordx4 v[206:207], off
	v_lshl_add_u64 v[206:207], s[44:45], 0, v[128:129]
	s_add_i32 m0, s43, 0x2000
	s_nop 0
	global_load_lds_dwordx4 v[206:207], off
	v_lshl_add_u64 v[206:207], s[18:19], 0, v[132:133]
	s_mov_b32 m0, s23
	s_nop 0
	global_load_lds_dwordx4 v[206:207], off
	s_mov_b32 m0, s24
	s_nop 0
	global_load_lds_dwordx4 v[240:241], off
	s_waitcnt vmcnt(8)
	s_waitcnt lgkmcnt(0)
	s_barrier
	s_waitcnt lgkmcnt(0)
	v_mfma_f32_16x16x32_bf16 v[60:63], v[140:143], v[186:189], v[60:63]
	v_mfma_f32_16x16x32_bf16 v[56:59], v[152:155], v[186:189], v[56:59]
	v_mfma_f32_16x16x32_bf16 v[44:47], v[140:143], v[194:197], v[44:47]
	v_mfma_f32_16x16x32_bf16 v[40:43], v[152:155], v[194:197], v[40:43]
	v_mfma_f32_16x16x32_bf16 v[28:31], v[140:143], v[202:205], v[28:31]
	v_mfma_f32_16x16x32_bf16 v[24:27], v[152:155], v[202:205], v[24:27]
	v_mfma_f32_16x16x32_bf16 v[12:15], v[140:143], v[232:235], v[12:15]
	v_mfma_f32_16x16x32_bf16 v[8:11], v[152:155], v[232:235], v[8:11]
	v_mfma_f32_16x16x32_bf16 v[60:63], v[148:151], v[190:193], v[60:63]
	v_mfma_f32_16x16x32_bf16 v[56:59], v[156:159], v[190:193], v[56:59]
	v_mfma_f32_16x16x32_bf16 v[44:47], v[148:151], v[198:201], v[44:47]
	v_mfma_f32_16x16x32_bf16 v[40:43], v[156:159], v[198:201], v[40:43]
	v_mfma_f32_16x16x32_bf16 v[28:31], v[148:151], v[228:231], v[28:31]
	v_mfma_f32_16x16x32_bf16 v[24:27], v[156:159], v[228:231], v[24:27]
	v_mfma_f32_16x16x32_bf16 v[12:15], v[148:151], v[236:239], v[12:15]
	v_mfma_f32_16x16x32_bf16 v[8:11], v[156:159], v[236:239], v[8:11]
	v_mfma_f32_16x16x32_bf16 v[52:55], v[170:173], v[186:189], v[52:55]
	v_mfma_f32_16x16x32_bf16 v[48:51], v[178:181], v[186:189], v[48:51]
	v_mfma_f32_16x16x32_bf16 v[36:39], v[170:173], v[194:197], v[36:39]
	v_mfma_f32_16x16x32_bf16 v[32:35], v[178:181], v[194:197], v[32:35]
	v_mfma_f32_16x16x32_bf16 v[20:23], v[170:173], v[202:205], v[20:23]
	v_mfma_f32_16x16x32_bf16 v[16:19], v[178:181], v[202:205], v[16:19]
	v_mfma_f32_16x16x32_bf16 v[4:7], v[170:173], v[232:235], v[4:7]
	v_mfma_f32_16x16x32_bf16 v[0:3], v[178:181], v[232:235], v[0:3]
	v_mfma_f32_16x16x32_bf16 v[52:55], v[174:177], v[190:193], v[52:55]
	v_mfma_f32_16x16x32_bf16 v[48:51], v[182:185], v[190:193], v[48:51]
	v_mfma_f32_16x16x32_bf16 v[36:39], v[174:177], v[198:201], v[36:39]
	v_mfma_f32_16x16x32_bf16 v[32:35], v[182:185], v[198:201], v[32:35]
	v_mfma_f32_16x16x32_bf16 v[20:23], v[174:177], v[228:231], v[20:23]
	v_mfma_f32_16x16x32_bf16 v[16:19], v[182:185], v[228:231], v[16:19]
	v_mfma_f32_16x16x32_bf16 v[4:7], v[174:177], v[236:239], v[4:7]
	v_mfma_f32_16x16x32_bf16 v[0:3], v[182:185], v[236:239], v[0:3]
	s_barrier
	s_add_i32 s43, 0, 0x18000
	v_add_u32_e32 v147, s43, v145
	s_add_i32 s44, 0, 0x1c000
	ds_read_b128 v[140:143], v147
	ds_read_b128 v[148:151], v147 offset:1024
	ds_read_b128 v[152:155], v147 offset:2048
	ds_read_b128 v[156:159], v147 offset:3072
	v_add_u32_e32 v147, s44, v145
	ds_read_b128 v[170:173], v147
	ds_read_b128 v[174:177], v147 offset:1024
	ds_read_b128 v[178:181], v147 offset:2048
	ds_read_b128 v[182:185], v147 offset:3072
	s_add_u32 s18, s18, 0x40000
	s_addc_u32 s19, s19, 0
	s_mov_b32 m0, s25
	v_lshl_add_u64 v[242:243], s[18:19], 0, v[132:133]
	ds_read_b128 v[186:189], v146 offset:32768
	ds_read_b128 v[190:193], v146 offset:33792
	ds_read_b128 v[194:197], v146 offset:34816
	ds_read_b128 v[198:201], v146 offset:35840
	ds_read_b128 v[202:205], v146 offset:36864
	ds_read_b128 v[228:231], v146 offset:37888
	ds_read_b128 v[232:235], v146 offset:38912
	ds_read_b128 v[236:239], v146 offset:39936
	global_load_lds_dwordx4 v[242:243], off
	v_lshl_add_u64 v[242:243], s[18:19], 0, v[130:131]
	s_mov_b32 m0, s26
	s_nop 0
	global_load_lds_dwordx4 v[242:243], off
	s_waitcnt vmcnt(8)
	s_waitcnt lgkmcnt(0)
	s_barrier
	s_waitcnt lgkmcnt(0)
	v_mfma_f32_16x16x32_bf16 v[124:127], v[140:143], v[186:189], v[124:127]
	v_mfma_f32_16x16x32_bf16 v[120:123], v[152:155], v[186:189], v[120:123]
	v_mfma_f32_16x16x32_bf16 v[108:111], v[140:143], v[194:197], v[108:111]
	v_mfma_f32_16x16x32_bf16 v[104:107], v[152:155], v[194:197], v[104:107]
	v_mfma_f32_16x16x32_bf16 v[92:95], v[140:143], v[202:205], v[92:95]
	v_mfma_f32_16x16x32_bf16 v[88:91], v[152:155], v[202:205], v[88:91]
	v_mfma_f32_16x16x32_bf16 v[76:79], v[140:143], v[232:235], v[76:79]
	v_mfma_f32_16x16x32_bf16 v[72:75], v[152:155], v[232:235], v[72:75]
	v_mfma_f32_16x16x32_bf16 v[124:127], v[148:151], v[190:193], v[124:127]
	v_mfma_f32_16x16x32_bf16 v[120:123], v[156:159], v[190:193], v[120:123]
	v_mfma_f32_16x16x32_bf16 v[108:111], v[148:151], v[198:201], v[108:111]
	v_mfma_f32_16x16x32_bf16 v[104:107], v[156:159], v[198:201], v[104:107]
	v_mfma_f32_16x16x32_bf16 v[92:95], v[148:151], v[228:231], v[92:95]
	v_mfma_f32_16x16x32_bf16 v[88:91], v[156:159], v[228:231], v[88:91]
	v_mfma_f32_16x16x32_bf16 v[76:79], v[148:151], v[236:239], v[76:79]
	v_mfma_f32_16x16x32_bf16 v[72:75], v[156:159], v[236:239], v[72:75]
	v_mfma_f32_16x16x32_bf16 v[116:119], v[170:173], v[186:189], v[116:119]
	v_mfma_f32_16x16x32_bf16 v[112:115], v[178:181], v[186:189], v[112:115]
	v_mfma_f32_16x16x32_bf16 v[100:103], v[170:173], v[194:197], v[100:103]
	v_mfma_f32_16x16x32_bf16 v[96:99], v[178:181], v[194:197], v[96:99]
	v_mfma_f32_16x16x32_bf16 v[84:87], v[170:173], v[202:205], v[84:87]
	v_mfma_f32_16x16x32_bf16 v[80:83], v[178:181], v[202:205], v[80:83]
	v_mfma_f32_16x16x32_bf16 v[68:71], v[170:173], v[232:235], v[68:71]
	v_mfma_f32_16x16x32_bf16 v[64:67], v[178:181], v[232:235], v[64:67]
	v_mfma_f32_16x16x32_bf16 v[116:119], v[174:177], v[190:193], v[116:119]
	v_mfma_f32_16x16x32_bf16 v[112:115], v[182:185], v[190:193], v[112:115]
	v_mfma_f32_16x16x32_bf16 v[100:103], v[174:177], v[198:201], v[100:103]
	v_mfma_f32_16x16x32_bf16 v[96:99], v[182:185], v[198:201], v[96:99]
	v_mfma_f32_16x16x32_bf16 v[84:87], v[174:177], v[228:231], v[84:87]
	v_mfma_f32_16x16x32_bf16 v[80:83], v[182:185], v[228:231], v[80:83]
	v_mfma_f32_16x16x32_bf16 v[68:71], v[174:177], v[236:239], v[68:71]
	v_mfma_f32_16x16x32_bf16 v[64:67], v[182:185], v[236:239], v[64:67]
	s_barrier
	s_add_i32 s18, s43, s77
	v_lshl_add_u64 v[166:167], v[166:167], 0, s[96:97]
	s_mov_b32 m0, s18
	ds_read_b128 v[186:189], v146 offset:49152
	ds_read_b128 v[190:193], v146 offset:50176
	ds_read_b128 v[194:197], v146 offset:51200
	ds_read_b128 v[198:201], v146 offset:52224
	ds_read_b128 v[202:205], v146 offset:53248
	ds_read_b128 v[228:231], v146 offset:54272
	ds_read_b128 v[232:235], v146 offset:55296
	ds_read_b128 v[236:239], v146 offset:56320
	global_load_lds_dwordx4 v[166:167], off
	s_add_i32 m0, s18, 0x2000
	s_add_u32 s16, s16, 0x40080
	v_lshl_add_u64 v[166:167], v[168:169], 0, s[96:97]
	s_addc_u32 s17, s17, 0
	s_add_i32 s18, s44, s77
	global_load_lds_dwordx4 v[166:167], off
	v_lshl_add_u64 v[166:167], s[16:17], 0, v[160:161]
	s_mov_b32 m0, s18
	s_nop 0
	global_load_lds_dwordx4 v[166:167], off
	v_lshl_add_u64 v[166:167], s[16:17], 0, v[128:129]
	s_add_i32 m0, s18, 0x2000
	s_nop 0
	global_load_lds_dwordx4 v[166:167], off
	v_lshl_add_u64 v[166:167], v[206:207], 0, s[96:97]
	s_mov_b32 m0, s31
	s_nop 0
	global_load_lds_dwordx4 v[166:167], off
	v_lshl_add_u64 v[166:167], v[240:241], 0, s[96:97]
	s_mov_b32 m0, s34
	s_nop 0
	global_load_lds_dwordx4 v[166:167], off
	s_waitcnt vmcnt(8)
	s_waitcnt lgkmcnt(0)
	s_barrier
	s_waitcnt lgkmcnt(0)
	v_mfma_f32_16x16x32_bf16 v[60:63], v[140:143], v[186:189], v[60:63]
	v_mfma_f32_16x16x32_bf16 v[56:59], v[152:155], v[186:189], v[56:59]
	v_mfma_f32_16x16x32_bf16 v[44:47], v[140:143], v[194:197], v[44:47]
	v_mfma_f32_16x16x32_bf16 v[40:43], v[152:155], v[194:197], v[40:43]
	v_mfma_f32_16x16x32_bf16 v[28:31], v[140:143], v[202:205], v[28:31]
	v_mfma_f32_16x16x32_bf16 v[24:27], v[152:155], v[202:205], v[24:27]
	v_mfma_f32_16x16x32_bf16 v[12:15], v[140:143], v[232:235], v[12:15]
	v_mfma_f32_16x16x32_bf16 v[8:11], v[152:155], v[232:235], v[8:11]
	v_mfma_f32_16x16x32_bf16 v[60:63], v[148:151], v[190:193], v[60:63]
	v_mfma_f32_16x16x32_bf16 v[56:59], v[156:159], v[190:193], v[56:59]
	v_mfma_f32_16x16x32_bf16 v[44:47], v[148:151], v[198:201], v[44:47]
	v_mfma_f32_16x16x32_bf16 v[40:43], v[156:159], v[198:201], v[40:43]
	v_mfma_f32_16x16x32_bf16 v[28:31], v[148:151], v[228:231], v[28:31]
	v_mfma_f32_16x16x32_bf16 v[24:27], v[156:159], v[228:231], v[24:27]
	v_mfma_f32_16x16x32_bf16 v[12:15], v[148:151], v[236:239], v[12:15]
	v_mfma_f32_16x16x32_bf16 v[8:11], v[156:159], v[236:239], v[8:11]
	v_mfma_f32_16x16x32_bf16 v[52:55], v[170:173], v[186:189], v[52:55]
	v_mfma_f32_16x16x32_bf16 v[48:51], v[178:181], v[186:189], v[48:51]
	v_mfma_f32_16x16x32_bf16 v[36:39], v[170:173], v[194:197], v[36:39]
	v_mfma_f32_16x16x32_bf16 v[32:35], v[178:181], v[194:197], v[32:35]
	v_mfma_f32_16x16x32_bf16 v[20:23], v[170:173], v[202:205], v[20:23]
	v_mfma_f32_16x16x32_bf16 v[16:19], v[178:181], v[202:205], v[16:19]
	v_mfma_f32_16x16x32_bf16 v[4:7], v[170:173], v[232:235], v[4:7]
	v_mfma_f32_16x16x32_bf16 v[0:3], v[178:181], v[232:235], v[0:3]
	v_mfma_f32_16x16x32_bf16 v[52:55], v[174:177], v[190:193], v[52:55]
	v_mfma_f32_16x16x32_bf16 v[48:51], v[182:185], v[190:193], v[48:51]
	v_mfma_f32_16x16x32_bf16 v[36:39], v[174:177], v[198:201], v[36:39]
	v_mfma_f32_16x16x32_bf16 v[32:35], v[182:185], v[198:201], v[32:35]
	v_mfma_f32_16x16x32_bf16 v[20:23], v[174:177], v[228:231], v[20:23]
	v_mfma_f32_16x16x32_bf16 v[16:19], v[182:185], v[228:231], v[16:19]
	v_mfma_f32_16x16x32_bf16 v[4:7], v[174:177], v[236:239], v[4:7]
	v_mfma_f32_16x16x32_bf16 v[0:3], v[182:185], v[236:239], v[0:3]
	s_barrier
	s_add_i32 s42, s42, 2
	s_add_u32 s40, s40, 0x100
	s_addc_u32 s41, s41, 0
	s_add_u32 s14, s14, 0x100
	s_addc_u32 s15, s15, 0
	s_cmp_gt_u32 s42, 13
	s_cbranch_scc0 .LBB0_272
	s_setprio 0
	v_readlane_b32 s14, v253, 23
	v_readlane_b32 s15, v253, 24
	s_and_b64 vcc, exec, s[14:15]
	s_cbranch_vccz .LBB0_275
	s_barrier

.LBB0_289:
	s_ashr_i32 s1, s0, 31
	s_lshl_b64 s[10:11], s[0:1], 19
	s_add_u32 s10, s2, s10
	s_addc_u32 s11, s20, s11
	s_and_b64 s[12:13], s[6:7], exec
	s_cselect_b32 s1, s11, s17
	s_cselect_b32 s37, s10, s16
	s_ashr_i32 s9, s8, 31
	s_lshl_b64 s[12:13], s[8:9], 19
	s_add_u32 s12, s21, s12
	s_addc_u32 s13, s22, s13
	s_and_b64 s[18:19], s[6:7], exec
	s_cselect_b32 s9, s13, s15
	s_cselect_b32 s38, s12, s14
	s_add_u32 s39, s14, 0x100
	s_addc_u32 s40, s15, 0
	s_add_u32 s14, s16, 0x40080
	v_mov_b32_e32 v0, 0
	s_addc_u32 s15, s17, 0
	s_mov_b32 s41, -2
	v_mov_b32_e32 v1, v0
	v_mov_b32_e32 v2, v0
	v_mov_b32_e32 v3, v0
	v_mov_b32_e32 v4, v0
	v_mov_b32_e32 v5, v0
	v_mov_b32_e32 v6, v0
	v_mov_b32_e32 v7, v0
	v_mov_b32_e32 v16, v0
	v_mov_b32_e32 v17, v0
	v_mov_b32_e32 v18, v0
	v_mov_b32_e32 v19, v0
	v_mov_b32_e32 v20, v0
	v_mov_b32_e32 v21, v0
	v_mov_b32_e32 v22, v0
	v_mov_b32_e32 v23, v0
	v_mov_b32_e32 v32, v0
	v_mov_b32_e32 v33, v0
	v_mov_b32_e32 v34, v0
	v_mov_b32_e32 v35, v0
	v_mov_b32_e32 v36, v0
	v_mov_b32_e32 v37, v0
	v_mov_b32_e32 v38, v0
	v_mov_b32_e32 v39, v0
	v_mov_b32_e32 v48, v0
	v_mov_b32_e32 v49, v0
	v_mov_b32_e32 v50, v0
	v_mov_b32_e32 v51, v0
	v_mov_b32_e32 v52, v0
	v_mov_b32_e32 v53, v0
	v_mov_b32_e32 v54, v0
	v_mov_b32_e32 v55, v0
	v_mov_b32_e32 v8, v0
	v_mov_b32_e32 v9, v0
	v_mov_b32_e32 v10, v0
	v_mov_b32_e32 v11, v0
	v_mov_b32_e32 v12, v0
	v_mov_b32_e32 v13, v0
	v_mov_b32_e32 v14, v0
	v_mov_b32_e32 v15, v0
	v_mov_b32_e32 v24, v0
	v_mov_b32_e32 v25, v0
	v_mov_b32_e32 v26, v0
	v_mov_b32_e32 v27, v0
	v_mov_b32_e32 v28, v0
	v_mov_b32_e32 v29, v0
	v_mov_b32_e32 v30, v0
	v_mov_b32_e32 v31, v0
	v_mov_b32_e32 v40, v0
	v_mov_b32_e32 v41, v0
	v_mov_b32_e32 v42, v0
	v_mov_b32_e32 v43, v0
	v_mov_b32_e32 v44, v0
	v_mov_b32_e32 v45, v0
	v_mov_b32_e32 v46, v0
	v_mov_b32_e32 v47, v0
	v_mov_b32_e32 v56, v0
	v_mov_b32_e32 v57, v0
	v_mov_b32_e32 v58, v0
	v_mov_b32_e32 v59, v0
	v_mov_b32_e32 v60, v0
	v_mov_b32_e32 v61, v0
	v_mov_b32_e32 v62, v0
	v_mov_b32_e32 v63, v0
	v_mov_b32_e32 v64, v0
	v_mov_b32_e32 v65, v0
	v_mov_b32_e32 v66, v0
	v_mov_b32_e32 v67, v0
	v_mov_b32_e32 v68, v0
	v_mov_b32_e32 v69, v0
	v_mov_b32_e32 v70, v0
	v_mov_b32_e32 v71, v0
	v_mov_b32_e32 v80, v0
	v_mov_b32_e32 v81, v0
	v_mov_b32_e32 v82, v0
	v_mov_b32_e32 v83, v0
	v_mov_b32_e32 v84, v0
	v_mov_b32_e32 v85, v0
	v_mov_b32_e32 v86, v0
	v_mov_b32_e32 v87, v0
	v_mov_b32_e32 v96, v0
	v_mov_b32_e32 v97, v0
	v_mov_b32_e32 v98, v0
	v_mov_b32_e32 v99, v0
	v_mov_b32_e32 v100, v0
	v_mov_b32_e32 v101, v0
	v_mov_b32_e32 v102, v0
	v_mov_b32_e32 v103, v0
	v_mov_b32_e32 v112, v0
	v_mov_b32_e32 v113, v0
	v_mov_b32_e32 v114, v0
	v_mov_b32_e32 v115, v0
	v_mov_b32_e32 v116, v0
	v_mov_b32_e32 v117, v0
	v_mov_b32_e32 v118, v0
	v_mov_b32_e32 v119, v0
	v_mov_b32_e32 v72, v0
	v_mov_b32_e32 v73, v0
	v_mov_b32_e32 v74, v0
	v_mov_b32_e32 v75, v0
	v_mov_b32_e32 v76, v0
	v_mov_b32_e32 v77, v0
	v_mov_b32_e32 v78, v0
	v_mov_b32_e32 v79, v0
	v_mov_b32_e32 v88, v0
	v_mov_b32_e32 v89, v0
	v_mov_b32_e32 v90, v0
	v_mov_b32_e32 v91, v0
	v_mov_b32_e32 v92, v0
	v_mov_b32_e32 v93, v0
	v_mov_b32_e32 v94, v0
	v_mov_b32_e32 v95, v0
	v_mov_b32_e32 v104, v0
	v_mov_b32_e32 v105, v0
	v_mov_b32_e32 v106, v0
	v_mov_b32_e32 v107, v0
	v_mov_b32_e32 v108, v0
	v_mov_b32_e32 v109, v0
	v_mov_b32_e32 v110, v0
	v_mov_b32_e32 v111, v0
	v_mov_b32_e32 v120, v0
	v_mov_b32_e32 v121, v0
	v_mov_b32_e32 v122, v0
	v_mov_b32_e32 v123, v0
	v_mov_b32_e32 v124, v0
	v_mov_b32_e32 v125, v0
	v_mov_b32_e32 v126, v0
	v_mov_b32_e32 v127, v0
	v_readlane_b32 s100, v252, 21
	s_sub_u32 s100, s100, 0
	s_cmp_lt_u32 s100, 4
	s_cbranch_scc0 .Lprio_6
	s_setprio 1
.Lprio_6:
.LBB0_290:
	s_add_u32 s16, s14, 0xfffc0080
	s_addc_u32 s17, s15, -1
	s_add_i32 s42, 0, 0x10000
	s_cmp_eq_u32 s41, 12
	s_cselect_b32 s19, s1, s17
	s_cselect_b32 s18, s37, s16
	v_add_u32_e32 v147, s42, v145
	s_cselect_b32 s17, s9, s40
	s_cselect_b32 s16, s38, s39
	s_add_i32 s44, 0, 0x14000
	ds_read_b128 v[140:143], v147
	ds_read_b128 v[148:151], v147 offset:1024
	ds_read_b128 v[152:155], v147 offset:2048
	ds_read_b128 v[156:159], v147 offset:3072
	v_add_u32_e32 v147, s44, v145
	ds_read_b128 v[170:173], v147
	ds_read_b128 v[174:177], v147 offset:1024
	ds_read_b128 v[178:181], v147 offset:2048
	ds_read_b128 v[182:185], v147 offset:3072
	v_lshl_add_u64 v[166:167], s[14:15], 0, v[138:139]
	s_add_i32 m0, s23, 0xc000
	ds_read_b128 v[186:189], v146
	ds_read_b128 v[190:193], v146 offset:1024
	ds_read_b128 v[194:197], v146 offset:2048
	ds_read_b128 v[198:201], v146 offset:3072
	ds_read_b128 v[202:205], v146 offset:4096
	ds_read_b128 v[228:231], v146 offset:5120
	ds_read_b128 v[232:235], v146 offset:6144
	ds_read_b128 v[236:239], v146 offset:7168
	global_load_lds_dwordx4 v[166:167], off
	v_lshl_add_u64 v[166:167], s[14:15], 0, v[136:137]
	s_add_i32 m0, s23, 0xe000
	s_nop 0
	global_load_lds_dwordx4 v[166:167], off
	s_waitcnt vmcnt(8)
	s_waitcnt lgkmcnt(0)
	s_barrier
	s_waitcnt lgkmcnt(0)
	v_mfma_f32_16x16x32_bf16 v[124:127], v[140:143], v[186:189], v[124:127]
	v_mfma_f32_16x16x32_bf16 v[120:123], v[152:155], v[186:189], v[120:123]
	v_mfma_f32_16x16x32_bf16 v[108:111], v[140:143], v[194:197], v[108:111]
	v_mfma_f32_16x16x32_bf16 v[104:107], v[152:155], v[194:197], v[104:107]
	v_mfma_f32_16x16x32_bf16 v[92:95], v[140:143], v[202:205], v[92:95]
	v_mfma_f32_16x16x32_bf16 v[88:91], v[152:155], v[202:205], v[88:91]
	v_mfma_f32_16x16x32_bf16 v[76:79], v[140:143], v[232:235], v[76:79]
	v_mfma_f32_16x16x32_bf16 v[72:75], v[152:155], v[232:235], v[72:75]
	v_mfma_f32_16x16x32_bf16 v[124:127], v[148:151], v[190:193], v[124:127]
	v_mfma_f32_16x16x32_bf16 v[120:123], v[156:159], v[190:193], v[120:123]
	v_mfma_f32_16x16x32_bf16 v[108:111], v[148:151], v[198:201], v[108:111]
	v_mfma_f32_16x16x32_bf16 v[104:107], v[156:159], v[198:201], v[104:107]
	v_mfma_f32_16x16x32_bf16 v[92:95], v[148:151], v[228:231], v[92:95]
	v_mfma_f32_16x16x32_bf16 v[88:91], v[156:159], v[228:231], v[88:91]
	v_mfma_f32_16x16x32_bf16 v[76:79], v[148:151], v[236:239], v[76:79]
	v_mfma_f32_16x16x32_bf16 v[72:75], v[156:159], v[236:239], v[72:75]
	v_mfma_f32_16x16x32_bf16 v[116:119], v[170:173], v[186:189], v[116:119]
	v_mfma_f32_16x16x32_bf16 v[112:115], v[178:181], v[186:189], v[112:115]
	v_mfma_f32_16x16x32_bf16 v[100:103], v[170:173], v[194:197], v[100:103]
	v_mfma_f32_16x16x32_bf16 v[96:99], v[178:181], v[194:197], v[96:99]
	v_mfma_f32_16x16x32_bf16 v[84:87], v[170:173], v[202:205], v[84:87]
	v_mfma_f32_16x16x32_bf16 v[80:83], v[178:181], v[202:205], v[80:83]
	v_mfma_f32_16x16x32_bf16 v[68:71], v[170:173], v[232:235], v[68:71]
	v_mfma_f32_16x16x32_bf16 v[64:67], v[178:181], v[232:235], v[64:67]
	v_mfma_f32_16x16x32_bf16 v[116:119], v[174:177], v[190:193], v[116:119]
	v_mfma_f32_16x16x32_bf16 v[112:115], v[182:185], v[190:193], v[112:115]
	v_mfma_f32_16x16x32_bf16 v[100:103], v[174:177], v[198:201], v[100:103]
	v_mfma_f32_16x16x32_bf16 v[96:99], v[182:185], v[198:201], v[96:99]
	v_mfma_f32_16x16x32_bf16 v[84:87], v[174:177], v[228:231], v[84:87]
	v_mfma_f32_16x16x32_bf16 v[80:83], v[182:185], v[228:231], v[80:83]
	v_mfma_f32_16x16x32_bf16 v[68:71], v[174:177], v[236:239], v[68:71]
	v_mfma_f32_16x16x32_bf16 v[64:67], v[182:185], v[236:239], v[64:67]
	s_barrier
	s_add_i32 s42, s42, s77
	v_lshl_add_u64 v[166:167], s[16:17], 0, v[160:161]
	s_mov_b32 m0, s42
	ds_read_b128 v[186:189], v146 offset:16384
	ds_read_b128 v[190:193], v146 offset:17408
	ds_read_b128 v[194:197], v146 offset:18432
	ds_read_b128 v[198:201], v146 offset:19456
	ds_read_b128 v[202:205], v146 offset:20480
	ds_read_b128 v[228:231], v146 offset:21504
	ds_read_b128 v[232:235], v146 offset:22528
	ds_read_b128 v[236:239], v146 offset:23552
	global_load_lds_dwordx4 v[166:167], off
	s_add_i32 m0, s42, 0x2000
	s_add_u32 s42, s16, 0x40000
	v_lshl_add_u64 v[168:169], s[16:17], 0, v[128:129]
	s_addc_u32 s43, s17, 0
	s_add_i32 s44, s44, s77
	global_load_lds_dwordx4 v[168:169], off
	v_lshl_add_u64 v[206:207], s[42:43], 0, v[160:161]
	s_mov_b32 m0, s44
	v_lshl_add_u64 v[240:241], s[18:19], 0, v[130:131]
	global_load_lds_dwordx4 v[206:207], off
	v_lshl_add_u64 v[206:207], s[42:43], 0, v[128:129]
	s_add_i32 m0, s44, 0x2000
	s_nop 0
	global_load_lds_dwordx4 v[206:207], off
	v_lshl_add_u64 v[206:207], s[18:19], 0, v[132:133]
	s_mov_b32 m0, s23
	s_nop 0
	global_load_lds_dwordx4 v[206:207], off
	s_mov_b32 m0, s24
	s_nop 0
	global_load_lds_dwordx4 v[240:241], off
	s_waitcnt vmcnt(8)
	s_waitcnt lgkmcnt(0)
	s_barrier
	s_waitcnt lgkmcnt(0)
	v_mfma_f32_16x16x32_bf16 v[60:63], v[140:143], v[186:189], v[60:63]
	v_mfma_f32_16x16x32_bf16 v[56:59], v[152:155], v[186:189], v[56:59]
	v_mfma_f32_16x16x32_bf16 v[44:47], v[140:143], v[194:197], v[44:47]
	v_mfma_f32_16x16x32_bf16 v[40:43], v[152:155], v[194:197], v[40:43]
	v_mfma_f32_16x16x32_bf16 v[28:31], v[140:143], v[202:205], v[28:31]
	v_mfma_f32_16x16x32_bf16 v[24:27], v[152:155], v[202:205], v[24:27]
	v_mfma_f32_16x16x32_bf16 v[12:15], v[140:143], v[232:235], v[12:15]
	v_mfma_f32_16x16x32_bf16 v[8:11], v[152:155], v[232:235], v[8:11]
	v_mfma_f32_16x16x32_bf16 v[60:63], v[148:151], v[190:193], v[60:63]
	v_mfma_f32_16x16x32_bf16 v[56:59], v[156:159], v[190:193], v[56:59]
	v_mfma_f32_16x16x32_bf16 v[44:47], v[148:151], v[198:201], v[44:47]
	v_mfma_f32_16x16x32_bf16 v[40:43], v[156:159], v[198:201], v[40:43]
	v_mfma_f32_16x16x32_bf16 v[28:31], v[148:151], v[228:231], v[28:31]
	v_mfma_f32_16x16x32_bf16 v[24:27], v[156:159], v[228:231], v[24:27]
	v_mfma_f32_16x16x32_bf16 v[12:15], v[148:151], v[236:239], v[12:15]
	v_mfma_f32_16x16x32_bf16 v[8:11], v[156:159], v[236:239], v[8:11]
	v_mfma_f32_16x16x32_bf16 v[52:55], v[170:173], v[186:189], v[52:55]
	v_mfma_f32_16x16x32_bf16 v[48:51], v[178:181], v[186:189], v[48:51]
	v_mfma_f32_16x16x32_bf16 v[36:39], v[170:173], v[194:197], v[36:39]
	v_mfma_f32_16x16x32_bf16 v[32:35], v[178:181], v[194:197], v[32:35]
	v_mfma_f32_16x16x32_bf16 v[20:23], v[170:173], v[202:205], v[20:23]
	v_mfma_f32_16x16x32_bf16 v[16:19], v[178:181], v[202:205], v[16:19]
	v_mfma_f32_16x16x32_bf16 v[4:7], v[170:173], v[232:235], v[4:7]
	v_mfma_f32_16x16x32_bf16 v[0:3], v[178:181], v[232:235], v[0:3]
	v_mfma_f32_16x16x32_bf16 v[52:55], v[174:177], v[190:193], v[52:55]
	v_mfma_f32_16x16x32_bf16 v[48:51], v[182:185], v[190:193], v[48:51]
	v_mfma_f32_16x16x32_bf16 v[36:39], v[174:177], v[198:201], v[36:39]
	v_mfma_f32_16x16x32_bf16 v[32:35], v[182:185], v[198:201], v[32:35]
	v_mfma_f32_16x16x32_bf16 v[20:23], v[174:177], v[228:231], v[20:23]
	v_mfma_f32_16x16x32_bf16 v[16:19], v[182:185], v[228:231], v[16:19]
	v_mfma_f32_16x16x32_bf16 v[4:7], v[174:177], v[236:239], v[4:7]
	v_mfma_f32_16x16x32_bf16 v[0:3], v[182:185], v[236:239], v[0:3]
	s_barrier
	s_add_i32 s42, 0, 0x18000
	v_add_u32_e32 v147, s42, v145
	s_add_i32 s43, 0, 0x1c000
	ds_read_b128 v[140:143], v147
	ds_read_b128 v[148:151], v147 offset:1024
	ds_read_b128 v[152:155], v147 offset:2048
	ds_read_b128 v[156:159], v147 offset:3072
	v_add_u32_e32 v147, s43, v145
	ds_read_b128 v[170:173], v147
	ds_read_b128 v[174:177], v147 offset:1024
	ds_read_b128 v[178:181], v147 offset:2048
	ds_read_b128 v[182:185], v147 offset:3072
	s_add_u32 s18, s18, 0x40000
	s_addc_u32 s19, s19, 0
	s_mov_b32 m0, s25
	v_lshl_add_u64 v[242:243], s[18:19], 0, v[132:133]
	ds_read_b128 v[186:189], v146 offset:32768
	ds_read_b128 v[190:193], v146 offset:33792
	ds_read_b128 v[194:197], v146 offset:34816
	ds_read_b128 v[198:201], v146 offset:35840
	ds_read_b128 v[202:205], v146 offset:36864
	ds_read_b128 v[228:231], v146 offset:37888
	ds_read_b128 v[232:235], v146 offset:38912
	ds_read_b128 v[236:239], v146 offset:39936
	global_load_lds_dwordx4 v[242:243], off
	v_lshl_add_u64 v[242:243], s[18:19], 0, v[130:131]
	s_mov_b32 m0, s26
	s_nop 0
	global_load_lds_dwordx4 v[242:243], off
	s_waitcnt vmcnt(8)
	s_waitcnt lgkmcnt(0)
	s_barrier
	s_waitcnt lgkmcnt(0)
	v_mfma_f32_16x16x32_bf16 v[124:127], v[140:143], v[186:189], v[124:127]
	v_mfma_f32_16x16x32_bf16 v[120:123], v[152:155], v[186:189], v[120:123]
	v_mfma_f32_16x16x32_bf16 v[108:111], v[140:143], v[194:197], v[108:111]
	v_mfma_f32_16x16x32_bf16 v[104:107], v[152:155], v[194:197], v[104:107]
	v_mfma_f32_16x16x32_bf16 v[92:95], v[140:143], v[202:205], v[92:95]
	v_mfma_f32_16x16x32_bf16 v[88:91], v[152:155], v[202:205], v[88:91]
	v_mfma_f32_16x16x32_bf16 v[76:79], v[140:143], v[232:235], v[76:79]
	v_mfma_f32_16x16x32_bf16 v[72:75], v[152:155], v[232:235], v[72:75]
	v_mfma_f32_16x16x32_bf16 v[124:127], v[148:151], v[190:193], v[124:127]
	v_mfma_f32_16x16x32_bf16 v[120:123], v[156:159], v[190:193], v[120:123]
	v_mfma_f32_16x16x32_bf16 v[108:111], v[148:151], v[198:201], v[108:111]
	v_mfma_f32_16x16x32_bf16 v[104:107], v[156:159], v[198:201], v[104:107]
	v_mfma_f32_16x16x32_bf16 v[92:95], v[148:151], v[228:231], v[92:95]
	v_mfma_f32_16x16x32_bf16 v[88:91], v[156:159], v[228:231], v[88:91]
	v_mfma_f32_16x16x32_bf16 v[76:79], v[148:151], v[236:239], v[76:79]
	v_mfma_f32_16x16x32_bf16 v[72:75], v[156:159], v[236:239], v[72:75]
	v_mfma_f32_16x16x32_bf16 v[116:119], v[170:173], v[186:189], v[116:119]
	v_mfma_f32_16x16x32_bf16 v[112:115], v[178:181], v[186:189], v[112:115]
	v_mfma_f32_16x16x32_bf16 v[100:103], v[170:173], v[194:197], v[100:103]
	v_mfma_f32_16x16x32_bf16 v[96:99], v[178:181], v[194:197], v[96:99]
	v_mfma_f32_16x16x32_bf16 v[84:87], v[170:173], v[202:205], v[84:87]
	v_mfma_f32_16x16x32_bf16 v[80:83], v[178:181], v[202:205], v[80:83]
	v_mfma_f32_16x16x32_bf16 v[68:71], v[170:173], v[232:235], v[68:71]
	v_mfma_f32_16x16x32_bf16 v[64:67], v[178:181], v[232:235], v[64:67]
	v_mfma_f32_16x16x32_bf16 v[116:119], v[174:177], v[190:193], v[116:119]
	v_mfma_f32_16x16x32_bf16 v[112:115], v[182:185], v[190:193], v[112:115]
	v_mfma_f32_16x16x32_bf16 v[100:103], v[174:177], v[198:201], v[100:103]
	v_mfma_f32_16x16x32_bf16 v[96:99], v[182:185], v[198:201], v[96:99]
	v_mfma_f32_16x16x32_bf16 v[84:87], v[174:177], v[228:231], v[84:87]
	v_mfma_f32_16x16x32_bf16 v[80:83], v[182:185], v[228:231], v[80:83]
	v_mfma_f32_16x16x32_bf16 v[68:71], v[174:177], v[236:239], v[68:71]
	v_mfma_f32_16x16x32_bf16 v[64:67], v[182:185], v[236:239], v[64:67]
	s_barrier
	s_add_i32 s18, s42, s77
	v_lshl_add_u64 v[166:167], v[166:167], 0, s[96:97]
	s_mov_b32 m0, s18
	ds_read_b128 v[186:189], v146 offset:49152
	ds_read_b128 v[190:193], v146 offset:50176
	ds_read_b128 v[194:197], v146 offset:51200
	ds_read_b128 v[198:201], v146 offset:52224
	ds_read_b128 v[202:205], v146 offset:53248
	ds_read_b128 v[228:231], v146 offset:54272
	ds_read_b128 v[232:235], v146 offset:55296
	ds_read_b128 v[236:239], v146 offset:56320
	global_load_lds_dwordx4 v[166:167], off
	s_add_i32 m0, s18, 0x2000
	s_add_u32 s16, s16, 0x40080
	v_lshl_add_u64 v[166:167], v[168:169], 0, s[96:97]
	s_addc_u32 s17, s17, 0
	s_add_i32 s18, s43, s77
	global_load_lds_dwordx4 v[166:167], off
	v_lshl_add_u64 v[166:167], s[16:17], 0, v[160:161]
	s_mov_b32 m0, s18
	s_nop 0
	global_load_lds_dwordx4 v[166:167], off
	v_lshl_add_u64 v[166:167], s[16:17], 0, v[128:129]
	s_add_i32 m0, s18, 0x2000
	s_nop 0
	global_load_lds_dwordx4 v[166:167], off
	v_lshl_add_u64 v[166:167], v[206:207], 0, s[96:97]
	s_mov_b32 m0, s31
	s_nop 0
	global_load_lds_dwordx4 v[166:167], off
	v_lshl_add_u64 v[166:167], v[240:241], 0, s[96:97]
	s_mov_b32 m0, s34
	s_nop 0
	global_load_lds_dwordx4 v[166:167], off
	s_waitcnt vmcnt(8)
	s_waitcnt lgkmcnt(0)
	s_barrier
	s_waitcnt lgkmcnt(0)
	v_mfma_f32_16x16x32_bf16 v[60:63], v[140:143], v[186:189], v[60:63]
	v_mfma_f32_16x16x32_bf16 v[56:59], v[152:155], v[186:189], v[56:59]
	v_mfma_f32_16x16x32_bf16 v[44:47], v[140:143], v[194:197], v[44:47]
	v_mfma_f32_16x16x32_bf16 v[40:43], v[152:155], v[194:197], v[40:43]
	v_mfma_f32_16x16x32_bf16 v[28:31], v[140:143], v[202:205], v[28:31]
	v_mfma_f32_16x16x32_bf16 v[24:27], v[152:155], v[202:205], v[24:27]
	v_mfma_f32_16x16x32_bf16 v[12:15], v[140:143], v[232:235], v[12:15]
	v_mfma_f32_16x16x32_bf16 v[8:11], v[152:155], v[232:235], v[8:11]
	v_mfma_f32_16x16x32_bf16 v[60:63], v[148:151], v[190:193], v[60:63]
	v_mfma_f32_16x16x32_bf16 v[56:59], v[156:159], v[190:193], v[56:59]
	v_mfma_f32_16x16x32_bf16 v[44:47], v[148:151], v[198:201], v[44:47]
	v_mfma_f32_16x16x32_bf16 v[40:43], v[156:159], v[198:201], v[40:43]
	v_mfma_f32_16x16x32_bf16 v[28:31], v[148:151], v[228:231], v[28:31]
	v_mfma_f32_16x16x32_bf16 v[24:27], v[156:159], v[228:231], v[24:27]
	v_mfma_f32_16x16x32_bf16 v[12:15], v[148:151], v[236:239], v[12:15]
	v_mfma_f32_16x16x32_bf16 v[8:11], v[156:159], v[236:239], v[8:11]
	v_mfma_f32_16x16x32_bf16 v[52:55], v[170:173], v[186:189], v[52:55]
	v_mfma_f32_16x16x32_bf16 v[48:51], v[178:181], v[186:189], v[48:51]
	v_mfma_f32_16x16x32_bf16 v[36:39], v[170:173], v[194:197], v[36:39]
	v_mfma_f32_16x16x32_bf16 v[32:35], v[178:181], v[194:197], v[32:35]
	v_mfma_f32_16x16x32_bf16 v[20:23], v[170:173], v[202:205], v[20:23]
	v_mfma_f32_16x16x32_bf16 v[16:19], v[178:181], v[202:205], v[16:19]
	v_mfma_f32_16x16x32_bf16 v[4:7], v[170:173], v[232:235], v[4:7]
	v_mfma_f32_16x16x32_bf16 v[0:3], v[178:181], v[232:235], v[0:3]
	v_mfma_f32_16x16x32_bf16 v[52:55], v[174:177], v[190:193], v[52:55]
	v_mfma_f32_16x16x32_bf16 v[48:51], v[182:185], v[190:193], v[48:51]
	v_mfma_f32_16x16x32_bf16 v[36:39], v[174:177], v[198:201], v[36:39]
	v_mfma_f32_16x16x32_bf16 v[32:35], v[182:185], v[198:201], v[32:35]
	v_mfma_f32_16x16x32_bf16 v[20:23], v[174:177], v[228:231], v[20:23]
	v_mfma_f32_16x16x32_bf16 v[16:19], v[182:185], v[228:231], v[16:19]
	v_mfma_f32_16x16x32_bf16 v[4:7], v[174:177], v[236:239], v[4:7]
	v_mfma_f32_16x16x32_bf16 v[0:3], v[182:185], v[236:239], v[0:3]
	s_barrier
	s_add_i32 s41, s41, 2
	s_add_u32 s39, s39, 0x100
	s_addc_u32 s40, s40, 0
	s_add_u32 s14, s14, 0x100
	s_addc_u32 s15, s15, 0
	s_cmp_gt_u32 s41, 13
	s_cbranch_scc0 .LBB0_290
	s_setprio 0
	v_readlane_b32 s14, v253, 23
	v_readlane_b32 s15, v253, 24
	s_and_b64 vcc, exec, s[14:15]
	s_cbranch_vccz .LBB0_293
	s_barrier

.LBB0_482:
	s_ashr_i32 s11, s10, 31
	s_lshl_b64 s[12:13], s[10:11], 19
	s_add_u32 s12, s20, s12
	s_addc_u32 s13, s21, s13
	s_and_b64 s[14:15], s[6:7], exec
	s_cselect_b32 s11, s13, s17
	s_cselect_b32 s34, s12, s16
	s_ashr_i32 s1, s0, 31
	s_lshl_b64 s[14:15], s[0:1], 19
	v_readlane_b32 s1, v252, 29
	s_add_u32 s14, s1, s14
	v_readlane_b32 s1, v252, 30
	s_addc_u32 s15, s1, s15
	s_and_b64 s[18:19], s[6:7], exec
	s_cselect_b32 s1, s15, s9
	s_cselect_b32 s35, s14, s8
	s_add_u32 s36, s8, 0x100
	s_addc_u32 s37, s9, 0
	s_add_u32 s8, s16, 0x40080
	v_mov_b32_e32 v0, 0
	s_addc_u32 s9, s17, 0
	s_mov_b32 s38, -2
	v_mov_b32_e32 v1, v0
	v_mov_b32_e32 v2, v0
	v_mov_b32_e32 v3, v0
	v_mov_b32_e32 v4, v0
	v_mov_b32_e32 v5, v0
	v_mov_b32_e32 v6, v0
	v_mov_b32_e32 v7, v0
	v_mov_b32_e32 v16, v0
	v_mov_b32_e32 v17, v0
	v_mov_b32_e32 v18, v0
	v_mov_b32_e32 v19, v0
	v_mov_b32_e32 v20, v0
	v_mov_b32_e32 v21, v0
	v_mov_b32_e32 v22, v0
	v_mov_b32_e32 v23, v0
	v_mov_b32_e32 v32, v0
	v_mov_b32_e32 v33, v0
	v_mov_b32_e32 v34, v0
	v_mov_b32_e32 v35, v0
	v_mov_b32_e32 v36, v0
	v_mov_b32_e32 v37, v0
	v_mov_b32_e32 v38, v0
	v_mov_b32_e32 v39, v0
	v_mov_b32_e32 v48, v0
	v_mov_b32_e32 v49, v0
	v_mov_b32_e32 v50, v0
	v_mov_b32_e32 v51, v0
	v_mov_b32_e32 v52, v0
	v_mov_b32_e32 v53, v0
	v_mov_b32_e32 v54, v0
	v_mov_b32_e32 v55, v0
	v_mov_b32_e32 v8, v0
	v_mov_b32_e32 v9, v0
	v_mov_b32_e32 v10, v0
	v_mov_b32_e32 v11, v0
	v_mov_b32_e32 v12, v0
	v_mov_b32_e32 v13, v0
	v_mov_b32_e32 v14, v0
	v_mov_b32_e32 v15, v0
	v_mov_b32_e32 v24, v0
	v_mov_b32_e32 v25, v0
	v_mov_b32_e32 v26, v0
	v_mov_b32_e32 v27, v0
	v_mov_b32_e32 v28, v0
	v_mov_b32_e32 v29, v0
	v_mov_b32_e32 v30, v0
	v_mov_b32_e32 v31, v0
	v_mov_b32_e32 v40, v0
	v_mov_b32_e32 v41, v0
	v_mov_b32_e32 v42, v0
	v_mov_b32_e32 v43, v0
	v_mov_b32_e32 v44, v0
	v_mov_b32_e32 v45, v0
	v_mov_b32_e32 v46, v0
	v_mov_b32_e32 v47, v0
	v_mov_b32_e32 v56, v0
	v_mov_b32_e32 v57, v0
	v_mov_b32_e32 v58, v0
	v_mov_b32_e32 v59, v0
	v_mov_b32_e32 v60, v0
	v_mov_b32_e32 v61, v0
	v_mov_b32_e32 v62, v0
	v_mov_b32_e32 v63, v0
	v_mov_b32_e32 v64, v0
	v_mov_b32_e32 v65, v0
	v_mov_b32_e32 v66, v0
	v_mov_b32_e32 v67, v0
	v_mov_b32_e32 v68, v0
	v_mov_b32_e32 v69, v0
	v_mov_b32_e32 v70, v0
	v_mov_b32_e32 v71, v0
	v_mov_b32_e32 v80, v0
	v_mov_b32_e32 v81, v0
	v_mov_b32_e32 v82, v0
	v_mov_b32_e32 v83, v0
	v_mov_b32_e32 v84, v0
	v_mov_b32_e32 v85, v0
	v_mov_b32_e32 v86, v0
	v_mov_b32_e32 v87, v0
	v_mov_b32_e32 v96, v0
	v_mov_b32_e32 v97, v0
	v_mov_b32_e32 v98, v0
	v_mov_b32_e32 v99, v0
	v_mov_b32_e32 v100, v0
	v_mov_b32_e32 v101, v0
	v_mov_b32_e32 v102, v0
	v_mov_b32_e32 v103, v0
	v_mov_b32_e32 v112, v0
	v_mov_b32_e32 v113, v0
	v_mov_b32_e32 v114, v0
	v_mov_b32_e32 v115, v0
	v_mov_b32_e32 v116, v0
	v_mov_b32_e32 v117, v0
	v_mov_b32_e32 v118, v0
	v_mov_b32_e32 v119, v0
	v_mov_b32_e32 v72, v0
	v_mov_b32_e32 v73, v0
	v_mov_b32_e32 v74, v0
	v_mov_b32_e32 v75, v0
	v_mov_b32_e32 v76, v0
	v_mov_b32_e32 v77, v0
	v_mov_b32_e32 v78, v0
	v_mov_b32_e32 v79, v0
	v_mov_b32_e32 v88, v0
	v_mov_b32_e32 v89, v0
	v_mov_b32_e32 v90, v0
	v_mov_b32_e32 v91, v0
	v_mov_b32_e32 v92, v0
	v_mov_b32_e32 v93, v0
	v_mov_b32_e32 v94, v0
	v_mov_b32_e32 v95, v0
	v_mov_b32_e32 v104, v0
	v_mov_b32_e32 v105, v0
	v_mov_b32_e32 v106, v0
	v_mov_b32_e32 v107, v0
	v_mov_b32_e32 v108, v0
	v_mov_b32_e32 v109, v0
	v_mov_b32_e32 v110, v0
	v_mov_b32_e32 v111, v0
	v_mov_b32_e32 v120, v0
	v_mov_b32_e32 v121, v0
	v_mov_b32_e32 v122, v0
	v_mov_b32_e32 v123, v0
	v_mov_b32_e32 v124, v0
	v_mov_b32_e32 v125, v0
	v_mov_b32_e32 v126, v0
	v_mov_b32_e32 v127, v0
	v_readlane_b32 s100, v252, 21
	s_sub_u32 s100, s100, 0
	s_cmp_lt_u32 s100, 4
	s_cbranch_scc0 .Lprio_8
	s_setprio 1
.Lprio_8:
.LBB0_483:
	s_add_u32 s16, s8, 0xfffc0080
	s_addc_u32 s17, s9, -1
	s_add_i32 s39, 0, 0x10000
	s_cmp_eq_u32 s38, 12
	s_cselect_b32 s19, s11, s17
	s_cselect_b32 s18, s34, s16
	s_cselect_b32 s17, s1, s37
	s_cselect_b32 s16, s35, s36
	s_add_i32 s42, 0, 0x14000
	v_add_u32_e32 v140, s39, v229
	v_add_u32_e32 v156, s42, v229
	ds_read_b128 v[128:131], v140
	ds_read_b128 v[132:135], v140 offset:1024
	ds_read_b128 v[136:139], v140 offset:2048
	ds_read_b128 v[140:143], v140 offset:3072
	ds_read_b128 v[144:147], v156
	ds_read_b128 v[148:151], v156 offset:1024
	ds_read_b128 v[152:155], v156 offset:2048
	ds_read_b128 v[156:159], v156 offset:3072
	v_lshl_add_u64 v[206:207], s[8:9], 0, v[188:189]
	s_add_i32 m0, s22, 0xc000
	ds_read_b128 v[190:193], v230
	ds_read_b128 v[194:197], v230 offset:1024
	ds_read_b128 v[198:201], v230 offset:2048
	ds_read_b128 v[202:205], v230 offset:3072
	ds_read_b128 v[232:235], v230 offset:4096
	ds_read_b128 v[236:239], v230 offset:5120
	ds_read_b128 v[240:243], v230 offset:6144
	ds_read_b128 v[244:247], v230 offset:7168
	global_load_lds_dwordx4 v[206:207], off
	v_lshl_add_u64 v[206:207], s[8:9], 0, v[186:187]
	s_add_i32 m0, s22, 0xe000
	s_nop 0
	global_load_lds_dwordx4 v[206:207], off
	s_waitcnt vmcnt(8)
	s_waitcnt lgkmcnt(0)
	s_barrier
	s_waitcnt lgkmcnt(0)
	v_mfma_f32_16x16x32_bf16 v[124:127], v[128:131], v[190:193], v[124:127]
	v_mfma_f32_16x16x32_bf16 v[120:123], v[136:139], v[190:193], v[120:123]
	v_mfma_f32_16x16x32_bf16 v[108:111], v[128:131], v[198:201], v[108:111]
	v_mfma_f32_16x16x32_bf16 v[104:107], v[136:139], v[198:201], v[104:107]
	v_mfma_f32_16x16x32_bf16 v[92:95], v[128:131], v[232:235], v[92:95]
	v_mfma_f32_16x16x32_bf16 v[88:91], v[136:139], v[232:235], v[88:91]
	v_mfma_f32_16x16x32_bf16 v[76:79], v[128:131], v[240:243], v[76:79]
	v_mfma_f32_16x16x32_bf16 v[72:75], v[136:139], v[240:243], v[72:75]
	v_mfma_f32_16x16x32_bf16 v[124:127], v[132:135], v[194:197], v[124:127]
	v_mfma_f32_16x16x32_bf16 v[120:123], v[140:143], v[194:197], v[120:123]
	v_mfma_f32_16x16x32_bf16 v[108:111], v[132:135], v[202:205], v[108:111]
	v_mfma_f32_16x16x32_bf16 v[104:107], v[140:143], v[202:205], v[104:107]
	v_mfma_f32_16x16x32_bf16 v[92:95], v[132:135], v[236:239], v[92:95]
	v_mfma_f32_16x16x32_bf16 v[88:91], v[140:143], v[236:239], v[88:91]
	v_mfma_f32_16x16x32_bf16 v[76:79], v[132:135], v[244:247], v[76:79]
	v_mfma_f32_16x16x32_bf16 v[72:75], v[140:143], v[244:247], v[72:75]
	v_mfma_f32_16x16x32_bf16 v[116:119], v[144:147], v[190:193], v[116:119]
	v_mfma_f32_16x16x32_bf16 v[112:115], v[152:155], v[190:193], v[112:115]
	v_mfma_f32_16x16x32_bf16 v[100:103], v[144:147], v[198:201], v[100:103]
	v_mfma_f32_16x16x32_bf16 v[96:99], v[152:155], v[198:201], v[96:99]
	v_mfma_f32_16x16x32_bf16 v[84:87], v[144:147], v[232:235], v[84:87]
	v_mfma_f32_16x16x32_bf16 v[80:83], v[152:155], v[232:235], v[80:83]
	v_mfma_f32_16x16x32_bf16 v[68:71], v[144:147], v[240:243], v[68:71]
	v_mfma_f32_16x16x32_bf16 v[64:67], v[152:155], v[240:243], v[64:67]
	v_mfma_f32_16x16x32_bf16 v[116:119], v[148:151], v[194:197], v[116:119]
	v_mfma_f32_16x16x32_bf16 v[112:115], v[156:159], v[194:197], v[112:115]
	v_mfma_f32_16x16x32_bf16 v[100:103], v[148:151], v[202:205], v[100:103]
	v_mfma_f32_16x16x32_bf16 v[96:99], v[156:159], v[202:205], v[96:99]
	v_mfma_f32_16x16x32_bf16 v[84:87], v[148:151], v[236:239], v[84:87]
	v_mfma_f32_16x16x32_bf16 v[80:83], v[156:159], v[236:239], v[80:83]
	v_mfma_f32_16x16x32_bf16 v[68:71], v[148:151], v[244:247], v[68:71]
	v_mfma_f32_16x16x32_bf16 v[64:67], v[156:159], v[244:247], v[64:67]
	s_barrier
	s_add_i32 s39, s39, s77
	v_lshl_add_u64 v[206:207], s[16:17], 0, v[174:175]
	s_mov_b32 m0, s39
	ds_read_b128 v[190:193], v230 offset:16384
	ds_read_b128 v[194:197], v230 offset:17408
	ds_read_b128 v[198:201], v230 offset:18432
	ds_read_b128 v[202:205], v230 offset:19456
	ds_read_b128 v[232:235], v230 offset:20480
	ds_read_b128 v[236:239], v230 offset:21504
	ds_read_b128 v[240:243], v230 offset:22528
	ds_read_b128 v[244:247], v230 offset:23552
	global_load_lds_dwordx4 v[206:207], off
	s_add_i32 m0, s39, 0x2000
	s_add_u32 s40, s16, 0x40000
	v_lshl_add_u64 v[248:249], s[16:17], 0, v[170:171]
	s_addc_u32 s41, s17, 0
	s_add_i32 s39, s42, s77
	global_load_lds_dwordx4 v[248:249], off
	v_lshl_add_u64 v[250:251], s[40:41], 0, v[174:175]
	s_mov_b32 m0, s39
	v_lshl_add_u64 v[166:167], s[18:19], 0, v[172:173]
	global_load_lds_dwordx4 v[250:251], off
	v_lshl_add_u64 v[250:251], s[40:41], 0, v[170:171]
	s_add_i32 m0, s39, 0x2000
	s_nop 0
	global_load_lds_dwordx4 v[250:251], off
	v_lshl_add_u64 v[250:251], s[18:19], 0, v[176:177]
	s_mov_b32 m0, s22
	s_nop 0
	global_load_lds_dwordx4 v[250:251], off
	s_mov_b32 m0, s23
	s_nop 0
	global_load_lds_dwordx4 v[166:167], off
	s_waitcnt vmcnt(8)
	s_waitcnt lgkmcnt(0)
	s_barrier
	s_waitcnt lgkmcnt(0)
	v_mfma_f32_16x16x32_bf16 v[60:63], v[128:131], v[190:193], v[60:63]
	v_mfma_f32_16x16x32_bf16 v[56:59], v[136:139], v[190:193], v[56:59]
	v_mfma_f32_16x16x32_bf16 v[44:47], v[128:131], v[198:201], v[44:47]
	v_mfma_f32_16x16x32_bf16 v[40:43], v[136:139], v[198:201], v[40:43]
	v_mfma_f32_16x16x32_bf16 v[28:31], v[128:131], v[232:235], v[28:31]
	v_mfma_f32_16x16x32_bf16 v[24:27], v[136:139], v[232:235], v[24:27]
	v_mfma_f32_16x16x32_bf16 v[12:15], v[128:131], v[240:243], v[12:15]
	v_mfma_f32_16x16x32_bf16 v[8:11], v[136:139], v[240:243], v[8:11]
	v_mfma_f32_16x16x32_bf16 v[60:63], v[132:135], v[194:197], v[60:63]
	v_mfma_f32_16x16x32_bf16 v[56:59], v[140:143], v[194:197], v[56:59]
	v_mfma_f32_16x16x32_bf16 v[44:47], v[132:135], v[202:205], v[44:47]
	v_mfma_f32_16x16x32_bf16 v[40:43], v[140:143], v[202:205], v[40:43]
	v_mfma_f32_16x16x32_bf16 v[28:31], v[132:135], v[236:239], v[28:31]
	v_mfma_f32_16x16x32_bf16 v[24:27], v[140:143], v[236:239], v[24:27]
	v_mfma_f32_16x16x32_bf16 v[12:15], v[132:135], v[244:247], v[12:15]
	v_mfma_f32_16x16x32_bf16 v[8:11], v[140:143], v[244:247], v[8:11]
	v_mfma_f32_16x16x32_bf16 v[52:55], v[144:147], v[190:193], v[52:55]
	v_mfma_f32_16x16x32_bf16 v[48:51], v[152:155], v[190:193], v[48:51]
	v_mfma_f32_16x16x32_bf16 v[36:39], v[144:147], v[198:201], v[36:39]
	v_mfma_f32_16x16x32_bf16 v[32:35], v[152:155], v[198:201], v[32:35]
	v_mfma_f32_16x16x32_bf16 v[20:23], v[144:147], v[232:235], v[20:23]
	v_mfma_f32_16x16x32_bf16 v[16:19], v[152:155], v[232:235], v[16:19]
	v_mfma_f32_16x16x32_bf16 v[4:7], v[144:147], v[240:243], v[4:7]
	v_mfma_f32_16x16x32_bf16 v[0:3], v[152:155], v[240:243], v[0:3]
	v_mfma_f32_16x16x32_bf16 v[52:55], v[148:151], v[194:197], v[52:55]
	v_mfma_f32_16x16x32_bf16 v[48:51], v[156:159], v[194:197], v[48:51]
	v_mfma_f32_16x16x32_bf16 v[36:39], v[148:151], v[202:205], v[36:39]
	v_mfma_f32_16x16x32_bf16 v[32:35], v[156:159], v[202:205], v[32:35]
	v_mfma_f32_16x16x32_bf16 v[20:23], v[148:151], v[236:239], v[20:23]
	v_mfma_f32_16x16x32_bf16 v[16:19], v[156:159], v[236:239], v[16:19]
	v_mfma_f32_16x16x32_bf16 v[4:7], v[148:151], v[244:247], v[4:7]
	v_mfma_f32_16x16x32_bf16 v[0:3], v[156:159], v[244:247], v[0:3]
	s_barrier
	s_add_i32 s39, 0, 0x18000
	s_add_i32 s40, 0, 0x1c000
	v_add_u32_e32 v140, s39, v229
	v_add_u32_e32 v156, s40, v229
	ds_read_b128 v[128:131], v140
	ds_read_b128 v[132:135], v140 offset:1024
	ds_read_b128 v[136:139], v140 offset:2048
	ds_read_b128 v[140:143], v140 offset:3072
	ds_read_b128 v[144:147], v156
	ds_read_b128 v[148:151], v156 offset:1024
	ds_read_b128 v[152:155], v156 offset:2048
	ds_read_b128 v[156:159], v156 offset:3072
	s_add_u32 s18, s18, 0x40000
	s_addc_u32 s19, s19, 0
	s_mov_b32 m0, s24
	v_lshl_add_u64 v[168:169], s[18:19], 0, v[176:177]
	ds_read_b128 v[190:193], v230 offset:32768
	ds_read_b128 v[194:197], v230 offset:33792
	ds_read_b128 v[198:201], v230 offset:34816
	ds_read_b128 v[202:205], v230 offset:35840
	ds_read_b128 v[232:235], v230 offset:36864
	ds_read_b128 v[236:239], v230 offset:37888
	ds_read_b128 v[240:243], v230 offset:38912
	ds_read_b128 v[244:247], v230 offset:39936
	global_load_lds_dwordx4 v[168:169], off
	v_lshl_add_u64 v[168:169], s[18:19], 0, v[172:173]
	s_mov_b32 m0, s25
	s_nop 0
	global_load_lds_dwordx4 v[168:169], off
	s_waitcnt vmcnt(8)
	s_waitcnt lgkmcnt(0)
	s_barrier
	s_waitcnt lgkmcnt(0)
	v_mfma_f32_16x16x32_bf16 v[124:127], v[128:131], v[190:193], v[124:127]
	v_mfma_f32_16x16x32_bf16 v[120:123], v[136:139], v[190:193], v[120:123]
	v_mfma_f32_16x16x32_bf16 v[108:111], v[128:131], v[198:201], v[108:111]
	v_mfma_f32_16x16x32_bf16 v[104:107], v[136:139], v[198:201], v[104:107]
	v_mfma_f32_16x16x32_bf16 v[92:95], v[128:131], v[232:235], v[92:95]
	v_mfma_f32_16x16x32_bf16 v[88:91], v[136:139], v[232:235], v[88:91]
	v_mfma_f32_16x16x32_bf16 v[76:79], v[128:131], v[240:243], v[76:79]
	v_mfma_f32_16x16x32_bf16 v[72:75], v[136:139], v[240:243], v[72:75]
	v_mfma_f32_16x16x32_bf16 v[124:127], v[132:135], v[194:197], v[124:127]
	v_mfma_f32_16x16x32_bf16 v[120:123], v[140:143], v[194:197], v[120:123]
	v_mfma_f32_16x16x32_bf16 v[108:111], v[132:135], v[202:205], v[108:111]
	v_mfma_f32_16x16x32_bf16 v[104:107], v[140:143], v[202:205], v[104:107]
	v_mfma_f32_16x16x32_bf16 v[92:95], v[132:135], v[236:239], v[92:95]
	v_mfma_f32_16x16x32_bf16 v[88:91], v[140:143], v[236:239], v[88:91]
	v_mfma_f32_16x16x32_bf16 v[76:79], v[132:135], v[244:247], v[76:79]
	v_mfma_f32_16x16x32_bf16 v[72:75], v[140:143], v[244:247], v[72:75]
	v_mfma_f32_16x16x32_bf16 v[116:119], v[144:147], v[190:193], v[116:119]
	v_mfma_f32_16x16x32_bf16 v[112:115], v[152:155], v[190:193], v[112:115]
	v_mfma_f32_16x16x32_bf16 v[100:103], v[144:147], v[198:201], v[100:103]
	v_mfma_f32_16x16x32_bf16 v[96:99], v[152:155], v[198:201], v[96:99]
	v_mfma_f32_16x16x32_bf16 v[84:87], v[144:147], v[232:235], v[84:87]
	v_mfma_f32_16x16x32_bf16 v[80:83], v[152:155], v[232:235], v[80:83]
	v_mfma_f32_16x16x32_bf16 v[68:71], v[144:147], v[240:243], v[68:71]
	v_mfma_f32_16x16x32_bf16 v[64:67], v[152:155], v[240:243], v[64:67]
	v_mfma_f32_16x16x32_bf16 v[116:119], v[148:151], v[194:197], v[116:119]
	v_mfma_f32_16x16x32_bf16 v[112:115], v[156:159], v[194:197], v[112:115]
	v_mfma_f32_16x16x32_bf16 v[100:103], v[148:151], v[202:205], v[100:103]
	v_mfma_f32_16x16x32_bf16 v[96:99], v[156:159], v[202:205], v[96:99]
	v_mfma_f32_16x16x32_bf16 v[84:87], v[148:151], v[236:239], v[84:87]
	v_mfma_f32_16x16x32_bf16 v[80:83], v[156:159], v[236:239], v[80:83]
	v_mfma_f32_16x16x32_bf16 v[68:71], v[148:151], v[244:247], v[68:71]
	v_mfma_f32_16x16x32_bf16 v[64:67], v[156:159], v[244:247], v[64:67]
	s_barrier
	s_add_i32 s18, s39, s77
	v_lshl_add_u64 v[168:169], v[206:207], 0, s[96:97]
	s_mov_b32 m0, s18
	ds_read_b128 v[190:193], v230 offset:49152
	ds_read_b128 v[194:197], v230 offset:50176
	ds_read_b128 v[198:201], v230 offset:51200
	ds_read_b128 v[202:205], v230 offset:52224
	ds_read_b128 v[232:235], v230 offset:53248
	ds_read_b128 v[236:239], v230 offset:54272
	ds_read_b128 v[240:243], v230 offset:55296
	ds_read_b128 v[244:247], v230 offset:56320
	global_load_lds_dwordx4 v[168:169], off
	s_add_i32 m0, s18, 0x2000
	s_add_u32 s16, s16, 0x40080
	v_lshl_add_u64 v[168:169], v[248:249], 0, s[96:97]
	s_addc_u32 s17, s17, 0
	s_add_i32 s18, s40, s77
	global_load_lds_dwordx4 v[168:169], off
	v_lshl_add_u64 v[168:169], s[16:17], 0, v[174:175]
	s_mov_b32 m0, s18
	v_lshl_add_u64 v[166:167], v[166:167], 0, s[96:97]
	global_load_lds_dwordx4 v[168:169], off
	v_lshl_add_u64 v[168:169], s[16:17], 0, v[170:171]
	s_add_i32 m0, s18, 0x2000
	s_nop 0
	global_load_lds_dwordx4 v[168:169], off
	v_lshl_add_u64 v[168:169], v[250:251], 0, s[96:97]
	s_mov_b32 m0, s28
	s_nop 0
	global_load_lds_dwordx4 v[168:169], off
	s_mov_b32 m0, s29
	s_nop 0
	global_load_lds_dwordx4 v[166:167], off
	s_waitcnt vmcnt(8)
	s_waitcnt lgkmcnt(0)
	s_barrier
	s_waitcnt lgkmcnt(0)
	v_mfma_f32_16x16x32_bf16 v[60:63], v[128:131], v[190:193], v[60:63]
	v_mfma_f32_16x16x32_bf16 v[56:59], v[136:139], v[190:193], v[56:59]
	v_mfma_f32_16x16x32_bf16 v[44:47], v[128:131], v[198:201], v[44:47]
	v_mfma_f32_16x16x32_bf16 v[40:43], v[136:139], v[198:201], v[40:43]
	v_mfma_f32_16x16x32_bf16 v[28:31], v[128:131], v[232:235], v[28:31]
	v_mfma_f32_16x16x32_bf16 v[24:27], v[136:139], v[232:235], v[24:27]
	v_mfma_f32_16x16x32_bf16 v[12:15], v[128:131], v[240:243], v[12:15]
	v_mfma_f32_16x16x32_bf16 v[8:11], v[136:139], v[240:243], v[8:11]
	v_mfma_f32_16x16x32_bf16 v[60:63], v[132:135], v[194:197], v[60:63]
	v_mfma_f32_16x16x32_bf16 v[56:59], v[140:143], v[194:197], v[56:59]
	v_mfma_f32_16x16x32_bf16 v[44:47], v[132:135], v[202:205], v[44:47]
	v_mfma_f32_16x16x32_bf16 v[40:43], v[140:143], v[202:205], v[40:43]
	v_mfma_f32_16x16x32_bf16 v[28:31], v[132:135], v[236:239], v[28:31]
	v_mfma_f32_16x16x32_bf16 v[24:27], v[140:143], v[236:239], v[24:27]
	v_mfma_f32_16x16x32_bf16 v[12:15], v[132:135], v[244:247], v[12:15]
	v_mfma_f32_16x16x32_bf16 v[8:11], v[140:143], v[244:247], v[8:11]
	v_mfma_f32_16x16x32_bf16 v[52:55], v[144:147], v[190:193], v[52:55]
	v_mfma_f32_16x16x32_bf16 v[48:51], v[152:155], v[190:193], v[48:51]
	v_mfma_f32_16x16x32_bf16 v[36:39], v[144:147], v[198:201], v[36:39]
	v_mfma_f32_16x16x32_bf16 v[32:35], v[152:155], v[198:201], v[32:35]
	v_mfma_f32_16x16x32_bf16 v[20:23], v[144:147], v[232:235], v[20:23]
	v_mfma_f32_16x16x32_bf16 v[16:19], v[152:155], v[232:235], v[16:19]
	v_mfma_f32_16x16x32_bf16 v[4:7], v[144:147], v[240:243], v[4:7]
	v_mfma_f32_16x16x32_bf16 v[0:3], v[152:155], v[240:243], v[0:3]
	v_mfma_f32_16x16x32_bf16 v[52:55], v[148:151], v[194:197], v[52:55]
	v_mfma_f32_16x16x32_bf16 v[48:51], v[156:159], v[194:197], v[48:51]
	v_mfma_f32_16x16x32_bf16 v[36:39], v[148:151], v[202:205], v[36:39]
	v_mfma_f32_16x16x32_bf16 v[32:35], v[156:159], v[202:205], v[32:35]
	v_mfma_f32_16x16x32_bf16 v[20:23], v[148:151], v[236:239], v[20:23]
	v_mfma_f32_16x16x32_bf16 v[16:19], v[156:159], v[236:239], v[16:19]
	v_mfma_f32_16x16x32_bf16 v[4:7], v[148:151], v[244:247], v[4:7]
	v_mfma_f32_16x16x32_bf16 v[0:3], v[156:159], v[244:247], v[0:3]
	s_barrier
	s_add_i32 s38, s38, 2
	s_add_u32 s36, s36, 0x100
	s_addc_u32 s37, s37, 0
	s_add_u32 s8, s8, 0x100
	s_addc_u32 s9, s9, 0
	s_cmp_gt_u32 s38, 13
	s_cbranch_scc0 .LBB0_483
	s_setprio 0
	v_readlane_b32 s8, v253, 23
	v_readlane_b32 s9, v253, 24
	s_and_b64 vcc, exec, s[8:9]
	s_cbranch_vccz .LBB0_486
	s_barrier

.LBB0_553:
	s_ashr_i32 s13, s12, 31
	s_lshl_b64 s[14:15], s[12:13], 21
	s_add_u32 s14, s2, s14
	s_addc_u32 s15, s24, s15
	s_and_b64 s[16:17], s[6:7], exec
	s_cselect_b32 s13, s15, s21
	s_cselect_b32 s40, s14, s20
	s_ashr_i32 s11, s10, 31
	s_lshl_b64 s[16:17], s[10:11], 21
	s_add_u32 s16, s25, s16
	s_addc_u32 s17, s26, s17
	s_and_b64 s[22:23], s[6:7], exec
	s_cselect_b32 s11, s17, s19
	s_cselect_b32 s41, s16, s18
	s_add_u32 s42, s18, 0x100
	s_addc_u32 s43, s19, 0
	s_add_u32 s18, s20, 0x100080
	v_mov_b32_e32 v0, 0
	s_addc_u32 s19, s21, 0
	s_mov_b32 s44, -2
	v_mov_b32_e32 v1, v0
	v_mov_b32_e32 v2, v0
	v_mov_b32_e32 v3, v0
	v_mov_b32_e32 v4, v0
	v_mov_b32_e32 v5, v0
	v_mov_b32_e32 v6, v0
	v_mov_b32_e32 v7, v0
	v_mov_b32_e32 v8, v0
	v_mov_b32_e32 v9, v0
	v_mov_b32_e32 v10, v0
	v_mov_b32_e32 v11, v0
	v_mov_b32_e32 v12, v0
	v_mov_b32_e32 v13, v0
	v_mov_b32_e32 v14, v0
	v_mov_b32_e32 v15, v0
	v_mov_b32_e32 v16, v0
	v_mov_b32_e32 v17, v0
	v_mov_b32_e32 v18, v0
	v_mov_b32_e32 v19, v0
	v_mov_b32_e32 v20, v0
	v_mov_b32_e32 v21, v0
	v_mov_b32_e32 v22, v0
	v_mov_b32_e32 v23, v0
	v_mov_b32_e32 v24, v0
	v_mov_b32_e32 v25, v0
	v_mov_b32_e32 v26, v0
	v_mov_b32_e32 v27, v0
	v_mov_b32_e32 v28, v0
	v_mov_b32_e32 v29, v0
	v_mov_b32_e32 v30, v0
	v_mov_b32_e32 v31, v0
	v_mov_b32_e32 v56, v0
	v_mov_b32_e32 v57, v0
	v_mov_b32_e32 v58, v0
	v_mov_b32_e32 v59, v0
	v_mov_b32_e32 v68, v0
	v_mov_b32_e32 v69, v0
	v_mov_b32_e32 v70, v0
	v_mov_b32_e32 v71, v0
	v_mov_b32_e32 v72, v0
	v_mov_b32_e32 v73, v0
	v_mov_b32_e32 v74, v0
	v_mov_b32_e32 v75, v0
	v_mov_b32_e32 v76, v0
	v_mov_b32_e32 v77, v0
	v_mov_b32_e32 v78, v0
	v_mov_b32_e32 v79, v0
	v_mov_b32_e32 v80, v0
	v_mov_b32_e32 v81, v0
	v_mov_b32_e32 v82, v0
	v_mov_b32_e32 v83, v0
	v_mov_b32_e32 v84, v0
	v_mov_b32_e32 v85, v0
	v_mov_b32_e32 v86, v0
	v_mov_b32_e32 v87, v0
	v_mov_b32_e32 v88, v0
	v_mov_b32_e32 v89, v0
	v_mov_b32_e32 v90, v0
	v_mov_b32_e32 v91, v0
	v_mov_b32_e32 v92, v0
	v_mov_b32_e32 v93, v0
	v_mov_b32_e32 v94, v0
	v_mov_b32_e32 v95, v0
	v_mov_b32_e32 v32, v0
	v_mov_b32_e32 v33, v0
	v_mov_b32_e32 v34, v0
	v_mov_b32_e32 v35, v0
	v_mov_b32_e32 v36, v0
	v_mov_b32_e32 v37, v0
	v_mov_b32_e32 v38, v0
	v_mov_b32_e32 v39, v0
	v_mov_b32_e32 v40, v0
	v_mov_b32_e32 v41, v0
	v_mov_b32_e32 v42, v0
	v_mov_b32_e32 v43, v0
	v_mov_b32_e32 v44, v0
	v_mov_b32_e32 v45, v0
	v_mov_b32_e32 v46, v0
	v_mov_b32_e32 v47, v0
	v_mov_b32_e32 v48, v0
	v_mov_b32_e32 v49, v0
	v_mov_b32_e32 v50, v0
	v_mov_b32_e32 v51, v0
	v_mov_b32_e32 v52, v0
	v_mov_b32_e32 v53, v0
	v_mov_b32_e32 v54, v0
	v_mov_b32_e32 v55, v0
	v_mov_b32_e32 v60, v0
	v_mov_b32_e32 v61, v0
	v_mov_b32_e32 v62, v0
	v_mov_b32_e32 v63, v0
	v_mov_b32_e32 v64, v0
	v_mov_b32_e32 v65, v0
	v_mov_b32_e32 v66, v0
	v_mov_b32_e32 v67, v0
	v_mov_b32_e32 v96, v0
	v_mov_b32_e32 v97, v0
	v_mov_b32_e32 v98, v0
	v_mov_b32_e32 v99, v0
	v_mov_b32_e32 v100, v0
	v_mov_b32_e32 v101, v0
	v_mov_b32_e32 v102, v0
	v_mov_b32_e32 v103, v0
	v_mov_b32_e32 v104, v0
	v_mov_b32_e32 v105, v0
	v_mov_b32_e32 v106, v0
	v_mov_b32_e32 v107, v0
	v_mov_b32_e32 v108, v0
	v_mov_b32_e32 v109, v0
	v_mov_b32_e32 v110, v0
	v_mov_b32_e32 v111, v0
	v_mov_b32_e32 v112, v0
	v_mov_b32_e32 v113, v0
	v_mov_b32_e32 v114, v0
	v_mov_b32_e32 v115, v0
	v_mov_b32_e32 v116, v0
	v_mov_b32_e32 v117, v0
	v_mov_b32_e32 v118, v0
	v_mov_b32_e32 v119, v0
	v_mov_b32_e32 v120, v0
	v_mov_b32_e32 v121, v0
	v_mov_b32_e32 v122, v0
	v_mov_b32_e32 v123, v0
	v_mov_b32_e32 v124, v0
	v_mov_b32_e32 v125, v0
	v_mov_b32_e32 v126, v0
	v_mov_b32_e32 v127, v0
	v_readlane_b32 s100, v252, 21
	s_sub_u32 s100, s100, 0
	s_cmp_lt_u32 s100, 4
	s_cbranch_scc0 .Lprio_9
	s_setprio 1
.Lprio_9:
.LBB0_554:
	s_add_u32 s20, s18, 0xfff00080
	s_addc_u32 s21, s19, -1
	s_add_i32 s45, 0, 0x10000
	s_cmp_eq_u32 s44, 60
	s_cselect_b32 s23, s13, s21
	s_cselect_b32 s22, s40, s20
	s_cselect_b32 s21, s11, s43
	s_cselect_b32 s20, s41, s42
	s_add_i32 s48, 0, 0x14000
	v_add_u32_e32 v150, s45, v157
	v_add_u32_e32 v154, s48, v157
	ds_read_b128 v[128:131], v150
	ds_read_b128 v[132:135], v150 offset:1024
	ds_read_b128 v[146:149], v150 offset:2048
	ds_read_b128 v[150:153], v150 offset:3072
	ds_read_b128 v[170:173], v154
	ds_read_b128 v[174:177], v154 offset:1024
	ds_read_b128 v[178:181], v154 offset:2048
	ds_read_b128 v[182:185], v154 offset:3072
	v_lshl_add_u64 v[154:155], s[18:19], 0, v[144:145]
	s_add_i32 m0, s27, 0xc000
	ds_read_b128 v[186:189], v159
	ds_read_b128 v[190:193], v159 offset:1024
	ds_read_b128 v[194:197], v159 offset:2048
	ds_read_b128 v[198:201], v159 offset:3072
	ds_read_b128 v[202:205], v159 offset:4096
	ds_read_b128 v[228:231], v159 offset:5120
	ds_read_b128 v[232:235], v159 offset:6144
	ds_read_b128 v[236:239], v159 offset:7168
	global_load_lds_dwordx4 v[154:155], off
	v_lshl_add_u64 v[154:155], s[18:19], 0, v[142:143]
	s_add_i32 m0, s27, 0xe000
	s_nop 0
	global_load_lds_dwordx4 v[154:155], off
	s_waitcnt vmcnt(8)
	s_waitcnt lgkmcnt(0)
	s_barrier
	s_waitcnt lgkmcnt(0)
	v_mfma_f32_16x16x32_bf16 v[124:127], v[128:131], v[186:189], v[124:127]
	v_mfma_f32_16x16x32_bf16 v[120:123], v[146:149], v[186:189], v[120:123]
	v_mfma_f32_16x16x32_bf16 v[116:119], v[128:131], v[194:197], v[116:119]
	v_mfma_f32_16x16x32_bf16 v[112:115], v[146:149], v[194:197], v[112:115]
	v_mfma_f32_16x16x32_bf16 v[108:111], v[128:131], v[202:205], v[108:111]
	v_mfma_f32_16x16x32_bf16 v[104:107], v[146:149], v[202:205], v[104:107]
	v_mfma_f32_16x16x32_bf16 v[100:103], v[128:131], v[232:235], v[100:103]
	v_mfma_f32_16x16x32_bf16 v[96:99], v[146:149], v[232:235], v[96:99]
	v_mfma_f32_16x16x32_bf16 v[124:127], v[132:135], v[190:193], v[124:127]
	v_mfma_f32_16x16x32_bf16 v[120:123], v[150:153], v[190:193], v[120:123]
	v_mfma_f32_16x16x32_bf16 v[116:119], v[132:135], v[198:201], v[116:119]
	v_mfma_f32_16x16x32_bf16 v[112:115], v[150:153], v[198:201], v[112:115]
	v_mfma_f32_16x16x32_bf16 v[108:111], v[132:135], v[228:231], v[108:111]
	v_mfma_f32_16x16x32_bf16 v[104:107], v[150:153], v[228:231], v[104:107]
	v_mfma_f32_16x16x32_bf16 v[100:103], v[132:135], v[236:239], v[100:103]
	v_mfma_f32_16x16x32_bf16 v[96:99], v[150:153], v[236:239], v[96:99]
	v_mfma_f32_16x16x32_bf16 v[64:67], v[170:173], v[186:189], v[64:67]
	v_mfma_f32_16x16x32_bf16 v[60:63], v[178:181], v[186:189], v[60:63]
	v_mfma_f32_16x16x32_bf16 v[52:55], v[170:173], v[194:197], v[52:55]
	v_mfma_f32_16x16x32_bf16 v[48:51], v[178:181], v[194:197], v[48:51]
	v_mfma_f32_16x16x32_bf16 v[44:47], v[170:173], v[202:205], v[44:47]
	v_mfma_f32_16x16x32_bf16 v[40:43], v[178:181], v[202:205], v[40:43]
	v_mfma_f32_16x16x32_bf16 v[36:39], v[170:173], v[232:235], v[36:39]
	v_mfma_f32_16x16x32_bf16 v[32:35], v[178:181], v[232:235], v[32:35]
	v_mfma_f32_16x16x32_bf16 v[64:67], v[174:177], v[190:193], v[64:67]
	v_mfma_f32_16x16x32_bf16 v[60:63], v[182:185], v[190:193], v[60:63]
	v_mfma_f32_16x16x32_bf16 v[52:55], v[174:177], v[198:201], v[52:55]
	v_mfma_f32_16x16x32_bf16 v[48:51], v[182:185], v[198:201], v[48:51]
	v_mfma_f32_16x16x32_bf16 v[44:47], v[174:177], v[228:231], v[44:47]
	v_mfma_f32_16x16x32_bf16 v[40:43], v[182:185], v[228:231], v[40:43]
	v_mfma_f32_16x16x32_bf16 v[36:39], v[174:177], v[236:239], v[36:39]
	v_mfma_f32_16x16x32_bf16 v[32:35], v[182:185], v[236:239], v[32:35]
	s_barrier
	s_add_i32 s45, s45, s77
	v_lshl_add_u64 v[154:155], s[20:21], 0, v[160:161]
	s_mov_b32 m0, s45
	ds_read_b128 v[186:189], v159 offset:16384
	ds_read_b128 v[190:193], v159 offset:17408
	ds_read_b128 v[194:197], v159 offset:18432
	ds_read_b128 v[198:201], v159 offset:19456
	ds_read_b128 v[202:205], v159 offset:20480
	ds_read_b128 v[228:231], v159 offset:21504
	ds_read_b128 v[232:235], v159 offset:22528
	ds_read_b128 v[236:239], v159 offset:23552
	global_load_lds_dwordx4 v[154:155], off
	s_add_i32 m0, s45, 0x2000
	s_add_u32 s46, s20, 0x100000
	v_lshl_add_u64 v[166:167], s[20:21], 0, v[136:137]
	s_addc_u32 s47, s21, 0
	s_add_i32 s45, s48, s77
	global_load_lds_dwordx4 v[166:167], off
	v_lshl_add_u64 v[168:169], s[46:47], 0, v[160:161]
	s_mov_b32 m0, s45
	v_lshl_add_u64 v[206:207], s[22:23], 0, v[138:139]
	global_load_lds_dwordx4 v[168:169], off
	v_lshl_add_u64 v[168:169], s[46:47], 0, v[136:137]
	s_add_i32 m0, s45, 0x2000
	s_nop 0
	global_load_lds_dwordx4 v[168:169], off
	v_lshl_add_u64 v[168:169], s[22:23], 0, v[140:141]
	s_mov_b32 m0, s27
	s_nop 0
	global_load_lds_dwordx4 v[168:169], off
	s_mov_b32 m0, s28
	s_nop 0
	global_load_lds_dwordx4 v[206:207], off
	s_waitcnt vmcnt(8)
	s_waitcnt lgkmcnt(0)
	s_barrier
	s_waitcnt lgkmcnt(0)
	v_mfma_f32_16x16x32_bf16 v[92:95], v[128:131], v[186:189], v[92:95]
	v_mfma_f32_16x16x32_bf16 v[88:91], v[146:149], v[186:189], v[88:91]
	v_mfma_f32_16x16x32_bf16 v[84:87], v[128:131], v[194:197], v[84:87]
	v_mfma_f32_16x16x32_bf16 v[80:83], v[146:149], v[194:197], v[80:83]
	v_mfma_f32_16x16x32_bf16 v[76:79], v[128:131], v[202:205], v[76:79]
	v_mfma_f32_16x16x32_bf16 v[72:75], v[146:149], v[202:205], v[72:75]
	v_mfma_f32_16x16x32_bf16 v[68:71], v[128:131], v[232:235], v[68:71]
	v_mfma_f32_16x16x32_bf16 v[56:59], v[146:149], v[232:235], v[56:59]
	v_mfma_f32_16x16x32_bf16 v[92:95], v[132:135], v[190:193], v[92:95]
	v_mfma_f32_16x16x32_bf16 v[88:91], v[150:153], v[190:193], v[88:91]
	v_mfma_f32_16x16x32_bf16 v[84:87], v[132:135], v[198:201], v[84:87]
	v_mfma_f32_16x16x32_bf16 v[80:83], v[150:153], v[198:201], v[80:83]
	v_mfma_f32_16x16x32_bf16 v[76:79], v[132:135], v[228:231], v[76:79]
	v_mfma_f32_16x16x32_bf16 v[72:75], v[150:153], v[228:231], v[72:75]
	v_mfma_f32_16x16x32_bf16 v[68:71], v[132:135], v[236:239], v[68:71]
	v_mfma_f32_16x16x32_bf16 v[56:59], v[150:153], v[236:239], v[56:59]
	v_mfma_f32_16x16x32_bf16 v[28:31], v[170:173], v[186:189], v[28:31]
	v_mfma_f32_16x16x32_bf16 v[24:27], v[178:181], v[186:189], v[24:27]
	v_mfma_f32_16x16x32_bf16 v[20:23], v[170:173], v[194:197], v[20:23]
	v_mfma_f32_16x16x32_bf16 v[16:19], v[178:181], v[194:197], v[16:19]
	v_mfma_f32_16x16x32_bf16 v[12:15], v[170:173], v[202:205], v[12:15]
	v_mfma_f32_16x16x32_bf16 v[8:11], v[178:181], v[202:205], v[8:11]
	v_mfma_f32_16x16x32_bf16 v[4:7], v[170:173], v[232:235], v[4:7]
	v_mfma_f32_16x16x32_bf16 v[0:3], v[178:181], v[232:235], v[0:3]
	v_mfma_f32_16x16x32_bf16 v[28:31], v[174:177], v[190:193], v[28:31]
	v_mfma_f32_16x16x32_bf16 v[24:27], v[182:185], v[190:193], v[24:27]
	v_mfma_f32_16x16x32_bf16 v[20:23], v[174:177], v[198:201], v[20:23]
	v_mfma_f32_16x16x32_bf16 v[16:19], v[182:185], v[198:201], v[16:19]
	v_mfma_f32_16x16x32_bf16 v[12:15], v[174:177], v[228:231], v[12:15]
	v_mfma_f32_16x16x32_bf16 v[8:11], v[182:185], v[228:231], v[8:11]
	v_mfma_f32_16x16x32_bf16 v[4:7], v[174:177], v[236:239], v[4:7]
	v_mfma_f32_16x16x32_bf16 v[0:3], v[182:185], v[236:239], v[0:3]
	s_barrier
	s_add_i32 s45, 0, 0x18000
	s_add_i32 s46, 0, 0x1c000
	v_add_u32_e32 v150, s45, v157
	v_add_u32_e32 v182, s46, v157
	ds_read_b128 v[128:131], v150
	ds_read_b128 v[132:135], v150 offset:1024
	ds_read_b128 v[146:149], v150 offset:2048
	ds_read_b128 v[150:153], v150 offset:3072
	ds_read_b128 v[170:173], v182
	ds_read_b128 v[174:177], v182 offset:1024
	ds_read_b128 v[178:181], v182 offset:2048
	ds_read_b128 v[182:185], v182 offset:3072
	s_add_u32 s22, s22, 0x100000
	s_addc_u32 s23, s23, 0
	s_mov_b32 m0, s29
	v_lshl_add_u64 v[240:241], s[22:23], 0, v[140:141]
	ds_read_b128 v[186:189], v159 offset:32768
	ds_read_b128 v[190:193], v159 offset:33792
	ds_read_b128 v[194:197], v159 offset:34816
	ds_read_b128 v[198:201], v159 offset:35840
	ds_read_b128 v[202:205], v159 offset:36864
	ds_read_b128 v[228:231], v159 offset:37888
	ds_read_b128 v[232:235], v159 offset:38912
	ds_read_b128 v[236:239], v159 offset:39936
	global_load_lds_dwordx4 v[240:241], off
	v_lshl_add_u64 v[240:241], s[22:23], 0, v[138:139]
	s_mov_b32 m0, s30
	s_nop 0
	global_load_lds_dwordx4 v[240:241], off
	s_waitcnt vmcnt(8)
	s_waitcnt lgkmcnt(0)
	s_barrier
	s_waitcnt lgkmcnt(0)
	v_mfma_f32_16x16x32_bf16 v[124:127], v[128:131], v[186:189], v[124:127]
	v_mfma_f32_16x16x32_bf16 v[120:123], v[146:149], v[186:189], v[120:123]
	v_mfma_f32_16x16x32_bf16 v[116:119], v[128:131], v[194:197], v[116:119]
	v_mfma_f32_16x16x32_bf16 v[112:115], v[146:149], v[194:197], v[112:115]
	v_mfma_f32_16x16x32_bf16 v[108:111], v[128:131], v[202:205], v[108:111]
	v_mfma_f32_16x16x32_bf16 v[104:107], v[146:149], v[202:205], v[104:107]
	v_mfma_f32_16x16x32_bf16 v[100:103], v[128:131], v[232:235], v[100:103]
	v_mfma_f32_16x16x32_bf16 v[96:99], v[146:149], v[232:235], v[96:99]
	v_mfma_f32_16x16x32_bf16 v[124:127], v[132:135], v[190:193], v[124:127]
	v_mfma_f32_16x16x32_bf16 v[120:123], v[150:153], v[190:193], v[120:123]
	v_mfma_f32_16x16x32_bf16 v[116:119], v[132:135], v[198:201], v[116:119]
	v_mfma_f32_16x16x32_bf16 v[112:115], v[150:153], v[198:201], v[112:115]
	v_mfma_f32_16x16x32_bf16 v[108:111], v[132:135], v[228:231], v[108:111]
	v_mfma_f32_16x16x32_bf16 v[104:107], v[150:153], v[228:231], v[104:107]
	v_mfma_f32_16x16x32_bf16 v[100:103], v[132:135], v[236:239], v[100:103]
	v_mfma_f32_16x16x32_bf16 v[96:99], v[150:153], v[236:239], v[96:99]
	v_mfma_f32_16x16x32_bf16 v[64:67], v[170:173], v[186:189], v[64:67]
	v_mfma_f32_16x16x32_bf16 v[60:63], v[178:181], v[186:189], v[60:63]
	v_mfma_f32_16x16x32_bf16 v[52:55], v[170:173], v[194:197], v[52:55]
	v_mfma_f32_16x16x32_bf16 v[48:51], v[178:181], v[194:197], v[48:51]
	v_mfma_f32_16x16x32_bf16 v[44:47], v[170:173], v[202:205], v[44:47]
	v_mfma_f32_16x16x32_bf16 v[40:43], v[178:181], v[202:205], v[40:43]
	v_mfma_f32_16x16x32_bf16 v[36:39], v[170:173], v[232:235], v[36:39]
	v_mfma_f32_16x16x32_bf16 v[32:35], v[178:181], v[232:235], v[32:35]
	v_mfma_f32_16x16x32_bf16 v[64:67], v[174:177], v[190:193], v[64:67]
	v_mfma_f32_16x16x32_bf16 v[60:63], v[182:185], v[190:193], v[60:63]
	v_mfma_f32_16x16x32_bf16 v[52:55], v[174:177], v[198:201], v[52:55]
	v_mfma_f32_16x16x32_bf16 v[48:51], v[182:185], v[198:201], v[48:51]
	v_mfma_f32_16x16x32_bf16 v[44:47], v[174:177], v[228:231], v[44:47]
	v_mfma_f32_16x16x32_bf16 v[40:43], v[182:185], v[228:231], v[40:43]
	v_mfma_f32_16x16x32_bf16 v[36:39], v[174:177], v[236:239], v[36:39]
	v_mfma_f32_16x16x32_bf16 v[32:35], v[182:185], v[236:239], v[32:35]
	s_barrier
	s_add_i32 s22, s45, s77
	v_lshl_add_u64 v[154:155], v[154:155], 0, s[96:97]
	s_mov_b32 m0, s22
	ds_read_b128 v[186:189], v159 offset:49152
	ds_read_b128 v[190:193], v159 offset:50176
	ds_read_b128 v[194:197], v159 offset:51200
	ds_read_b128 v[198:201], v159 offset:52224
	ds_read_b128 v[202:205], v159 offset:53248
	ds_read_b128 v[228:231], v159 offset:54272
	ds_read_b128 v[232:235], v159 offset:55296
	ds_read_b128 v[236:239], v159 offset:56320
	global_load_lds_dwordx4 v[154:155], off
	s_add_i32 m0, s22, 0x2000
	s_add_u32 s20, s20, 0x100080
	v_lshl_add_u64 v[154:155], v[166:167], 0, s[96:97]
	s_addc_u32 s21, s21, 0
	s_add_i32 s22, s46, s77
	global_load_lds_dwordx4 v[154:155], off
	v_lshl_add_u64 v[154:155], s[20:21], 0, v[160:161]
	s_mov_b32 m0, s22
	s_nop 0
	global_load_lds_dwordx4 v[154:155], off
	v_lshl_add_u64 v[154:155], s[20:21], 0, v[136:137]
	s_add_i32 m0, s22, 0x2000
	s_nop 0
	global_load_lds_dwordx4 v[154:155], off
	v_lshl_add_u64 v[154:155], v[168:169], 0, s[96:97]
	s_mov_b32 m0, s35
	s_nop 0
	global_load_lds_dwordx4 v[154:155], off
	v_lshl_add_u64 v[154:155], v[206:207], 0, s[96:97]
	s_mov_b32 m0, s36
	s_nop 0
	global_load_lds_dwordx4 v[154:155], off
	s_waitcnt vmcnt(8)
	s_waitcnt lgkmcnt(0)
	s_barrier
	s_waitcnt lgkmcnt(0)
	v_mfma_f32_16x16x32_bf16 v[92:95], v[128:131], v[186:189], v[92:95]
	v_mfma_f32_16x16x32_bf16 v[88:91], v[146:149], v[186:189], v[88:91]
	v_mfma_f32_16x16x32_bf16 v[84:87], v[128:131], v[194:197], v[84:87]
	v_mfma_f32_16x16x32_bf16 v[80:83], v[146:149], v[194:197], v[80:83]
	v_mfma_f32_16x16x32_bf16 v[76:79], v[128:131], v[202:205], v[76:79]
	v_mfma_f32_16x16x32_bf16 v[72:75], v[146:149], v[202:205], v[72:75]
	v_mfma_f32_16x16x32_bf16 v[68:71], v[128:131], v[232:235], v[68:71]
	v_mfma_f32_16x16x32_bf16 v[56:59], v[146:149], v[232:235], v[56:59]
	v_mfma_f32_16x16x32_bf16 v[92:95], v[132:135], v[190:193], v[92:95]
	v_mfma_f32_16x16x32_bf16 v[88:91], v[150:153], v[190:193], v[88:91]
	v_mfma_f32_16x16x32_bf16 v[84:87], v[132:135], v[198:201], v[84:87]
	v_mfma_f32_16x16x32_bf16 v[80:83], v[150:153], v[198:201], v[80:83]
	v_mfma_f32_16x16x32_bf16 v[76:79], v[132:135], v[228:231], v[76:79]
	v_mfma_f32_16x16x32_bf16 v[72:75], v[150:153], v[228:231], v[72:75]
	v_mfma_f32_16x16x32_bf16 v[68:71], v[132:135], v[236:239], v[68:71]
	v_mfma_f32_16x16x32_bf16 v[56:59], v[150:153], v[236:239], v[56:59]
	v_mfma_f32_16x16x32_bf16 v[28:31], v[170:173], v[186:189], v[28:31]
	v_mfma_f32_16x16x32_bf16 v[24:27], v[178:181], v[186:189], v[24:27]
	v_mfma_f32_16x16x32_bf16 v[20:23], v[170:173], v[194:197], v[20:23]
	v_mfma_f32_16x16x32_bf16 v[16:19], v[178:181], v[194:197], v[16:19]
	v_mfma_f32_16x16x32_bf16 v[12:15], v[170:173], v[202:205], v[12:15]
	v_mfma_f32_16x16x32_bf16 v[8:11], v[178:181], v[202:205], v[8:11]
	v_mfma_f32_16x16x32_bf16 v[4:7], v[170:173], v[232:235], v[4:7]
	v_mfma_f32_16x16x32_bf16 v[0:3], v[178:181], v[232:235], v[0:3]
	v_mfma_f32_16x16x32_bf16 v[28:31], v[174:177], v[190:193], v[28:31]
	v_mfma_f32_16x16x32_bf16 v[24:27], v[182:185], v[190:193], v[24:27]
	v_mfma_f32_16x16x32_bf16 v[20:23], v[174:177], v[198:201], v[20:23]
	v_mfma_f32_16x16x32_bf16 v[16:19], v[182:185], v[198:201], v[16:19]
	v_mfma_f32_16x16x32_bf16 v[12:15], v[174:177], v[228:231], v[12:15]
	v_mfma_f32_16x16x32_bf16 v[8:11], v[182:185], v[228:231], v[8:11]
	v_mfma_f32_16x16x32_bf16 v[4:7], v[174:177], v[236:239], v[4:7]
	v_mfma_f32_16x16x32_bf16 v[0:3], v[182:185], v[236:239], v[0:3]
	s_barrier
	s_add_i32 s44, s44, 2
	s_add_u32 s42, s42, 0x100
	s_addc_u32 s43, s43, 0
	s_add_u32 s18, s18, 0x100
	s_addc_u32 s19, s19, 0
	s_cmp_gt_u32 s44, 61
	s_cbranch_scc0 .LBB0_554
	s_setprio 0
	v_readlane_b32 s18, v253, 23
	v_readlane_b32 s19, v253, 24
	s_and_b64 vcc, exec, s[18:19]
	s_cbranch_vccz .LBB0_557
	s_barrier
